# v30 plus non-temporal hint on the f32 residual-stream row stores (H and d_out, 256 MB per phase) of the four residual/norm loops; bf16 XN stores and all loads left at default policy
# speedup vs baseline: 1.0010x; 1.0010x over previous
.LBB0_1692:
	s_waitcnt lgkmcnt(0)
	v_lshl_add_u64 v[4:5], s[16:17], 0, v[68:69]
	global_load_dword v8, v[4:5], off
	global_load_dwordx4 v[0:3], v[16:17], off
	v_lshl_add_u64 v[12:13], s[12:13], 0, v[72:73]
	global_load_dwordx4 v[4:7], v[12:13], off
	v_lshl_add_u64 v[74:75], s[16:17], 0, v[70:71]
	v_add_co_u32_e32 v120, vcc, s28, v74
	s_waitcnt vmcnt(2)
	ds_bpermute_b32 v9, v126, v8
	v_addc_co_u32_e32 v121, vcc, 0, v75, vcc
	global_load_dwordx2 v[76:77], v[120:121], off offset:-4096
	v_add_co_u32_e32 v14, vcc, s15, v74
	s_waitcnt lgkmcnt(0)
	v_add_f32_e32 v8, v8, v9
	ds_bpermute_b32 v9, v127, v8
	v_addc_co_u32_e32 v15, vcc, 0, v75, vcc
	s_waitcnt vmcnt(2)
	v_mov_b32_e32 v78, v0
	s_waitcnt vmcnt(1)
	v_mov_b32_e32 v0, v4
	s_waitcnt lgkmcnt(0)
	v_add_f32_e32 v10, v8, v9
	ds_bpermute_b32 v11, v128, v10
	v_lshl_add_u64 v[8:9], s[16:17], 0, v[72:73]
	v_mov_b32_e32 v79, v2
	v_mov_b32_e32 v2, v1
	v_mov_b32_e32 v1, v6
	s_waitcnt lgkmcnt(0)
	v_add_f32_e32 v10, v10, v11
	ds_bpermute_b32 v11, v129, v10
	v_mov_b32_e32 v6, v5
	s_waitcnt lgkmcnt(0)
	v_add_f32_e32 v80, v10, v11
	ds_bpermute_b32 v81, v130, v80
	v_add_co_u32_e32 v10, vcc, s27, v8
	s_waitcnt lgkmcnt(0)
	v_add_f32_e32 v80, v80, v81
	ds_bpermute_b32 v81, v131, v80
	v_addc_co_u32_e32 v11, vcc, 0, v9, vcc
	s_waitcnt lgkmcnt(0)
	v_add_f32_e32 v4, v80, v81
	v_fmamk_f32 v4, v4, 0x39800000, v132
	v_mul_f32_e32 v5, 0x4f800000, v4
	v_cmp_gt_f32_e32 vcc, s11, v4
	s_nop 1
	v_cndmask_b32_e32 v80, v4, v5, vcc
	v_sqrt_f32_e32 v81, v80
	s_waitcnt vmcnt(0)
	v_lshlrev_b32_e32 v4, 16, v76
	v_add_u32_e32 v82, -1, v81
	v_add_u32_e32 v83, 1, v81
	v_fma_f32 v84, -v82, v81, v80
	v_fma_f32 v85, -v83, v81, v80
	v_cmp_ge_f32_e64 s[2:3], 0, v84
	v_and_b32_e32 v76, 0xffff0000, v76
	v_lshlrev_b32_e32 v5, 16, v77
	v_cndmask_b32_e64 v81, v81, v82, s[2:3]
	v_cmp_lt_f32_e64 s[2:3], 0, v85
	v_and_b32_e32 v77, 0xffff0000, v77
	s_nop 0
	v_cndmask_b32_e64 v81, v81, v83, s[2:3]
	v_mul_f32_e32 v82, 0x37800000, v81
	v_cndmask_b32_e32 v81, v81, v82, vcc
	v_cmp_class_f32_e32 vcc, v80, v133
	s_nop 1
	v_cndmask_b32_e32 v80, v81, v80, vcc
	v_div_scale_f32 v81, s[2:3], v80, v80, 1.0
	v_rcp_f32_e32 v82, v81
	v_div_scale_f32 v83, vcc, 1.0, v80, 1.0
	v_fma_f32 v84, -v81, v82, 1.0
	v_fmac_f32_e32 v82, v84, v82
	v_mul_f32_e32 v84, v83, v82
	v_fma_f32 v85, -v81, v84, v83
	v_fmac_f32_e32 v84, v85, v82
	v_fma_f32 v81, -v81, v84, v83
	v_div_fmas_f32 v81, v81, v82, v84
	v_div_fixup_f32 v122, v81, v80, 1.0
	v_pk_mul_f32 v[4:5], v[122:123], v[4:5] op_sel_hi:[0,1]
	v_pk_mul_f32 v[76:77], v[122:123], v[76:77] op_sel_hi:[0,1]
	v_pk_fma_f32 v[82:83], v[78:79], v[4:5], v[0:1]
	v_pk_fma_f32 v[76:77], v[2:3], v[76:77], v[6:7]
	v_mov_b32_e32 v0, v82
	v_mov_b32_e32 v1, v76
	v_mov_b32_e32 v2, v83
	v_mov_b32_e32 v3, v77
	global_store_dwordx4 v[10:11], v[0:3], off offset:-4096 nt
	global_load_dwordx2 v[78:79], v[14:15], off offset:512
	s_nop 0
	global_load_dwordx4 v[0:3], v[16:17], off offset:1024
	global_load_dwordx4 v[4:7], v[12:13], off offset:1024
	v_add_co_u32_e32 v92, vcc, s26, v8
	s_waitcnt vmcnt(2)
	v_lshlrev_b32_e32 v81, 16, v79
	v_lshlrev_b32_e32 v80, 16, v78
	v_and_b32_e32 v79, 0xffff0000, v79
	v_and_b32_e32 v78, 0xffff0000, v78
	s_waitcnt vmcnt(1)
	v_mov_b32_e32 v84, v0
	v_mov_b32_e32 v85, v2
	s_waitcnt vmcnt(0)
	v_mov_b32_e32 v86, v4
	v_mov_b32_e32 v87, v6
	v_mov_b32_e32 v2, v1
	v_mov_b32_e32 v6, v5
	v_pk_mul_f32 v[0:1], v[122:123], v[80:81] op_sel_hi:[0,1]
	v_pk_mul_f32 v[4:5], v[122:123], v[78:79] op_sel_hi:[0,1]
	v_pk_fma_f32 v[86:87], v[84:85], v[0:1], v[86:87]
	v_pk_fma_f32 v[84:85], v[2:3], v[4:5], v[6:7]
	v_addc_co_u32_e32 v93, vcc, 0, v9, vcc
	v_mov_b32_e32 v0, v86
	v_mov_b32_e32 v1, v84
	v_mov_b32_e32 v2, v87
	v_mov_b32_e32 v3, v85
	global_store_dwordx4 v[92:93], v[0:3], off offset:1024 nt
	global_load_dwordx2 v[78:79], v[14:15], off offset:1024
	s_nop 0
	global_load_dwordx4 v[0:3], v[12:13], off offset:2048
	global_load_dwordx4 v[4:7], v[16:17], off offset:2048
	v_add_co_u32_e32 v104, vcc, s24, v12
	s_waitcnt vmcnt(2)
	v_lshlrev_b32_e32 v80, 16, v78
	v_and_b32_e32 v81, 0xffff0000, v78
	v_lshlrev_b32_e32 v78, 16, v79
	v_and_b32_e32 v79, 0xffff0000, v79
	v_pk_mul_f32 v[80:81], v[122:123], v[80:81] op_sel_hi:[0,1]
	v_pk_mul_f32 v[78:79], v[122:123], v[78:79] op_sel_hi:[0,1]
	s_waitcnt vmcnt(0)
	v_pk_fma_f32 v[0:1], v[4:5], v[80:81], v[0:1]
	v_pk_fma_f32 v[2:3], v[6:7], v[78:79], v[2:3]
	global_store_dwordx4 v[92:93], v[0:3], off offset:2048 nt
	global_load_dwordx2 v[78:79], v[14:15], off offset:1536
	global_load_dwordx4 v[4:7], v[16:17], off offset:3072
	global_load_dwordx4 v[88:91], v[12:13], off offset:3072
	v_addc_co_u32_e32 v105, vcc, 0, v13, vcc
	v_add_co_u32_e32 v110, vcc, s23, v12
	s_waitcnt vmcnt(2)
	v_lshlrev_b32_e32 v80, 16, v78
	v_and_b32_e32 v78, 0xffff0000, v78
	v_lshlrev_b32_e32 v81, 16, v79
	v_and_b32_e32 v79, 0xffff0000, v79
	s_waitcnt vmcnt(1)
	v_mov_b32_e32 v94, v4
	v_mov_b32_e32 v95, v6
	s_waitcnt vmcnt(0)
	v_mov_b32_e32 v96, v88
	v_mov_b32_e32 v97, v90
	v_mov_b32_e32 v6, v5
	v_mov_b32_e32 v90, v89
	v_pk_mul_f32 v[4:5], v[122:123], v[80:81] op_sel_hi:[0,1]
	v_pk_mul_f32 v[78:79], v[122:123], v[78:79] op_sel_hi:[0,1]
	v_pk_fma_f32 v[80:81], v[94:95], v[4:5], v[96:97]
	v_pk_fma_f32 v[78:79], v[6:7], v[78:79], v[90:91]
	v_mov_b32_e32 v4, v80
	v_mov_b32_e32 v5, v78
	v_mov_b32_e32 v6, v81
	v_mov_b32_e32 v7, v79
	global_store_dwordx4 v[92:93], v[4:7], off offset:3072 nt
	global_load_dwordx2 v[88:89], v[14:15], off offset:2048
	s_nop 0
	global_load_dwordx4 v[4:7], v[18:19], off
	global_load_dwordx4 v[90:93], v[104:105], off offset:-4096
	v_addc_co_u32_e32 v111, vcc, 0, v13, vcc
	v_add_co_u32_e32 v124, vcc, s30, v8
	s_waitcnt vmcnt(2)
	v_lshlrev_b32_e32 v95, 16, v89
	v_lshlrev_b32_e32 v94, 16, v88
	v_and_b32_e32 v89, 0xffff0000, v89
	v_and_b32_e32 v88, 0xffff0000, v88
	s_waitcnt vmcnt(1)
	v_mov_b32_e32 v96, v4
	v_mov_b32_e32 v97, v6
	s_waitcnt vmcnt(0)
	v_mov_b32_e32 v98, v90
	v_mov_b32_e32 v99, v92
	v_mov_b32_e32 v6, v5
	v_mov_b32_e32 v92, v91
	v_pk_mul_f32 v[4:5], v[122:123], v[94:95] op_sel_hi:[0,1]
	v_pk_mul_f32 v[88:89], v[122:123], v[88:89] op_sel_hi:[0,1]
	v_pk_fma_f32 v[90:91], v[96:97], v[4:5], v[98:99]
	v_pk_fma_f32 v[88:89], v[6:7], v[88:89], v[92:93]
	v_mov_b32_e32 v4, v90
	v_mov_b32_e32 v5, v88
	v_mov_b32_e32 v6, v91
	v_mov_b32_e32 v7, v89
	global_store_dwordx4 v[10:11], v[4:7], off nt
	global_load_dwordx2 v[96:97], v[14:15], off offset:2560
	s_nop 0
	global_load_dwordx4 v[4:7], v[20:21], off
	global_load_dwordx4 v[92:95], v[110:111], off offset:1024
	v_addc_co_u32_e32 v125, vcc, 0, v9, vcc
	s_waitcnt vmcnt(2)
	v_lshlrev_b32_e32 v99, 16, v97
	v_lshlrev_b32_e32 v98, 16, v96
	v_and_b32_e32 v97, 0xffff0000, v97
	v_and_b32_e32 v96, 0xffff0000, v96
	s_waitcnt vmcnt(1)
	v_mov_b32_e32 v100, v4
	v_mov_b32_e32 v101, v6
	s_waitcnt vmcnt(0)
	v_mov_b32_e32 v102, v92
	v_mov_b32_e32 v103, v94
	v_mov_b32_e32 v6, v5
	v_mov_b32_e32 v94, v93
	v_pk_mul_f32 v[4:5], v[122:123], v[98:99] op_sel_hi:[0,1]
	v_pk_mul_f32 v[92:93], v[122:123], v[96:97] op_sel_hi:[0,1]
	v_pk_fma_f32 v[98:99], v[100:101], v[4:5], v[102:103]
	v_pk_fma_f32 v[94:95], v[6:7], v[92:93], v[94:95]
	v_mov_b32_e32 v4, v98
	v_mov_b32_e32 v5, v94
	v_mov_b32_e32 v6, v99
	v_mov_b32_e32 v7, v95
	global_store_dwordx4 v[10:11], v[4:7], off offset:1024 nt
	global_load_dwordx2 v[92:93], v[14:15], off offset:3072
	s_nop 0
	global_load_dwordx4 v[4:7], v[110:111], off offset:2048
	global_load_dwordx4 v[100:103], v[22:23], off
	s_waitcnt vmcnt(2)
	v_lshlrev_b32_e32 v96, 16, v92
	v_and_b32_e32 v97, 0xffff0000, v92
	v_lshlrev_b32_e32 v92, 16, v93
	v_and_b32_e32 v93, 0xffff0000, v93
	v_pk_mul_f32 v[96:97], v[122:123], v[96:97] op_sel_hi:[0,1]
	v_pk_mul_f32 v[92:93], v[122:123], v[92:93] op_sel_hi:[0,1]
	s_waitcnt vmcnt(0)
	v_pk_fma_f32 v[4:5], v[100:101], v[96:97], v[4:5]
	v_pk_fma_f32 v[6:7], v[102:103], v[92:93], v[6:7]
	global_store_dwordx4 v[10:11], v[4:7], off offset:2048 nt
	global_load_dwordx2 v[92:93], v[14:15], off offset:3584
	global_load_dwordx4 v[100:103], v[24:25], off
	global_load_dwordx4 v[106:109], v[110:111], off offset:3072
	s_waitcnt vmcnt(2)
	v_lshlrev_b32_e32 v14, 16, v92
	v_and_b32_e32 v92, 0xffff0000, v92
	v_lshlrev_b32_e32 v15, 16, v93
	v_and_b32_e32 v93, 0xffff0000, v93
	s_waitcnt vmcnt(1)
	v_mov_b32_e32 v96, v100
	v_mov_b32_e32 v97, v102
	s_waitcnt vmcnt(0)
	v_mov_b32_e32 v110, v106
	v_mov_b32_e32 v111, v108
	v_mov_b32_e32 v102, v101
	v_mov_b32_e32 v108, v107
	v_pk_mul_f32 v[14:15], v[122:123], v[14:15] op_sel_hi:[0,1]
	v_pk_mul_f32 v[92:93], v[122:123], v[92:93] op_sel_hi:[0,1]
	v_pk_fma_f32 v[96:97], v[96:97], v[14:15], v[110:111]
	v_pk_fma_f32 v[92:93], v[102:103], v[92:93], v[108:109]
	v_mov_b32_e32 v100, v96
	v_mov_b32_e32 v101, v92
	v_mov_b32_e32 v102, v97
	v_mov_b32_e32 v103, v93
	global_store_dwordx4 v[10:11], v[100:103], off offset:3072 nt
	global_load_dwordx2 v[10:11], v[120:121], off
	s_nop 0
	global_load_dwordx4 v[106:109], v[26:27], off
	global_load_dwordx4 v[110:113], v[104:105], off
	s_waitcnt vmcnt(2)
	v_lshlrev_b32_e32 v15, 16, v11
	v_lshlrev_b32_e32 v14, 16, v10
	v_and_b32_e32 v11, 0xffff0000, v11
	v_and_b32_e32 v10, 0xffff0000, v10
	s_waitcnt vmcnt(1)
	v_mov_b32_e32 v100, v106
	v_mov_b32_e32 v101, v108
	s_waitcnt vmcnt(0)
	v_mov_b32_e32 v102, v110
	v_mov_b32_e32 v103, v112
	v_mov_b32_e32 v108, v107
	v_mov_b32_e32 v112, v111
	v_pk_mul_f32 v[14:15], v[122:123], v[14:15] op_sel_hi:[0,1]
	v_pk_mul_f32 v[10:11], v[122:123], v[10:11] op_sel_hi:[0,1]
	v_pk_fma_f32 v[102:103], v[100:101], v[14:15], v[102:103]
	v_pk_fma_f32 v[100:101], v[108:109], v[10:11], v[112:113]
	v_mov_b32_e32 v106, v102
	v_mov_b32_e32 v107, v100
	v_mov_b32_e32 v108, v103
	v_mov_b32_e32 v109, v101
	global_store_dwordx4 v[124:125], v[106:109], off offset:-4096 nt
	global_load_dwordx2 v[10:11], v[120:121], off offset:512
	s_nop 0
	global_load_dwordx4 v[106:109], v[28:29], off
	global_load_dwordx4 v[110:113], v[104:105], off offset:1024
	v_add_co_u32_e32 v14, vcc, s29, v8
	s_waitcnt vmcnt(2)
	v_lshlrev_b32_e32 v8, 16, v10
	v_addc_co_u32_e32 v15, vcc, 0, v9, vcc
	v_lshlrev_b32_e32 v9, 16, v11
	v_and_b32_e32 v11, 0xffff0000, v11
	v_and_b32_e32 v10, 0xffff0000, v10
	s_waitcnt vmcnt(1)
	v_mov_b32_e32 v114, v106
	v_mov_b32_e32 v115, v108
	s_waitcnt vmcnt(0)
	v_mov_b32_e32 v116, v110
	v_mov_b32_e32 v117, v112
	v_mov_b32_e32 v108, v107
	v_mov_b32_e32 v112, v111
	v_pk_mul_f32 v[8:9], v[122:123], v[8:9] op_sel_hi:[0,1]
	v_pk_mul_f32 v[10:11], v[122:123], v[10:11] op_sel_hi:[0,1]
	v_pk_fma_f32 v[110:111], v[114:115], v[8:9], v[116:117]
	v_pk_fma_f32 v[108:109], v[108:109], v[10:11], v[112:113]
	v_mov_b32_e32 v8, v110
	v_mov_b32_e32 v9, v108
	v_mov_b32_e32 v10, v111
	v_mov_b32_e32 v11, v109
	global_store_dwordx4 v[14:15], v[8:11], off offset:1024 nt
	global_load_dwordx2 v[106:107], v[120:121], off offset:1024
	s_nop 0
	global_load_dwordx4 v[8:11], v[104:105], off offset:2048
	global_load_dwordx4 v[112:115], v[30:31], off
	v_add_co_u32_e32 v140, vcc, s25, v12
	s_waitcnt vmcnt(2)
	v_lshlrev_b32_e32 v116, 16, v106
	v_and_b32_e32 v117, 0xffff0000, v106
	v_lshlrev_b32_e32 v106, 16, v107
	v_and_b32_e32 v107, 0xffff0000, v107
	v_pk_mul_f32 v[116:117], v[122:123], v[116:117] op_sel_hi:[0,1]
	v_pk_mul_f32 v[106:107], v[122:123], v[106:107] op_sel_hi:[0,1]
	s_waitcnt vmcnt(0)
	v_pk_fma_f32 v[8:9], v[112:113], v[116:117], v[8:9]
	v_pk_fma_f32 v[10:11], v[114:115], v[106:107], v[10:11]
	global_store_dwordx4 v[14:15], v[8:11], off offset:2048 nt
	global_load_dwordx2 v[106:107], v[120:121], off offset:1536
	global_load_dwordx4 v[112:115], v[32:33], off
	global_load_dwordx4 v[116:119], v[104:105], off offset:3072
	v_addc_co_u32_e32 v141, vcc, 0, v13, vcc
	s_andn2_b64 vcc, exec, s[4:5]
	s_waitcnt vmcnt(2)
	v_lshlrev_b32_e32 v104, 16, v106
	v_and_b32_e32 v106, 0xffff0000, v106
	v_lshlrev_b32_e32 v105, 16, v107
	v_and_b32_e32 v107, 0xffff0000, v107
	s_waitcnt vmcnt(1)
	v_mov_b32_e32 v136, v112
	v_mov_b32_e32 v137, v114
	s_waitcnt vmcnt(0)
	v_mov_b32_e32 v138, v116
	v_mov_b32_e32 v139, v118
	v_mov_b32_e32 v114, v113
	v_mov_b32_e32 v118, v117
	v_pk_mul_f32 v[104:105], v[122:123], v[104:105] op_sel_hi:[0,1]
	v_pk_mul_f32 v[112:113], v[122:123], v[106:107] op_sel_hi:[0,1]
	v_pk_fma_f32 v[106:107], v[136:137], v[104:105], v[138:139]
	v_pk_fma_f32 v[104:105], v[114:115], v[112:113], v[118:119]
	v_mov_b32_e32 v112, v106
	v_mov_b32_e32 v113, v104
	v_mov_b32_e32 v114, v107
	v_mov_b32_e32 v115, v105
	global_store_dwordx4 v[14:15], v[112:115], off offset:3072 nt
	global_load_dwordx2 v[112:113], v[120:121], off offset:2048
	s_nop 0
	global_load_dwordx4 v[114:117], v[34:35], off
	global_load_dwordx4 v[12:15], v[140:141], off
	s_waitcnt vmcnt(2)
	v_lshlrev_b32_e32 v119, 16, v113
	v_lshlrev_b32_e32 v118, 16, v112
	v_and_b32_e32 v113, 0xffff0000, v113
	v_and_b32_e32 v112, 0xffff0000, v112
	s_waitcnt vmcnt(1)
	v_mov_b32_e32 v136, v114
	v_mov_b32_e32 v137, v116
	s_waitcnt vmcnt(0)
	v_mov_b32_e32 v138, v12
	v_mov_b32_e32 v139, v14
	v_mov_b32_e32 v116, v115
	v_mov_b32_e32 v14, v13
	v_pk_mul_f32 v[12:13], v[122:123], v[118:119] op_sel_hi:[0,1]
	v_pk_mul_f32 v[112:113], v[122:123], v[112:113] op_sel_hi:[0,1]
	v_pk_fma_f32 v[114:115], v[136:137], v[12:13], v[138:139]
	v_pk_fma_f32 v[112:113], v[116:117], v[112:113], v[14:15]
	v_mov_b32_e32 v12, v114
	v_mov_b32_e32 v13, v112
	v_mov_b32_e32 v14, v115
	v_mov_b32_e32 v15, v113
	global_store_dwordx4 v[124:125], v[12:15], off nt
	global_load_dwordx2 v[116:117], v[120:121], off offset:2560
	s_nop 0
	global_load_dwordx4 v[12:15], v[36:37], off
	global_load_dwordx4 v[136:139], v[140:141], off offset:1024
	s_waitcnt vmcnt(2)
	v_lshlrev_b32_e32 v119, 16, v117
	v_lshlrev_b32_e32 v118, 16, v116
	v_and_b32_e32 v117, 0xffff0000, v117
	v_and_b32_e32 v116, 0xffff0000, v116
	s_waitcnt vmcnt(1)
	v_mov_b32_e32 v142, v12
	v_mov_b32_e32 v143, v14
	s_waitcnt vmcnt(0)
	v_mov_b32_e32 v144, v136
	v_mov_b32_e32 v145, v138
	v_mov_b32_e32 v14, v13
	v_mov_b32_e32 v138, v137
	v_pk_mul_f32 v[12:13], v[122:123], v[118:119] op_sel_hi:[0,1]
	v_pk_mul_f32 v[116:117], v[122:123], v[116:117] op_sel_hi:[0,1]
	v_pk_fma_f32 v[118:119], v[142:143], v[12:13], v[144:145]
	v_pk_fma_f32 v[116:117], v[14:15], v[116:117], v[138:139]
	v_mov_b32_e32 v12, v118
	v_mov_b32_e32 v13, v116
	v_mov_b32_e32 v14, v119
	v_mov_b32_e32 v15, v117
	global_store_dwordx4 v[124:125], v[12:15], off offset:1024 nt
	global_load_dwordx2 v[142:143], v[120:121], off offset:3072
	s_nop 0
	global_load_dwordx4 v[12:15], v[140:141], off offset:2048
	global_load_dwordx4 v[136:139], v[38:39], off
	s_waitcnt vmcnt(2)
	v_lshlrev_b32_e32 v144, 16, v142
	v_and_b32_e32 v145, 0xffff0000, v142
	v_lshlrev_b32_e32 v142, 16, v143
	v_and_b32_e32 v143, 0xffff0000, v143
	v_pk_mul_f32 v[144:145], v[122:123], v[144:145] op_sel_hi:[0,1]
	v_pk_mul_f32 v[142:143], v[122:123], v[142:143] op_sel_hi:[0,1]
	s_waitcnt vmcnt(0)
	v_pk_fma_f32 v[12:13], v[136:137], v[144:145], v[12:13]
	v_pk_fma_f32 v[14:15], v[138:139], v[142:143], v[14:15]
	global_store_dwordx4 v[124:125], v[12:15], off offset:2048 nt
	global_load_dwordx2 v[120:121], v[120:121], off offset:3584
	s_nop 0
	global_load_dwordx4 v[136:139], v[40:41], off
	s_nop 0
	global_load_dwordx4 v[140:143], v[140:141], off offset:3072
	s_waitcnt vmcnt(2)
	v_lshlrev_b32_e32 v144, 16, v120
	v_and_b32_e32 v120, 0xffff0000, v120
	v_lshlrev_b32_e32 v145, 16, v121
	v_and_b32_e32 v121, 0xffff0000, v121
	s_waitcnt vmcnt(1)
	v_mov_b32_e32 v146, v136
	v_mov_b32_e32 v147, v138
	s_waitcnt vmcnt(0)
	v_mov_b32_e32 v148, v140
	v_mov_b32_e32 v149, v142
	v_mov_b32_e32 v138, v137
	v_mov_b32_e32 v142, v141
	v_pk_mul_f32 v[136:137], v[122:123], v[144:145] op_sel_hi:[0,1]
	v_pk_mul_f32 v[120:121], v[122:123], v[120:121] op_sel_hi:[0,1]
	v_pk_fma_f32 v[122:123], v[146:147], v[136:137], v[148:149]
	v_pk_fma_f32 v[120:121], v[138:139], v[120:121], v[142:143]
	v_mov_b32_e32 v136, v122
	v_mov_b32_e32 v137, v120
	v_mov_b32_e32 v138, v123
	v_mov_b32_e32 v139, v121
	global_store_dwordx4 v[124:125], v[136:139], off offset:3072 nt
	s_cbranch_vccnz .LBB0_1691
	v_mov_b32_e32 v124, v82
	v_mov_b32_e32 v125, v76
	v_mul_f32_e32 v136, v76, v76
	v_pk_fma_f32 v[124:125], v[124:125], v[124:125], v[136:137] op_sel_hi:[1,1,0]
	v_mov_b32_e32 v136, v83
	v_mov_b32_e32 v137, v77
	v_mul_f32_e32 v138, v77, v77
	v_pk_fma_f32 v[136:137], v[136:137], v[136:137], v[138:139] op_sel_hi:[1,1,0]
	v_pk_mul_f32 v[138:139], v[84:85], v[84:85]
	v_mul_f32_e32 v140, v1, v1
	v_pk_fma_f32 v[138:139], v[86:87], v[86:87], v[138:139]
	v_mul_f32_e32 v142, v3, v3
	v_pk_add_f32 v[138:139], v[138:139], v[138:139] op_sel:[0,1] op_sel_hi:[1,0]
	v_pk_fma_f32 v[140:141], v[0:1], v[0:1], v[140:141] op_sel_hi:[1,1,0]
	v_pk_fma_f32 v[142:143], v[2:3], v[2:3], v[142:143] op_sel_hi:[1,1,0]
	v_pk_mul_f32 v[144:145], v[78:79], v[78:79]
	v_pk_mul_f32 v[146:147], v[80:81], v[80:81]
	v_pk_add_f32 v[124:125], v[124:125], v[136:137]
	v_mov_b32_e32 v139, v144
	v_mov_b32_e32 v125, v146
	v_mov_b32_e32 v141, v147
	v_mov_b32_e32 v143, v145
	v_pk_add_f32 v[124:125], v[124:125], v[138:139]
	v_pk_add_f32 v[136:137], v[140:141], v[142:143]
	v_pk_mul_f32 v[138:139], v[94:95], v[94:95]
	v_pk_add_f32 v[124:125], v[124:125], v[136:137]
	v_pk_mul_f32 v[136:137], v[88:89], v[88:89]
	v_pk_add_f32 v[124:125], v[124:125], v[124:125] op_sel:[0,1] op_sel_hi:[1,0]
	v_pk_fma_f32 v[136:137], v[90:91], v[90:91], v[136:137]
	v_pk_fma_f32 v[138:139], v[98:99], v[98:99], v[138:139]
	v_pk_add_f32 v[136:137], v[136:137], v[136:137] op_sel:[0,1] op_sel_hi:[1,0]
	v_mul_f32_e32 v140, v5, v5
	v_mul_f32_e32 v142, v7, v7
	v_pk_add_f32 v[138:139], v[138:139], v[138:139] op_sel:[0,1] op_sel_hi:[1,0]
	v_pk_fma_f32 v[140:141], v[4:5], v[4:5], v[140:141] op_sel_hi:[1,1,0]
	v_pk_fma_f32 v[142:143], v[6:7], v[6:7], v[142:143] op_sel_hi:[1,1,0]
	v_pk_mul_f32 v[144:145], v[92:93], v[92:93]
	v_pk_mul_f32 v[146:147], v[96:97], v[96:97]
	v_pk_add_f32 v[124:125], v[124:125], v[136:137]
	v_mov_b32_e32 v139, v144
	v_mov_b32_e32 v125, v146
	v_mov_b32_e32 v141, v147
	v_mov_b32_e32 v143, v145
	v_pk_add_f32 v[124:125], v[124:125], v[138:139]
	v_pk_add_f32 v[136:137], v[140:141], v[142:143]
	v_pk_mul_f32 v[138:139], v[108:109], v[108:109]
	v_pk_add_f32 v[124:125], v[124:125], v[136:137]
	v_pk_mul_f32 v[136:137], v[100:101], v[100:101]
	v_pk_add_f32 v[124:125], v[124:125], v[124:125] op_sel:[0,1] op_sel_hi:[1,0]
	v_pk_fma_f32 v[136:137], v[102:103], v[102:103], v[136:137]
	v_pk_fma_f32 v[138:139], v[110:111], v[110:111], v[138:139]
	v_pk_add_f32 v[136:137], v[136:137], v[136:137] op_sel:[0,1] op_sel_hi:[1,0]
	v_mul_f32_e32 v140, v9, v9
	v_mul_f32_e32 v142, v11, v11
	v_pk_add_f32 v[138:139], v[138:139], v[138:139] op_sel:[0,1] op_sel_hi:[1,0]
	v_pk_fma_f32 v[140:141], v[8:9], v[8:9], v[140:141] op_sel_hi:[1,1,0]
	v_pk_fma_f32 v[142:143], v[10:11], v[10:11], v[142:143] op_sel_hi:[1,1,0]
	v_pk_mul_f32 v[144:145], v[104:105], v[104:105]
	v_pk_mul_f32 v[146:147], v[106:107], v[106:107]
	v_pk_add_f32 v[124:125], v[124:125], v[136:137]
	v_mov_b32_e32 v139, v144
	v_mov_b32_e32 v125, v146
	v_mov_b32_e32 v141, v147
	v_mov_b32_e32 v143, v145
	v_pk_add_f32 v[124:125], v[124:125], v[138:139]
	v_pk_add_f32 v[136:137], v[140:141], v[142:143]
	v_pk_mul_f32 v[138:139], v[116:117], v[116:117]
	v_pk_add_f32 v[124:125], v[124:125], v[136:137]
	v_pk_mul_f32 v[136:137], v[112:113], v[112:113]
	v_pk_add_f32 v[124:125], v[124:125], v[124:125] op_sel:[0,1] op_sel_hi:[1,0]
	v_pk_fma_f32 v[136:137], v[114:115], v[114:115], v[136:137]
	v_pk_fma_f32 v[138:139], v[118:119], v[118:119], v[138:139]
	v_pk_add_f32 v[136:137], v[136:137], v[136:137] op_sel:[0,1] op_sel_hi:[1,0]
	v_pk_add_f32 v[138:139], v[138:139], v[138:139] op_sel:[0,1] op_sel_hi:[1,0]
	v_pk_mul_f32 v[144:145], v[120:121], v[120:121]
	v_pk_mul_f32 v[146:147], v[122:123], v[122:123]
	v_pk_add_f32 v[124:125], v[124:125], v[136:137]
	v_mov_b32_e32 v139, v144
	v_mov_b32_e32 v125, v146
	v_pk_add_f32 v[124:125], v[124:125], v[138:139]
	global_load_dwordx4 v[136:139], v[42:43], off
	v_mul_f32_e32 v140, v13, v13
	v_mul_f32_e32 v142, v15, v15
	v_pk_fma_f32 v[140:141], v[12:13], v[12:13], v[140:141] op_sel_hi:[1,1,0]
	v_pk_fma_f32 v[142:143], v[14:15], v[14:15], v[142:143] op_sel_hi:[1,1,0]
	v_mov_b32_e32 v141, v147
	v_mov_b32_e32 v143, v145
	v_pk_add_f32 v[140:141], v[140:141], v[142:143]
	s_nop 0
	v_pk_add_f32 v[124:125], v[124:125], v[140:141]
	s_nop 0
	v_add_f32_e32 v124, v124, v125
	ds_bpermute_b32 v125, v126, v124
	s_waitcnt lgkmcnt(0)
	v_add_f32_e32 v124, v124, v125
	ds_bpermute_b32 v125, v127, v124
	s_waitcnt lgkmcnt(0)
	v_add_f32_e32 v124, v124, v125
	ds_bpermute_b32 v125, v128, v124
	s_waitcnt lgkmcnt(0)
	v_add_f32_e32 v124, v124, v125
	ds_bpermute_b32 v125, v129, v124
	s_waitcnt lgkmcnt(0)
	v_add_f32_e32 v124, v124, v125
	ds_bpermute_b32 v125, v130, v124
	s_waitcnt lgkmcnt(0)
	v_add_f32_e32 v124, v124, v125
	ds_bpermute_b32 v125, v131, v124
	s_waitcnt lgkmcnt(0)
	v_add_f32_e32 v124, v124, v125
	v_fmamk_f32 v124, v124, 0x39800000, v132
	v_mul_f32_e32 v125, 0x4f800000, v124
	v_cmp_gt_f32_e32 vcc, s11, v124
	s_nop 1
	v_cndmask_b32_e32 v124, v124, v125, vcc
	v_sqrt_f32_e32 v125, v124
	s_nop 0
	v_add_u32_e32 v135, -1, v125
	v_fma_f32 v140, -v135, v125, v124
	v_cmp_ge_f32_e64 s[2:3], 0, v140
	v_add_u32_e32 v140, 1, v125
	s_nop 0
	v_cndmask_b32_e64 v135, v125, v135, s[2:3]
	v_fma_f32 v125, -v140, v125, v124
	v_cmp_lt_f32_e64 s[2:3], 0, v125
	s_nop 1
	v_cndmask_b32_e64 v125, v135, v140, s[2:3]
	v_mul_f32_e32 v135, 0x37800000, v125
	v_cndmask_b32_e32 v125, v125, v135, vcc
	v_cmp_class_f32_e32 vcc, v124, v133
	s_nop 1
	v_cndmask_b32_e32 v124, v125, v124, vcc
	v_div_scale_f32 v125, s[2:3], v124, v124, 1.0
	v_rcp_f32_e32 v135, v125
	s_nop 0
	v_fma_f32 v140, -v125, v135, 1.0
	v_fmac_f32_e32 v135, v140, v135
	v_div_scale_f32 v140, vcc, 1.0, v124, 1.0
	v_mul_f32_e32 v141, v140, v135
	v_fma_f32 v142, -v125, v141, v140
	v_fmac_f32_e32 v141, v142, v135
	v_fma_f32 v125, -v125, v141, v140
	v_div_fmas_f32 v125, v125, v135, v141
	v_div_fixup_f32 v124, v125, v124, 1.0
	v_pk_mul_f32 v[82:83], v[82:83], v[124:125] op_sel_hi:[1,0]
	s_waitcnt vmcnt(0)
	v_mov_b32_e32 v140, v136
	v_mov_b32_e32 v141, v138
	v_pk_mul_f32 v[82:83], v[140:141], v[82:83]
	v_pk_mul_f32 v[76:77], v[76:77], v[124:125] op_sel_hi:[1,0]
	v_mov_b32_e32 v138, v137
	v_pk_mul_f32 v[76:77], v[138:139], v[76:77]
	v_and_b32_sdwa v135, v82, v134 dst_sel:DWORD dst_unused:UNUSED_PAD src0_sel:WORD_1 src1_sel:DWORD
	v_and_b32_sdwa v125, v83, v134 dst_sel:DWORD dst_unused:UNUSED_PAD src0_sel:WORD_1 src1_sel:DWORD
	v_add3_u32 v82, v82, v135, s31
	v_and_b32_sdwa v135, v76, v134 dst_sel:DWORD dst_unused:UNUSED_PAD src0_sel:WORD_1 src1_sel:DWORD
	v_add3_u32 v83, v83, v125, s31
	v_and_b32_sdwa v125, v77, v134 dst_sel:DWORD dst_unused:UNUSED_PAD src0_sel:WORD_1 src1_sel:DWORD
	v_add3_u32 v76, v76, v135, s31
	v_add3_u32 v77, v77, v125, s31
	v_and_b32_e32 v76, 0xffff0000, v76
	v_and_b32_e32 v77, 0xffff0000, v77
	v_or_b32_sdwa v82, v76, v82 dst_sel:DWORD dst_unused:UNUSED_PAD src0_sel:DWORD src1_sel:WORD_1
	v_add_co_u32_e32 v76, vcc, s34, v74
	v_or_b32_sdwa v83, v77, v83 dst_sel:DWORD dst_unused:UNUSED_PAD src0_sel:DWORD src1_sel:WORD_1
	s_nop 0
	v_addc_co_u32_e32 v77, vcc, 0, v75, vcc
	global_store_dwordx2 v[76:77], v[82:83], off offset:-4096
	global_load_dwordx4 v[136:139], v[42:43], off offset:1024
	v_pk_mul_f32 v[82:83], v[86:87], v[124:125] op_sel_hi:[1,0]
	v_pk_mul_f32 v[84:85], v[84:85], v[124:125] op_sel_hi:[1,0]
	v_add_co_u32_e32 v74, vcc, s33, v74
	s_waitcnt vmcnt(0)
	v_mov_b32_e32 v87, v138
	v_mov_b32_e32 v138, v137
	v_mov_b32_e32 v86, v136
	v_pk_mul_f32 v[84:85], v[138:139], v[84:85]
	v_pk_mul_f32 v[82:83], v[86:87], v[82:83]
	v_and_b32_sdwa v125, v85, v134 dst_sel:DWORD dst_unused:UNUSED_PAD src0_sel:WORD_1 src1_sel:DWORD
	v_and_b32_sdwa v135, v84, v134 dst_sel:DWORD dst_unused:UNUSED_PAD src0_sel:WORD_1 src1_sel:DWORD
	v_and_b32_sdwa v86, v83, v134 dst_sel:DWORD dst_unused:UNUSED_PAD src0_sel:WORD_1 src1_sel:DWORD
	v_and_b32_sdwa v87, v82, v134 dst_sel:DWORD dst_unused:UNUSED_PAD src0_sel:WORD_1 src1_sel:DWORD
	v_add3_u32 v85, v85, v125, s31
	v_add3_u32 v84, v84, v135, s31
	v_add3_u32 v82, v82, v87, s31
	v_add3_u32 v83, v83, v86, s31
	v_and_b32_e32 v85, 0xffff0000, v85
	v_and_b32_e32 v84, 0xffff0000, v84
	v_addc_co_u32_e32 v75, vcc, 0, v75, vcc
	v_or_b32_sdwa v83, v85, v83 dst_sel:DWORD dst_unused:UNUSED_PAD src0_sel:DWORD src1_sel:WORD_1
	v_or_b32_sdwa v82, v84, v82 dst_sel:DWORD dst_unused:UNUSED_PAD src0_sel:DWORD src1_sel:WORD_1
	global_store_dwordx2 v[74:75], v[82:83], off offset:512
	global_load_dwordx4 v[82:85], v[42:43], off offset:2048
	v_mov_b32_e32 v86, v0
	v_mov_b32_e32 v87, v2
	v_mov_b32_e32 v2, v1
	v_pk_mul_f32 v[0:1], v[86:87], v[124:125] op_sel_hi:[1,0]
	v_pk_mul_f32 v[2:3], v[2:3], v[124:125] op_sel_hi:[1,0]
	v_pk_mul_f32 v[78:79], v[78:79], v[124:125] op_sel_hi:[1,0]
	v_pk_mul_f32 v[80:81], v[80:81], v[124:125] op_sel_hi:[1,0]
	s_waitcnt vmcnt(0)
	v_mov_b32_e32 v87, v84
	v_mov_b32_e32 v84, v83
	v_mov_b32_e32 v86, v82
	v_pk_mul_f32 v[2:3], v[84:85], v[2:3]
	v_pk_mul_f32 v[0:1], v[86:87], v[0:1]
	v_and_b32_sdwa v84, v3, v134 dst_sel:DWORD dst_unused:UNUSED_PAD src0_sel:WORD_1 src1_sel:DWORD
	v_and_b32_sdwa v85, v2, v134 dst_sel:DWORD dst_unused:UNUSED_PAD src0_sel:WORD_1 src1_sel:DWORD
	v_and_b32_sdwa v82, v1, v134 dst_sel:DWORD dst_unused:UNUSED_PAD src0_sel:WORD_1 src1_sel:DWORD
	v_and_b32_sdwa v83, v0, v134 dst_sel:DWORD dst_unused:UNUSED_PAD src0_sel:WORD_1 src1_sel:DWORD
	v_add3_u32 v3, v3, v84, s31
	v_add3_u32 v2, v2, v85, s31
	v_add3_u32 v0, v0, v83, s31
	v_add3_u32 v1, v1, v82, s31
	v_and_b32_e32 v3, 0xffff0000, v3
	v_and_b32_e32 v2, 0xffff0000, v2
	v_or_b32_sdwa v1, v3, v1 dst_sel:DWORD dst_unused:UNUSED_PAD src0_sel:DWORD src1_sel:WORD_1
	v_or_b32_sdwa v0, v2, v0 dst_sel:DWORD dst_unused:UNUSED_PAD src0_sel:DWORD src1_sel:WORD_1
	global_store_dwordx2 v[74:75], v[0:1], off offset:1024
	global_load_dwordx4 v[0:3], v[42:43], off offset:3072
	s_waitcnt vmcnt(0)
	v_mov_b32_e32 v83, v2
	v_mov_b32_e32 v2, v1
	v_mov_b32_e32 v82, v0
	v_pk_mul_f32 v[2:3], v[78:79], v[2:3]
	v_pk_mul_f32 v[0:1], v[80:81], v[82:83]
	v_and_b32_sdwa v80, v3, v134 dst_sel:DWORD dst_unused:UNUSED_PAD src0_sel:WORD_1 src1_sel:DWORD
	v_and_b32_sdwa v81, v2, v134 dst_sel:DWORD dst_unused:UNUSED_PAD src0_sel:WORD_1 src1_sel:DWORD
	v_and_b32_sdwa v78, v1, v134 dst_sel:DWORD dst_unused:UNUSED_PAD src0_sel:WORD_1 src1_sel:DWORD
	v_and_b32_sdwa v79, v0, v134 dst_sel:DWORD dst_unused:UNUSED_PAD src0_sel:WORD_1 src1_sel:DWORD
	v_add3_u32 v3, v3, v80, s31
	v_add3_u32 v2, v2, v81, s31
	v_add3_u32 v0, v0, v79, s31
	v_add3_u32 v1, v1, v78, s31
	v_and_b32_e32 v3, 0xffff0000, v3
	v_and_b32_e32 v2, 0xffff0000, v2
	v_or_b32_sdwa v1, v3, v1 dst_sel:DWORD dst_unused:UNUSED_PAD src0_sel:DWORD src1_sel:WORD_1
	v_or_b32_sdwa v0, v2, v0 dst_sel:DWORD dst_unused:UNUSED_PAD src0_sel:DWORD src1_sel:WORD_1
	global_store_dwordx2 v[74:75], v[0:1], off offset:1536
	global_load_dwordx4 v[0:3], v[44:45], off
	v_pk_mul_f32 v[80:81], v[88:89], v[124:125] op_sel_hi:[1,0]
	v_pk_mul_f32 v[78:79], v[90:91], v[124:125] op_sel_hi:[1,0]
	s_waitcnt vmcnt(0)
	v_mov_b32_e32 v83, v2
	v_mov_b32_e32 v2, v1
	v_mov_b32_e32 v82, v0
	v_pk_mul_f32 v[2:3], v[80:81], v[2:3]
	v_pk_mul_f32 v[0:1], v[78:79], v[82:83]
	v_and_b32_sdwa v80, v3, v134 dst_sel:DWORD dst_unused:UNUSED_PAD src0_sel:WORD_1 src1_sel:DWORD
	v_and_b32_sdwa v81, v2, v134 dst_sel:DWORD dst_unused:UNUSED_PAD src0_sel:WORD_1 src1_sel:DWORD
	v_and_b32_sdwa v78, v1, v134 dst_sel:DWORD dst_unused:UNUSED_PAD src0_sel:WORD_1 src1_sel:DWORD
	v_and_b32_sdwa v79, v0, v134 dst_sel:DWORD dst_unused:UNUSED_PAD src0_sel:WORD_1 src1_sel:DWORD
	v_add3_u32 v3, v3, v80, s31
	v_add3_u32 v2, v2, v81, s31
	v_add3_u32 v0, v0, v79, s31
	v_add3_u32 v1, v1, v78, s31
	v_and_b32_e32 v3, 0xffff0000, v3
	v_and_b32_e32 v2, 0xffff0000, v2
	v_or_b32_sdwa v1, v3, v1 dst_sel:DWORD dst_unused:UNUSED_PAD src0_sel:DWORD src1_sel:WORD_1
	v_or_b32_sdwa v0, v2, v0 dst_sel:DWORD dst_unused:UNUSED_PAD src0_sel:DWORD src1_sel:WORD_1
	global_store_dwordx2 v[74:75], v[0:1], off offset:2048
	global_load_dwordx4 v[0:3], v[46:47], off
	v_pk_mul_f32 v[80:81], v[94:95], v[124:125] op_sel_hi:[1,0]
	v_pk_mul_f32 v[78:79], v[98:99], v[124:125] op_sel_hi:[1,0]
	s_waitcnt vmcnt(0)
	v_mov_b32_e32 v83, v2
	v_mov_b32_e32 v2, v1
	v_mov_b32_e32 v82, v0
	v_pk_mul_f32 v[2:3], v[80:81], v[2:3]
	v_pk_mul_f32 v[0:1], v[78:79], v[82:83]
	v_and_b32_sdwa v80, v3, v134 dst_sel:DWORD dst_unused:UNUSED_PAD src0_sel:WORD_1 src1_sel:DWORD
	v_and_b32_sdwa v81, v2, v134 dst_sel:DWORD dst_unused:UNUSED_PAD src0_sel:WORD_1 src1_sel:DWORD
	v_and_b32_sdwa v78, v1, v134 dst_sel:DWORD dst_unused:UNUSED_PAD src0_sel:WORD_1 src1_sel:DWORD
	v_and_b32_sdwa v79, v0, v134 dst_sel:DWORD dst_unused:UNUSED_PAD src0_sel:WORD_1 src1_sel:DWORD
	v_add3_u32 v3, v3, v80, s31
	v_add3_u32 v2, v2, v81, s31
	v_add3_u32 v0, v0, v79, s31
	v_add3_u32 v1, v1, v78, s31
	v_and_b32_e32 v3, 0xffff0000, v3
	v_and_b32_e32 v2, 0xffff0000, v2
	v_or_b32_sdwa v1, v3, v1 dst_sel:DWORD dst_unused:UNUSED_PAD src0_sel:DWORD src1_sel:WORD_1
	v_or_b32_sdwa v0, v2, v0 dst_sel:DWORD dst_unused:UNUSED_PAD src0_sel:DWORD src1_sel:WORD_1
	global_store_dwordx2 v[74:75], v[0:1], off offset:2560
	global_load_dwordx4 v[0:3], v[48:49], off
	v_mov_b32_e32 v78, v4
	v_mov_b32_e32 v79, v6
	v_mov_b32_e32 v6, v5
	v_pk_mul_f32 v[4:5], v[78:79], v[124:125] op_sel_hi:[1,0]
	v_pk_mul_f32 v[6:7], v[6:7], v[124:125] op_sel_hi:[1,0]
	s_waitcnt vmcnt(0)
	v_mov_b32_e32 v79, v2
	v_mov_b32_e32 v2, v1
	v_mov_b32_e32 v78, v0
	v_pk_mul_f32 v[2:3], v[6:7], v[2:3]
	v_pk_mul_f32 v[0:1], v[4:5], v[78:79]
	v_and_b32_sdwa v6, v3, v134 dst_sel:DWORD dst_unused:UNUSED_PAD src0_sel:WORD_1 src1_sel:DWORD
	v_and_b32_sdwa v7, v2, v134 dst_sel:DWORD dst_unused:UNUSED_PAD src0_sel:WORD_1 src1_sel:DWORD
	v_and_b32_sdwa v4, v1, v134 dst_sel:DWORD dst_unused:UNUSED_PAD src0_sel:WORD_1 src1_sel:DWORD
	v_and_b32_sdwa v5, v0, v134 dst_sel:DWORD dst_unused:UNUSED_PAD src0_sel:WORD_1 src1_sel:DWORD
	v_add3_u32 v3, v3, v6, s31
	v_add3_u32 v2, v2, v7, s31
	v_add3_u32 v0, v0, v5, s31
	v_add3_u32 v1, v1, v4, s31
	v_and_b32_e32 v3, 0xffff0000, v3
	v_and_b32_e32 v2, 0xffff0000, v2
	v_or_b32_sdwa v1, v3, v1 dst_sel:DWORD dst_unused:UNUSED_PAD src0_sel:DWORD src1_sel:WORD_1
	v_or_b32_sdwa v0, v2, v0 dst_sel:DWORD dst_unused:UNUSED_PAD src0_sel:DWORD src1_sel:WORD_1
	global_store_dwordx2 v[74:75], v[0:1], off offset:3072
	global_load_dwordx4 v[0:3], v[50:51], off
	v_pk_mul_f32 v[6:7], v[92:93], v[124:125] op_sel_hi:[1,0]
	v_pk_mul_f32 v[4:5], v[96:97], v[124:125] op_sel_hi:[1,0]
	s_waitcnt vmcnt(0)
	v_mov_b32_e32 v79, v2
	v_mov_b32_e32 v2, v1
	v_mov_b32_e32 v78, v0
	v_pk_mul_f32 v[2:3], v[6:7], v[2:3]
	v_pk_mul_f32 v[0:1], v[4:5], v[78:79]
	v_and_b32_sdwa v6, v3, v134 dst_sel:DWORD dst_unused:UNUSED_PAD src0_sel:WORD_1 src1_sel:DWORD
	v_and_b32_sdwa v7, v2, v134 dst_sel:DWORD dst_unused:UNUSED_PAD src0_sel:WORD_1 src1_sel:DWORD
	v_and_b32_sdwa v4, v1, v134 dst_sel:DWORD dst_unused:UNUSED_PAD src0_sel:WORD_1 src1_sel:DWORD
	v_and_b32_sdwa v5, v0, v134 dst_sel:DWORD dst_unused:UNUSED_PAD src0_sel:WORD_1 src1_sel:DWORD
	v_add3_u32 v3, v3, v6, s31
	v_add3_u32 v2, v2, v7, s31
	v_add3_u32 v0, v0, v5, s31
	v_add3_u32 v1, v1, v4, s31
	v_and_b32_e32 v3, 0xffff0000, v3
	v_and_b32_e32 v2, 0xffff0000, v2
	v_or_b32_sdwa v1, v3, v1 dst_sel:DWORD dst_unused:UNUSED_PAD src0_sel:DWORD src1_sel:WORD_1
	v_or_b32_sdwa v0, v2, v0 dst_sel:DWORD dst_unused:UNUSED_PAD src0_sel:DWORD src1_sel:WORD_1
	global_store_dwordx2 v[74:75], v[0:1], off offset:3584
	global_load_dwordx4 v[0:3], v[52:53], off
	v_pk_mul_f32 v[6:7], v[100:101], v[124:125] op_sel_hi:[1,0]
	v_pk_mul_f32 v[4:5], v[102:103], v[124:125] op_sel_hi:[1,0]
	s_waitcnt vmcnt(0)
	v_mov_b32_e32 v75, v2
	v_mov_b32_e32 v2, v1
	v_mov_b32_e32 v74, v0
	v_pk_mul_f32 v[2:3], v[6:7], v[2:3]
	v_pk_mul_f32 v[0:1], v[4:5], v[74:75]
	v_and_b32_sdwa v6, v3, v134 dst_sel:DWORD dst_unused:UNUSED_PAD src0_sel:WORD_1 src1_sel:DWORD
	v_and_b32_sdwa v7, v2, v134 dst_sel:DWORD dst_unused:UNUSED_PAD src0_sel:WORD_1 src1_sel:DWORD
	v_and_b32_sdwa v4, v1, v134 dst_sel:DWORD dst_unused:UNUSED_PAD src0_sel:WORD_1 src1_sel:DWORD
	v_and_b32_sdwa v5, v0, v134 dst_sel:DWORD dst_unused:UNUSED_PAD src0_sel:WORD_1 src1_sel:DWORD
	v_add3_u32 v3, v3, v6, s31
	v_add3_u32 v2, v2, v7, s31
	v_add3_u32 v0, v0, v5, s31
	v_add3_u32 v1, v1, v4, s31
	v_and_b32_e32 v3, 0xffff0000, v3
	v_and_b32_e32 v2, 0xffff0000, v2
	v_or_b32_sdwa v1, v3, v1 dst_sel:DWORD dst_unused:UNUSED_PAD src0_sel:DWORD src1_sel:WORD_1
	v_or_b32_sdwa v0, v2, v0 dst_sel:DWORD dst_unused:UNUSED_PAD src0_sel:DWORD src1_sel:WORD_1
	global_store_dwordx2 v[76:77], v[0:1], off
	global_load_dwordx4 v[0:3], v[54:55], off
	v_pk_mul_f32 v[6:7], v[108:109], v[124:125] op_sel_hi:[1,0]
	v_pk_mul_f32 v[4:5], v[110:111], v[124:125] op_sel_hi:[1,0]
	s_waitcnt vmcnt(0)
	v_mov_b32_e32 v75, v2
	v_mov_b32_e32 v2, v1
	v_mov_b32_e32 v74, v0
	v_pk_mul_f32 v[2:3], v[6:7], v[2:3]
	v_pk_mul_f32 v[0:1], v[4:5], v[74:75]
	v_and_b32_sdwa v6, v3, v134 dst_sel:DWORD dst_unused:UNUSED_PAD src0_sel:WORD_1 src1_sel:DWORD
	v_and_b32_sdwa v7, v2, v134 dst_sel:DWORD dst_unused:UNUSED_PAD src0_sel:WORD_1 src1_sel:DWORD
	v_and_b32_sdwa v4, v1, v134 dst_sel:DWORD dst_unused:UNUSED_PAD src0_sel:WORD_1 src1_sel:DWORD
	v_and_b32_sdwa v5, v0, v134 dst_sel:DWORD dst_unused:UNUSED_PAD src0_sel:WORD_1 src1_sel:DWORD
	v_add3_u32 v3, v3, v6, s31
	v_add3_u32 v2, v2, v7, s31
	v_add3_u32 v0, v0, v5, s31
	v_add3_u32 v1, v1, v4, s31
	v_and_b32_e32 v3, 0xffff0000, v3
	v_and_b32_e32 v2, 0xffff0000, v2
	v_or_b32_sdwa v1, v3, v1 dst_sel:DWORD dst_unused:UNUSED_PAD src0_sel:DWORD src1_sel:WORD_1
	v_or_b32_sdwa v0, v2, v0 dst_sel:DWORD dst_unused:UNUSED_PAD src0_sel:DWORD src1_sel:WORD_1
	global_store_dwordx2 v[76:77], v[0:1], off offset:512
	global_load_dwordx4 v[0:3], v[56:57], off
	v_mov_b32_e32 v5, v10
	v_mov_b32_e32 v10, v9
	v_mov_b32_e32 v4, v8
	v_pk_mul_f32 v[6:7], v[10:11], v[124:125] op_sel_hi:[1,0]
	v_pk_mul_f32 v[4:5], v[4:5], v[124:125] op_sel_hi:[1,0]
	s_waitcnt vmcnt(0)
	v_mov_b32_e32 v9, v2
	v_mov_b32_e32 v2, v1
	v_mov_b32_e32 v8, v0
	v_pk_mul_f32 v[2:3], v[6:7], v[2:3]
	v_pk_mul_f32 v[0:1], v[4:5], v[8:9]
	v_and_b32_sdwa v6, v3, v134 dst_sel:DWORD dst_unused:UNUSED_PAD src0_sel:WORD_1 src1_sel:DWORD
	v_and_b32_sdwa v7, v2, v134 dst_sel:DWORD dst_unused:UNUSED_PAD src0_sel:WORD_1 src1_sel:DWORD
	v_and_b32_sdwa v4, v1, v134 dst_sel:DWORD dst_unused:UNUSED_PAD src0_sel:WORD_1 src1_sel:DWORD
	v_and_b32_sdwa v5, v0, v134 dst_sel:DWORD dst_unused:UNUSED_PAD src0_sel:WORD_1 src1_sel:DWORD
	v_add3_u32 v3, v3, v6, s31
	v_add3_u32 v2, v2, v7, s31
	v_add3_u32 v0, v0, v5, s31
	v_add3_u32 v1, v1, v4, s31
	v_and_b32_e32 v3, 0xffff0000, v3
	v_and_b32_e32 v2, 0xffff0000, v2
	v_or_b32_sdwa v1, v3, v1 dst_sel:DWORD dst_unused:UNUSED_PAD src0_sel:DWORD src1_sel:WORD_1
	v_or_b32_sdwa v0, v2, v0 dst_sel:DWORD dst_unused:UNUSED_PAD src0_sel:DWORD src1_sel:WORD_1
	global_store_dwordx2 v[76:77], v[0:1], off offset:1024
	global_load_dwordx4 v[0:3], v[58:59], off
	v_pk_mul_f32 v[6:7], v[104:105], v[124:125] op_sel_hi:[1,0]
	v_pk_mul_f32 v[4:5], v[106:107], v[124:125] op_sel_hi:[1,0]
	s_waitcnt vmcnt(0)
	v_mov_b32_e32 v9, v2
	v_mov_b32_e32 v2, v1
	v_mov_b32_e32 v8, v0
	v_pk_mul_f32 v[2:3], v[6:7], v[2:3]
	v_pk_mul_f32 v[0:1], v[4:5], v[8:9]
	v_and_b32_sdwa v6, v3, v134 dst_sel:DWORD dst_unused:UNUSED_PAD src0_sel:WORD_1 src1_sel:DWORD
	v_and_b32_sdwa v7, v2, v134 dst_sel:DWORD dst_unused:UNUSED_PAD src0_sel:WORD_1 src1_sel:DWORD
	v_and_b32_sdwa v4, v1, v134 dst_sel:DWORD dst_unused:UNUSED_PAD src0_sel:WORD_1 src1_sel:DWORD
	v_and_b32_sdwa v5, v0, v134 dst_sel:DWORD dst_unused:UNUSED_PAD src0_sel:WORD_1 src1_sel:DWORD
	v_add3_u32 v3, v3, v6, s31
	v_add3_u32 v2, v2, v7, s31
	v_add3_u32 v0, v0, v5, s31
	v_add3_u32 v1, v1, v4, s31
	v_and_b32_e32 v3, 0xffff0000, v3
	v_and_b32_e32 v2, 0xffff0000, v2
	v_or_b32_sdwa v1, v3, v1 dst_sel:DWORD dst_unused:UNUSED_PAD src0_sel:DWORD src1_sel:WORD_1
	v_or_b32_sdwa v0, v2, v0 dst_sel:DWORD dst_unused:UNUSED_PAD src0_sel:DWORD src1_sel:WORD_1
	global_store_dwordx2 v[76:77], v[0:1], off offset:1536
	global_load_dwordx4 v[0:3], v[60:61], off
	v_pk_mul_f32 v[6:7], v[112:113], v[124:125] op_sel_hi:[1,0]
	v_pk_mul_f32 v[4:5], v[114:115], v[124:125] op_sel_hi:[1,0]
	s_waitcnt vmcnt(0)
	v_mov_b32_e32 v9, v2
	v_mov_b32_e32 v2, v1
	v_mov_b32_e32 v8, v0
	v_pk_mul_f32 v[2:3], v[6:7], v[2:3]
	v_pk_mul_f32 v[0:1], v[4:5], v[8:9]
	v_and_b32_sdwa v6, v3, v134 dst_sel:DWORD dst_unused:UNUSED_PAD src0_sel:WORD_1 src1_sel:DWORD
	v_and_b32_sdwa v7, v2, v134 dst_sel:DWORD dst_unused:UNUSED_PAD src0_sel:WORD_1 src1_sel:DWORD
	v_and_b32_sdwa v4, v1, v134 dst_sel:DWORD dst_unused:UNUSED_PAD src0_sel:WORD_1 src1_sel:DWORD
	v_and_b32_sdwa v5, v0, v134 dst_sel:DWORD dst_unused:UNUSED_PAD src0_sel:WORD_1 src1_sel:DWORD
	v_add3_u32 v3, v3, v6, s31
	v_add3_u32 v2, v2, v7, s31
	v_add3_u32 v0, v0, v5, s31
	v_add3_u32 v1, v1, v4, s31
	v_and_b32_e32 v3, 0xffff0000, v3
	v_and_b32_e32 v2, 0xffff0000, v2
	v_or_b32_sdwa v1, v3, v1 dst_sel:DWORD dst_unused:UNUSED_PAD src0_sel:DWORD src1_sel:WORD_1
	v_or_b32_sdwa v0, v2, v0 dst_sel:DWORD dst_unused:UNUSED_PAD src0_sel:DWORD src1_sel:WORD_1
	global_store_dwordx2 v[76:77], v[0:1], off offset:2048
	global_load_dwordx4 v[0:3], v[62:63], off
	v_pk_mul_f32 v[6:7], v[116:117], v[124:125] op_sel_hi:[1,0]
	v_pk_mul_f32 v[4:5], v[118:119], v[124:125] op_sel_hi:[1,0]
	s_waitcnt vmcnt(0)
	v_mov_b32_e32 v9, v2
	v_mov_b32_e32 v2, v1
	v_mov_b32_e32 v8, v0
	v_pk_mul_f32 v[2:3], v[6:7], v[2:3]
	v_pk_mul_f32 v[0:1], v[4:5], v[8:9]
	v_and_b32_sdwa v6, v3, v134 dst_sel:DWORD dst_unused:UNUSED_PAD src0_sel:WORD_1 src1_sel:DWORD
	v_and_b32_sdwa v7, v2, v134 dst_sel:DWORD dst_unused:UNUSED_PAD src0_sel:WORD_1 src1_sel:DWORD
	v_and_b32_sdwa v4, v1, v134 dst_sel:DWORD dst_unused:UNUSED_PAD src0_sel:WORD_1 src1_sel:DWORD
	v_and_b32_sdwa v5, v0, v134 dst_sel:DWORD dst_unused:UNUSED_PAD src0_sel:WORD_1 src1_sel:DWORD
	v_add3_u32 v3, v3, v6, s31
	v_add3_u32 v2, v2, v7, s31
	v_add3_u32 v0, v0, v5, s31
	v_add3_u32 v1, v1, v4, s31
	v_and_b32_e32 v3, 0xffff0000, v3
	v_and_b32_e32 v2, 0xffff0000, v2
	v_or_b32_sdwa v1, v3, v1 dst_sel:DWORD dst_unused:UNUSED_PAD src0_sel:DWORD src1_sel:WORD_1
	v_or_b32_sdwa v0, v2, v0 dst_sel:DWORD dst_unused:UNUSED_PAD src0_sel:DWORD src1_sel:WORD_1
	global_store_dwordx2 v[76:77], v[0:1], off offset:2560
	global_load_dwordx4 v[0:3], v[64:65], off
	v_mov_b32_e32 v5, v14
	v_mov_b32_e32 v14, v13
	v_mov_b32_e32 v4, v12
	v_pk_mul_f32 v[6:7], v[14:15], v[124:125] op_sel_hi:[1,0]
	v_pk_mul_f32 v[4:5], v[4:5], v[124:125] op_sel_hi:[1,0]
	s_waitcnt vmcnt(0)
	v_mov_b32_e32 v9, v2
	v_mov_b32_e32 v2, v1
	v_mov_b32_e32 v8, v0
	v_pk_mul_f32 v[2:3], v[6:7], v[2:3]
	v_pk_mul_f32 v[0:1], v[4:5], v[8:9]
	v_and_b32_sdwa v6, v3, v134 dst_sel:DWORD dst_unused:UNUSED_PAD src0_sel:WORD_1 src1_sel:DWORD
	v_and_b32_sdwa v7, v2, v134 dst_sel:DWORD dst_unused:UNUSED_PAD src0_sel:WORD_1 src1_sel:DWORD
	v_and_b32_sdwa v4, v1, v134 dst_sel:DWORD dst_unused:UNUSED_PAD src0_sel:WORD_1 src1_sel:DWORD
	v_and_b32_sdwa v5, v0, v134 dst_sel:DWORD dst_unused:UNUSED_PAD src0_sel:WORD_1 src1_sel:DWORD
	v_add3_u32 v3, v3, v6, s31
	v_add3_u32 v2, v2, v7, s31
	v_add3_u32 v0, v0, v5, s31
	v_add3_u32 v1, v1, v4, s31
	v_and_b32_e32 v3, 0xffff0000, v3
	v_and_b32_e32 v2, 0xffff0000, v2
	v_or_b32_sdwa v1, v3, v1 dst_sel:DWORD dst_unused:UNUSED_PAD src0_sel:DWORD src1_sel:WORD_1
	v_or_b32_sdwa v0, v2, v0 dst_sel:DWORD dst_unused:UNUSED_PAD src0_sel:DWORD src1_sel:WORD_1
	global_store_dwordx2 v[76:77], v[0:1], off offset:3072
	global_load_dwordx4 v[0:3], v[66:67], off
	v_pk_mul_f32 v[6:7], v[120:121], v[124:125] op_sel_hi:[1,0]
	v_pk_mul_f32 v[4:5], v[122:123], v[124:125] op_sel_hi:[1,0]
	s_waitcnt vmcnt(0)
	v_mov_b32_e32 v9, v2
	v_mov_b32_e32 v2, v1
	v_mov_b32_e32 v8, v0
	v_pk_mul_f32 v[2:3], v[6:7], v[2:3]
	v_pk_mul_f32 v[0:1], v[4:5], v[8:9]
	v_and_b32_sdwa v6, v3, v134 dst_sel:DWORD dst_unused:UNUSED_PAD src0_sel:WORD_1 src1_sel:DWORD
	v_and_b32_sdwa v7, v2, v134 dst_sel:DWORD dst_unused:UNUSED_PAD src0_sel:WORD_1 src1_sel:DWORD
	v_and_b32_sdwa v4, v1, v134 dst_sel:DWORD dst_unused:UNUSED_PAD src0_sel:WORD_1 src1_sel:DWORD
	v_and_b32_sdwa v5, v0, v134 dst_sel:DWORD dst_unused:UNUSED_PAD src0_sel:WORD_1 src1_sel:DWORD
	v_add3_u32 v3, v3, v6, s31
	v_add3_u32 v2, v2, v7, s31
	v_add3_u32 v0, v0, v5, s31
	v_add3_u32 v1, v1, v4, s31
	v_and_b32_e32 v3, 0xffff0000, v3
	v_and_b32_e32 v2, 0xffff0000, v2
	v_or_b32_sdwa v1, v3, v1 dst_sel:DWORD dst_unused:UNUSED_PAD src0_sel:DWORD src1_sel:WORD_1
	v_or_b32_sdwa v0, v2, v0 dst_sel:DWORD dst_unused:UNUSED_PAD src0_sel:DWORD src1_sel:WORD_1
	global_store_dwordx2 v[76:77], v[0:1], off offset:3584
	s_branch .LBB0_1691

.LBB0_2076:
	s_waitcnt lgkmcnt(0)
	v_lshl_add_u64 v[6:7], s[14:15], 0, v[108:109]
	v_add_co_u32_e32 v28, vcc, s13, v6
	v_lshl_add_u64 v[8:9], s[14:15], 0, v[110:111]
	s_nop 0
	v_addc_co_u32_e32 v29, vcc, 0, v7, vcc
	v_add_co_u32_e32 v16, vcc, s25, v6
	v_lshl_add_u64 v[18:19], s[6:7], 0, v[110:111]
	s_nop 0
	v_addc_co_u32_e32 v17, vcc, 0, v7, vcc
	v_add_co_u32_e32 v12, vcc, s23, v8
	v_lshl_add_u64 v[4:5], s[14:15], 0, v[106:107]
	s_nop 0
	v_addc_co_u32_e32 v13, vcc, 0, v9, vcc
	v_add_co_u32_e32 v30, vcc, s24, v8
	global_load_dwordx4 v[0:3], v[54:55], off
	s_nop 0
	v_addc_co_u32_e32 v31, vcc, 0, v9, vcc
	v_add_co_u32_e32 v34, vcc, s20, v18
	s_add_i32 s12, s12, s10
	s_nop 0
	v_addc_co_u32_e32 v35, vcc, 0, v19, vcc
	v_add_co_u32_e32 v22, vcc, s21, v18
	v_lshl_add_u64 v[106:107], v[106:107], 0, s[4:5]
	s_nop 0
	v_addc_co_u32_e32 v23, vcc, 0, v19, vcc
	v_add_co_u32_e32 v32, vcc, s27, v8
	v_lshl_add_u64 v[108:109], v[108:109], 0, s[16:17]
	s_nop 0
	v_addc_co_u32_e32 v33, vcc, 0, v9, vcc
	v_add_co_u32_e32 v114, vcc, s28, v8
	v_lshl_add_u64 v[110:111], v[110:111], 0, s[18:19]
	s_nop 0
	v_addc_co_u32_e32 v115, vcc, 0, v9, vcc
	v_add_co_u32_e32 v116, vcc, s22, v18
	s_cmpk_gt_i32 s12, 0x3fff
	s_nop 0
	v_addc_co_u32_e32 v117, vcc, 0, v19, vcc
	v_add_co_u32_e32 v118, vcc, s30, v6
	s_nop 1
	v_addc_co_u32_e32 v119, vcc, 0, v7, vcc
	v_add_co_u32_e32 v112, vcc, s31, v6
	s_nop 1
	v_addc_co_u32_e32 v113, vcc, 0, v7, vcc
	global_load_dword v14, v[4:5], off
	global_load_dwordx2 v[10:11], v[16:17], off offset:-4096
	global_load_dwordx4 v[6:9], v[30:31], off offset:-4096
	s_waitcnt vmcnt(2)
	ds_bpermute_b32 v15, v123, v14
	s_waitcnt vmcnt(1)
	v_lshlrev_b32_e32 v4, 16, v10
	v_and_b32_e32 v5, 0xffff0000, v10
	v_lshlrev_b32_e32 v10, 16, v11
	v_and_b32_e32 v11, 0xffff0000, v11
	s_waitcnt lgkmcnt(0)
	v_add_f32_e32 v14, v14, v15
	ds_bpermute_b32 v15, v132, v14
	s_waitcnt lgkmcnt(0)
	v_add_f32_e32 v14, v14, v15
	ds_bpermute_b32 v15, v133, v14
	s_waitcnt lgkmcnt(0)
	v_add_f32_e32 v14, v14, v15
	ds_bpermute_b32 v15, v134, v14
	s_waitcnt lgkmcnt(0)
	v_add_f32_e32 v14, v14, v15
	ds_bpermute_b32 v15, v135, v14
	s_waitcnt lgkmcnt(0)
	v_add_f32_e32 v14, v14, v15
	ds_bpermute_b32 v15, v136, v14
	s_waitcnt lgkmcnt(0)
	v_add_f32_e32 v14, v14, v15
	v_fmamk_f32 v14, v14, 0x39800000, v137
	v_mul_f32_e32 v15, 0x4f800000, v14
	v_cmp_gt_f32_e32 vcc, s11, v14
	s_nop 1
	v_cndmask_b32_e32 v14, v14, v15, vcc
	v_sqrt_f32_e32 v15, v14
	s_nop 0
	v_add_u32_e32 v20, -1, v15
	v_add_u32_e32 v21, 1, v15
	v_fma_f32 v24, -v20, v15, v14
	v_fma_f32 v25, -v21, v15, v14
	v_cmp_ge_f32_e64 s[2:3], 0, v24
	s_nop 1
	v_cndmask_b32_e64 v15, v15, v20, s[2:3]
	v_cmp_lt_f32_e64 s[2:3], 0, v25
	s_nop 1
	v_cndmask_b32_e64 v15, v15, v21, s[2:3]
	v_mul_f32_e32 v20, 0x37800000, v15
	v_cndmask_b32_e32 v15, v15, v20, vcc
	v_cmp_class_f32_e32 vcc, v14, v138
	s_nop 1
	v_cndmask_b32_e32 v14, v15, v14, vcc
	v_div_scale_f32 v15, s[2:3], v14, v14, 1.0
	v_rcp_f32_e32 v21, v15
	v_div_scale_f32 v20, vcc, 1.0, v14, 1.0
	v_fma_f32 v24, -v15, v21, 1.0
	v_fmac_f32_e32 v21, v24, v21
	v_mul_f32_e32 v24, v20, v21
	v_fma_f32 v25, -v15, v24, v20
	v_fmac_f32_e32 v24, v25, v21
	v_fma_f32 v15, -v15, v24, v20
	v_div_fmas_f32 v15, v15, v21, v24
	v_div_fixup_f32 v122, v15, v14, 1.0
	v_pk_mul_f32 v[4:5], v[122:123], v[4:5] op_sel_hi:[0,1]
	v_pk_mul_f32 v[10:11], v[122:123], v[10:11] op_sel_hi:[0,1]
	s_waitcnt vmcnt(0)
	v_pk_fma_f32 v[0:1], v[0:1], v[4:5], v[6:7]
	v_pk_fma_f32 v[2:3], v[2:3], v[10:11], v[8:9]
	global_store_dwordx4 v[18:19], v[0:3], off nt
	v_mov_b32_e32 v120, v0
	v_mov_b32_e32 v121, v2
	v_mov_b32_e32 v2, v1
	global_load_dwordx2 v[0:1], v[28:29], off offset:512
	global_load_dwordx4 v[4:7], v[12:13], off offset:1024
	global_load_dwordx4 v[8:11], v[54:55], off offset:1024
	v_pk_mul_f32 v[14:15], v[2:3], v[2:3]
	s_nop 0
	v_pk_fma_f32 v[14:15], v[120:121], v[120:121], v[14:15]
	s_nop 0
	v_pk_add_f32 v[40:41], v[14:15], v[14:15] op_sel:[0,1] op_sel_hi:[1,0]
	s_waitcnt vmcnt(2)
	v_lshlrev_b32_e32 v14, 16, v0
	v_and_b32_e32 v15, 0xffff0000, v0
	v_lshlrev_b32_e32 v0, 16, v1
	v_and_b32_e32 v1, 0xffff0000, v1
	v_pk_mul_f32 v[14:15], v[122:123], v[14:15] op_sel_hi:[0,1]
	v_pk_mul_f32 v[0:1], v[122:123], v[0:1] op_sel_hi:[0,1]
	s_waitcnt vmcnt(0)
	v_pk_fma_f32 v[4:5], v[8:9], v[14:15], v[4:5]
	v_pk_fma_f32 v[6:7], v[10:11], v[0:1], v[6:7]
	global_store_dwordx4 v[18:19], v[4:7], off offset:1024 nt
	v_mov_b32_e32 v0, v4
	v_mov_b32_e32 v1, v6
	v_mov_b32_e32 v6, v5
	global_load_dwordx2 v[4:5], v[28:29], off offset:1024
	global_load_dwordx4 v[8:11], v[12:13], off offset:2048
	global_load_dwordx4 v[24:27], v[54:55], off offset:2048
	v_pk_mul_f32 v[14:15], v[6:7], v[6:7]
	s_nop 0
	v_pk_fma_f32 v[14:15], v[0:1], v[0:1], v[14:15]
	s_nop 0
	v_pk_add_f32 v[42:43], v[14:15], v[14:15] op_sel:[0,1] op_sel_hi:[1,0]
	s_waitcnt vmcnt(2)
	v_lshlrev_b32_e32 v14, 16, v4
	v_and_b32_e32 v15, 0xffff0000, v4
	v_lshlrev_b32_e32 v4, 16, v5
	v_and_b32_e32 v5, 0xffff0000, v5
	v_pk_mul_f32 v[14:15], v[122:123], v[14:15] op_sel_hi:[0,1]
	v_pk_mul_f32 v[4:5], v[122:123], v[4:5] op_sel_hi:[0,1]
	s_waitcnt vmcnt(0)
	v_pk_fma_f32 v[8:9], v[24:25], v[14:15], v[8:9]
	v_pk_fma_f32 v[10:11], v[26:27], v[4:5], v[10:11]
	global_store_dwordx4 v[18:19], v[8:11], off offset:2048 nt
	global_load_dwordx2 v[44:45], v[28:29], off offset:1536
	global_load_dwordx4 v[24:27], v[12:13], off offset:3072
	global_load_dwordx4 v[36:39], v[54:55], off offset:3072
	v_mul_f32_e32 v14, v9, v9
	v_mul_f32_e32 v20, v11, v11
	v_mov_b32_e32 v4, v8
	v_mov_b32_e32 v5, v10
	v_pk_fma_f32 v[46:47], v[8:9], v[8:9], v[14:15] op_sel_hi:[1,1,0]
	v_pk_fma_f32 v[48:49], v[10:11], v[10:11], v[20:21] op_sel_hi:[1,1,0]
	v_mov_b32_e32 v10, v9
	s_waitcnt vmcnt(2)
	v_lshlrev_b32_e32 v8, 16, v44
	v_and_b32_e32 v9, 0xffff0000, v44
	v_lshlrev_b32_e32 v12, 16, v45
	v_and_b32_e32 v13, 0xffff0000, v45
	v_pk_mul_f32 v[8:9], v[122:123], v[8:9] op_sel_hi:[0,1]
	v_pk_mul_f32 v[14:15], v[122:123], v[12:13] op_sel_hi:[0,1]
	s_waitcnt vmcnt(0)
	v_pk_fma_f32 v[12:13], v[36:37], v[8:9], v[24:25]
	v_pk_fma_f32 v[14:15], v[38:39], v[14:15], v[26:27]
	global_store_dwordx4 v[18:19], v[12:15], off offset:3072 nt
	v_pk_mul_f32 v[36:37], v[12:13], v[12:13]
	v_pk_mul_f32 v[38:39], v[14:15], v[14:15]
	v_mov_b32_e32 v8, v12
	v_mov_b32_e32 v9, v14
	v_mov_b32_e32 v14, v13
	global_load_dwordx2 v[12:13], v[28:29], off offset:2048
	global_load_dwordx4 v[18:21], v[30:31], off
	global_load_dwordx4 v[24:27], v[56:57], off
	v_mov_b32_e32 v41, v36
	v_mov_b32_e32 v43, v37
	v_mov_b32_e32 v47, v38
	v_mov_b32_e32 v49, v39
	v_pk_add_f32 v[36:37], v[40:41], v[42:43]
	v_pk_add_f32 v[38:39], v[46:47], v[48:49]
	s_nop 0
	v_pk_add_f32 v[36:37], v[36:37], v[38:39]
	s_nop 0
	v_pk_add_f32 v[40:41], v[36:37], v[36:37] op_sel:[0,1] op_sel_hi:[1,0]
	s_waitcnt vmcnt(2)
	v_lshlrev_b32_e32 v36, 16, v12
	v_and_b32_e32 v37, 0xffff0000, v12
	v_lshlrev_b32_e32 v12, 16, v13
	v_and_b32_e32 v13, 0xffff0000, v13
	v_pk_mul_f32 v[36:37], v[122:123], v[36:37] op_sel_hi:[0,1]
	v_pk_mul_f32 v[12:13], v[122:123], v[12:13] op_sel_hi:[0,1]
	s_waitcnt vmcnt(0)
	v_pk_fma_f32 v[18:19], v[24:25], v[36:37], v[18:19]
	v_pk_fma_f32 v[20:21], v[26:27], v[12:13], v[20:21]
	global_store_dwordx4 v[22:23], v[18:21], off offset:-4096 nt
	v_mov_b32_e32 v12, v18
	v_mov_b32_e32 v13, v20
	v_mov_b32_e32 v20, v19
	global_load_dwordx2 v[18:19], v[28:29], off offset:2560
	global_load_dwordx4 v[24:27], v[30:31], off offset:1024
	global_load_dwordx4 v[36:39], v[58:59], off
	v_pk_mul_f32 v[42:43], v[20:21], v[20:21]
	s_nop 0
	v_pk_fma_f32 v[42:43], v[12:13], v[12:13], v[42:43]
	s_nop 0
	v_pk_add_f32 v[46:47], v[42:43], v[42:43] op_sel:[0,1] op_sel_hi:[1,0]
	s_waitcnt vmcnt(2)
	v_lshlrev_b32_e32 v42, 16, v18
	v_and_b32_e32 v43, 0xffff0000, v18
	v_lshlrev_b32_e32 v18, 16, v19
	v_and_b32_e32 v19, 0xffff0000, v19
	v_pk_mul_f32 v[42:43], v[122:123], v[42:43] op_sel_hi:[0,1]
	v_pk_mul_f32 v[18:19], v[122:123], v[18:19] op_sel_hi:[0,1]
	s_waitcnt vmcnt(0)
	v_pk_fma_f32 v[24:25], v[36:37], v[42:43], v[24:25]
	v_pk_fma_f32 v[26:27], v[38:39], v[18:19], v[26:27]
	global_store_dwordx4 v[34:35], v[24:27], off offset:1024 nt
	global_load_dwordx2 v[50:51], v[28:29], off offset:3072
	global_load_dwordx4 v[36:39], v[30:31], off offset:2048
	global_load_dwordx4 v[42:45], v[60:61], off
	v_mul_f32_e32 v18, v25, v25
	v_mul_f32_e32 v48, v27, v27
	v_mov_b32_e32 v124, v24
	v_mov_b32_e32 v125, v26
	v_pk_fma_f32 v[18:19], v[24:25], v[24:25], v[18:19] op_sel_hi:[1,1,0]
	v_pk_fma_f32 v[48:49], v[26:27], v[26:27], v[48:49] op_sel_hi:[1,1,0]
	v_mov_b32_e32 v26, v25
	s_waitcnt vmcnt(2)
	v_lshlrev_b32_e32 v24, 16, v50
	v_and_b32_e32 v25, 0xffff0000, v50
	v_lshlrev_b32_e32 v50, 16, v51
	v_and_b32_e32 v51, 0xffff0000, v51
	v_pk_mul_f32 v[24:25], v[122:123], v[24:25] op_sel_hi:[0,1]
	v_pk_mul_f32 v[50:51], v[122:123], v[50:51] op_sel_hi:[0,1]
	s_waitcnt vmcnt(0)
	v_pk_fma_f32 v[42:43], v[42:43], v[24:25], v[36:37]
	v_pk_fma_f32 v[44:45], v[44:45], v[50:51], v[38:39]
	global_store_dwordx4 v[34:35], v[42:45], off offset:2048 nt
	v_pk_mul_f32 v[24:25], v[42:43], v[42:43]
	v_pk_mul_f32 v[50:51], v[44:45], v[44:45]
	v_mov_b32_e32 v128, v42
	v_mov_b32_e32 v129, v44
	v_mov_b32_e32 v44, v43
	global_load_dwordx2 v[42:43], v[28:29], off offset:3584
	s_nop 0
	global_load_dwordx4 v[28:31], v[30:31], off offset:3072
	s_nop 0
	global_load_dwordx4 v[36:39], v[62:63], off
	v_mov_b32_e32 v41, v24
	v_mov_b32_e32 v47, v25
	v_mov_b32_e32 v19, v50
	v_mov_b32_e32 v49, v51
	v_pk_add_f32 v[24:25], v[40:41], v[46:47]
	v_pk_add_f32 v[18:19], v[18:19], v[48:49]
	s_waitcnt vmcnt(2)
	v_lshlrev_b32_e32 v40, 16, v43
	v_pk_add_f32 v[18:19], v[24:25], v[18:19]
	v_lshlrev_b32_e32 v24, 16, v42
	v_and_b32_e32 v25, 0xffff0000, v42
	v_and_b32_e32 v41, 0xffff0000, v43
	v_pk_mul_f32 v[24:25], v[122:123], v[24:25] op_sel_hi:[0,1]
	v_pk_mul_f32 v[40:41], v[122:123], v[40:41] op_sel_hi:[0,1]
	s_waitcnt vmcnt(0)
	v_pk_fma_f32 v[46:47], v[36:37], v[24:25], v[28:29]
	v_pk_fma_f32 v[48:49], v[38:39], v[40:41], v[30:31]
	global_store_dwordx4 v[34:35], v[46:49], off offset:3072 nt
	global_load_dwordx2 v[24:25], v[16:17], off
	global_load_dwordx4 v[28:31], v[114:115], off offset:-4096
	s_nop 0
	global_load_dwordx4 v[34:37], v[64:65], off
	v_mov_b32_e32 v130, v46
	v_mov_b32_e32 v131, v48
	v_mov_b32_e32 v48, v47
	v_pk_mul_f32 v[38:39], v[48:49], v[48:49]
	v_pk_add_f32 v[18:19], v[18:19], v[18:19] op_sel:[0,1] op_sel_hi:[1,0]
	v_pk_fma_f32 v[38:39], v[130:131], v[130:131], v[38:39]
	s_waitcnt vmcnt(2)
	v_lshlrev_b32_e32 v40, 16, v24
	v_and_b32_e32 v41, 0xffff0000, v24
	v_lshlrev_b32_e32 v24, 16, v25
	v_and_b32_e32 v25, 0xffff0000, v25
	v_pk_mul_f32 v[40:41], v[122:123], v[40:41] op_sel_hi:[0,1]
	v_pk_mul_f32 v[24:25], v[122:123], v[24:25] op_sel_hi:[0,1]
	s_waitcnt vmcnt(0)
	v_pk_fma_f32 v[50:51], v[34:35], v[40:41], v[28:29]
	v_pk_fma_f32 v[52:53], v[36:37], v[24:25], v[30:31]
	global_store_dwordx4 v[22:23], v[50:53], off nt
	global_load_dwordx2 v[42:43], v[16:17], off offset:512
	global_load_dwordx4 v[28:31], v[32:33], off offset:1024
	global_load_dwordx4 v[34:37], v[66:67], off
	v_mul_f32_e32 v40, v53, v53
	v_pk_fma_f32 v[46:47], v[52:53], v[52:53], v[40:41] op_sel_hi:[1,1,0]
	v_mul_f32_e32 v24, v51, v51
	v_mov_b32_e32 v144, v50
	v_mov_b32_e32 v145, v52
	v_pk_fma_f32 v[24:25], v[50:51], v[50:51], v[24:25] op_sel_hi:[1,1,0]
	v_mov_b32_e32 v52, v51
	v_pk_add_f32 v[38:39], v[38:39], v[38:39] op_sel:[0,1] op_sel_hi:[1,0]
	s_waitcnt vmcnt(2)
	v_lshlrev_b32_e32 v40, 16, v42
	v_and_b32_e32 v41, 0xffff0000, v42
	v_lshlrev_b32_e32 v42, 16, v43
	v_and_b32_e32 v43, 0xffff0000, v43
	v_pk_mul_f32 v[40:41], v[122:123], v[40:41] op_sel_hi:[0,1]
	v_pk_mul_f32 v[42:43], v[122:123], v[42:43] op_sel_hi:[0,1]
	s_waitcnt vmcnt(0)
	v_pk_fma_f32 v[34:35], v[34:35], v[40:41], v[28:29]
	v_pk_fma_f32 v[36:37], v[36:37], v[42:43], v[30:31]
	global_store_dwordx4 v[22:23], v[34:37], off offset:1024 nt
	v_pk_mul_f32 v[126:127], v[34:35], v[34:35]
	v_pk_mul_f32 v[140:141], v[36:37], v[36:37]
	v_mov_b32_e32 v50, v34
	v_mov_b32_e32 v51, v36
	v_mov_b32_e32 v36, v35
	global_load_dwordx2 v[34:35], v[16:17], off offset:1024
	global_load_dwordx4 v[28:31], v[32:33], off offset:2048
	global_load_dwordx4 v[40:43], v[68:69], off
	v_mov_b32_e32 v19, v126
	v_mov_b32_e32 v39, v127
	v_mov_b32_e32 v25, v140
	v_mov_b32_e32 v47, v141
	v_pk_add_f32 v[18:19], v[18:19], v[38:39]
	v_pk_add_f32 v[24:25], v[24:25], v[46:47]
	s_nop 0
	v_pk_add_f32 v[18:19], v[18:19], v[24:25]
	s_waitcnt vmcnt(2)
	v_lshlrev_b32_e32 v24, 16, v34
	v_and_b32_e32 v25, 0xffff0000, v34
	v_lshlrev_b32_e32 v34, 16, v35
	v_and_b32_e32 v35, 0xffff0000, v35
	v_pk_mul_f32 v[24:25], v[122:123], v[24:25] op_sel_hi:[0,1]
	v_pk_mul_f32 v[34:35], v[122:123], v[34:35] op_sel_hi:[0,1]
	s_waitcnt vmcnt(0)
	v_pk_fma_f32 v[40:41], v[40:41], v[24:25], v[28:29]
	v_pk_fma_f32 v[42:43], v[42:43], v[34:35], v[30:31]
	global_store_dwordx4 v[22:23], v[40:43], off offset:2048 nt
	global_load_dwordx2 v[24:25], v[16:17], off offset:1536
	global_load_dwordx4 v[28:31], v[32:33], off offset:3072
	s_nop 0
	global_load_dwordx4 v[32:35], v[70:71], off
	v_mov_b32_e32 v127, v42
	v_mov_b32_e32 v42, v41
	v_mov_b32_e32 v126, v40
	v_pk_mul_f32 v[38:39], v[42:43], v[42:43]
	v_pk_add_f32 v[18:19], v[18:19], v[18:19] op_sel:[0,1] op_sel_hi:[1,0]
	v_pk_fma_f32 v[38:39], v[126:127], v[126:127], v[38:39]
	s_nop 0
	v_pk_add_f32 v[46:47], v[38:39], v[38:39] op_sel:[0,1] op_sel_hi:[1,0]
	s_waitcnt vmcnt(2)
	v_lshlrev_b32_e32 v38, 16, v24
	v_and_b32_e32 v39, 0xffff0000, v24
	v_lshlrev_b32_e32 v24, 16, v25
	v_and_b32_e32 v25, 0xffff0000, v25
	v_pk_mul_f32 v[38:39], v[122:123], v[38:39] op_sel_hi:[0,1]
	v_pk_mul_f32 v[24:25], v[122:123], v[24:25] op_sel_hi:[0,1]
	s_waitcnt vmcnt(0)
	v_pk_fma_f32 v[38:39], v[32:33], v[38:39], v[28:29]
	v_pk_fma_f32 v[40:41], v[34:35], v[24:25], v[30:31]
	global_store_dwordx4 v[22:23], v[38:41], off offset:3072 nt
	global_load_dwordx2 v[140:141], v[16:17], off offset:2048
	s_nop 0
	global_load_dwordx4 v[22:25], v[114:115], off
	global_load_dwordx4 v[28:31], v[72:73], off
	v_mul_f32_e32 v32, v39, v39
	v_mul_f32_e32 v34, v41, v41
	v_pk_fma_f32 v[142:143], v[38:39], v[38:39], v[32:33] op_sel_hi:[1,1,0]
	v_pk_fma_f32 v[146:147], v[40:41], v[40:41], v[34:35] op_sel_hi:[1,1,0]
	s_waitcnt vmcnt(2)
	v_lshlrev_b32_e32 v32, 16, v140
	v_and_b32_e32 v33, 0xffff0000, v140
	v_lshlrev_b32_e32 v34, 16, v141
	v_and_b32_e32 v35, 0xffff0000, v141
	v_pk_mul_f32 v[32:33], v[122:123], v[32:33] op_sel_hi:[0,1]
	v_pk_mul_f32 v[34:35], v[122:123], v[34:35] op_sel_hi:[0,1]
	s_waitcnt vmcnt(0)
	v_pk_fma_f32 v[32:33], v[28:29], v[32:33], v[22:23]
	v_pk_fma_f32 v[34:35], v[30:31], v[34:35], v[24:25]
	global_store_dwordx4 v[116:117], v[32:35], off nt
	global_load_dwordx2 v[150:151], v[16:17], off offset:2560
	global_load_dwordx4 v[22:25], v[114:115], off offset:1024
	global_load_dwordx4 v[28:31], v[74:75], off
	v_pk_mul_f32 v[140:141], v[32:33], v[32:33]
	v_pk_mul_f32 v[148:149], v[34:35], v[34:35]
	v_mov_b32_e32 v19, v140
	v_mov_b32_e32 v47, v141
	v_mov_b32_e32 v143, v148
	v_mov_b32_e32 v147, v149
	v_pk_add_f32 v[18:19], v[18:19], v[46:47]
	v_pk_add_f32 v[46:47], v[142:143], v[146:147]
	s_nop 0
	v_pk_add_f32 v[18:19], v[18:19], v[46:47]
	s_waitcnt vmcnt(2)
	v_lshlrev_b32_e32 v46, 16, v151
	v_pk_add_f32 v[146:147], v[18:19], v[18:19] op_sel:[0,1] op_sel_hi:[1,0]
	v_lshlrev_b32_e32 v18, 16, v150
	v_and_b32_e32 v19, 0xffff0000, v150
	v_and_b32_e32 v47, 0xffff0000, v151
	v_pk_mul_f32 v[18:19], v[122:123], v[18:19] op_sel_hi:[0,1]
	v_pk_mul_f32 v[46:47], v[122:123], v[46:47] op_sel_hi:[0,1]
	s_waitcnt vmcnt(0)
	v_pk_fma_f32 v[28:29], v[28:29], v[18:19], v[22:23]
	v_pk_fma_f32 v[30:31], v[30:31], v[46:47], v[24:25]
	global_store_dwordx4 v[116:117], v[28:31], off offset:1024 nt
	global_load_dwordx2 v[18:19], v[16:17], off offset:3072
	global_load_dwordx4 v[22:25], v[114:115], off offset:2048
	global_load_dwordx4 v[140:143], v[76:77], off
	v_mov_b32_e32 v47, v30
	v_mov_b32_e32 v30, v29
	v_mov_b32_e32 v46, v28
	v_pk_mul_f32 v[28:29], v[30:31], v[30:31]
	s_waitcnt vmcnt(2)
	v_lshlrev_b32_e32 v148, 16, v18
	v_and_b32_e32 v149, 0xffff0000, v18
	v_lshlrev_b32_e32 v18, 16, v19
	v_and_b32_e32 v19, 0xffff0000, v19
	v_pk_mul_f32 v[148:149], v[122:123], v[148:149] op_sel_hi:[0,1]
	v_pk_mul_f32 v[18:19], v[122:123], v[18:19] op_sel_hi:[0,1]
	s_waitcnt vmcnt(0)
	v_pk_fma_f32 v[22:23], v[140:141], v[148:149], v[22:23]
	v_pk_fma_f32 v[24:25], v[142:143], v[18:19], v[24:25]
	global_store_dwordx4 v[116:117], v[22:25], off offset:2048 nt
	global_load_dwordx2 v[152:153], v[16:17], off offset:3584
	s_nop 0
	global_load_dwordx4 v[16:19], v[114:115], off offset:3072
	global_load_dwordx4 v[140:143], v[78:79], off
	v_pk_fma_f32 v[28:29], v[46:47], v[46:47], v[28:29]
	v_mul_f32_e32 v148, v23, v23
	v_mul_f32_e32 v150, v25, v25
	v_pk_add_f32 v[28:29], v[28:29], v[28:29] op_sel:[0,1] op_sel_hi:[1,0]
	v_pk_fma_f32 v[148:149], v[22:23], v[22:23], v[148:149] op_sel_hi:[1,1,0]
	v_pk_fma_f32 v[150:151], v[24:25], v[24:25], v[150:151] op_sel_hi:[1,1,0]
	s_waitcnt vmcnt(2)
	v_lshlrev_b32_e32 v114, 16, v152
	v_and_b32_e32 v115, 0xffff0000, v152
	v_lshlrev_b32_e32 v152, 16, v153
	v_and_b32_e32 v153, 0xffff0000, v153
	v_pk_mul_f32 v[114:115], v[122:123], v[114:115] op_sel_hi:[0,1]
	v_pk_mul_f32 v[152:153], v[122:123], v[152:153] op_sel_hi:[0,1]
	s_waitcnt vmcnt(0)
	v_pk_fma_f32 v[16:17], v[140:141], v[114:115], v[16:17]
	v_pk_fma_f32 v[18:19], v[142:143], v[152:153], v[18:19]
	global_store_dwordx4 v[116:117], v[16:19], off offset:3072 nt
	v_pk_mul_f32 v[114:115], v[16:17], v[16:17]
	v_pk_mul_f32 v[116:117], v[18:19], v[18:19]
	v_mov_b32_e32 v147, v114
	v_mov_b32_e32 v29, v115
	v_mov_b32_e32 v149, v116
	v_mov_b32_e32 v151, v117
	global_load_dwordx4 v[114:117], v[80:81], off
	v_pk_add_f32 v[28:29], v[146:147], v[28:29]
	v_pk_add_f32 v[140:141], v[148:149], v[150:151]
	s_nop 0
	v_pk_add_f32 v[28:29], v[28:29], v[140:141]
	s_nop 0
	v_add_f32_e32 v28, v28, v29
	ds_bpermute_b32 v29, v123, v28
	s_waitcnt lgkmcnt(0)
	v_add_f32_e32 v28, v28, v29
	ds_bpermute_b32 v29, v132, v28
	s_waitcnt lgkmcnt(0)
	v_add_f32_e32 v28, v28, v29
	ds_bpermute_b32 v29, v133, v28
	s_waitcnt lgkmcnt(0)
	v_add_f32_e32 v28, v28, v29
	ds_bpermute_b32 v29, v134, v28
	s_waitcnt lgkmcnt(0)
	v_add_f32_e32 v28, v28, v29
	ds_bpermute_b32 v29, v135, v28
	s_waitcnt lgkmcnt(0)
	v_add_f32_e32 v28, v28, v29
	ds_bpermute_b32 v29, v136, v28
	s_waitcnt lgkmcnt(0)
	v_add_f32_e32 v28, v28, v29
	v_fmamk_f32 v28, v28, 0x39800000, v137
	v_mul_f32_e32 v29, 0x4f800000, v28
	v_cmp_gt_f32_e32 vcc, s11, v28
	s_nop 1
	v_cndmask_b32_e32 v28, v28, v29, vcc
	v_sqrt_f32_e32 v29, v28
	s_nop 0
	v_add_u32_e32 v122, -1, v29
	v_add_u32_e32 v140, 1, v29
	v_fma_f32 v141, -v122, v29, v28
	v_fma_f32 v142, -v140, v29, v28
	v_cmp_ge_f32_e64 s[2:3], 0, v141
	s_nop 1
	v_cndmask_b32_e64 v29, v29, v122, s[2:3]
	v_cmp_lt_f32_e64 s[2:3], 0, v142
	s_nop 1
	v_cndmask_b32_e64 v29, v29, v140, s[2:3]
	v_mul_f32_e32 v122, 0x37800000, v29
	v_cndmask_b32_e32 v29, v29, v122, vcc
	v_cmp_class_f32_e32 vcc, v28, v138
	s_nop 1
	v_cndmask_b32_e32 v28, v29, v28, vcc
	v_div_scale_f32 v29, s[2:3], v28, v28, 1.0
	v_rcp_f32_e32 v140, v29
	v_div_scale_f32 v122, vcc, 1.0, v28, 1.0
	v_fma_f32 v141, -v29, v140, 1.0
	v_fmac_f32_e32 v140, v141, v140
	v_mul_f32_e32 v141, v122, v140
	v_fma_f32 v142, -v29, v141, v122
	v_fmac_f32_e32 v141, v142, v140
	v_fma_f32 v29, -v29, v141, v122
	v_div_fmas_f32 v29, v29, v140, v141
	v_div_fixup_f32 v28, v29, v28, 1.0
	v_pk_mul_f32 v[2:3], v[2:3], v[28:29] op_sel_hi:[1,0]
	v_pk_mul_f32 v[140:141], v[0:1], v[28:29] op_sel_hi:[1,0]
	s_waitcnt vmcnt(0)
	v_mov_b32_e32 v1, v116
	v_mov_b32_e32 v116, v115
	v_pk_mul_f32 v[120:121], v[120:121], v[28:29] op_sel_hi:[1,0]
	v_mov_b32_e32 v0, v114
	v_pk_mul_f32 v[2:3], v[116:117], v[2:3]
	v_pk_mul_f32 v[0:1], v[0:1], v[120:121]
	v_and_b32_sdwa v115, v3, v139 dst_sel:DWORD dst_unused:UNUSED_PAD src0_sel:WORD_1 src1_sel:DWORD
	v_and_b32_sdwa v116, v2, v139 dst_sel:DWORD dst_unused:UNUSED_PAD src0_sel:WORD_1 src1_sel:DWORD
	v_pk_mul_f32 v[6:7], v[6:7], v[28:29] op_sel_hi:[1,0]
	v_pk_mul_f32 v[4:5], v[4:5], v[28:29] op_sel_hi:[1,0]
	v_pk_mul_f32 v[10:11], v[10:11], v[28:29] op_sel_hi:[1,0]
	v_pk_mul_f32 v[8:9], v[8:9], v[28:29] op_sel_hi:[1,0]
	v_pk_mul_f32 v[14:15], v[14:15], v[28:29] op_sel_hi:[1,0]
	v_pk_mul_f32 v[12:13], v[12:13], v[28:29] op_sel_hi:[1,0]
	v_pk_mul_f32 v[20:21], v[20:21], v[28:29] op_sel_hi:[1,0]
	v_pk_mul_f32 v[124:125], v[124:125], v[28:29] op_sel_hi:[1,0]
	v_pk_mul_f32 v[26:27], v[26:27], v[28:29] op_sel_hi:[1,0]
	v_pk_mul_f32 v[128:129], v[128:129], v[28:29] op_sel_hi:[1,0]
	v_pk_mul_f32 v[44:45], v[44:45], v[28:29] op_sel_hi:[1,0]
	v_pk_mul_f32 v[130:131], v[130:131], v[28:29] op_sel_hi:[1,0]
	v_pk_mul_f32 v[48:49], v[48:49], v[28:29] op_sel_hi:[1,0]
	v_pk_mul_f32 v[142:143], v[144:145], v[28:29] op_sel_hi:[1,0]
	v_pk_mul_f32 v[52:53], v[52:53], v[28:29] op_sel_hi:[1,0]
	v_and_b32_sdwa v29, v1, v139 dst_sel:DWORD dst_unused:UNUSED_PAD src0_sel:WORD_1 src1_sel:DWORD
	v_and_b32_sdwa v114, v0, v139 dst_sel:DWORD dst_unused:UNUSED_PAD src0_sel:WORD_1 src1_sel:DWORD
	v_add3_u32 v3, v3, v115, s29
	v_add3_u32 v2, v2, v116, s29
	v_add3_u32 v0, v0, v114, s29
	v_add3_u32 v1, v1, v29, s29
	v_and_b32_e32 v3, 0xffff0000, v3
	v_and_b32_e32 v2, 0xffff0000, v2
	v_or_b32_sdwa v1, v3, v1 dst_sel:DWORD dst_unused:UNUSED_PAD src0_sel:DWORD src1_sel:WORD_1
	v_or_b32_sdwa v0, v2, v0 dst_sel:DWORD dst_unused:UNUSED_PAD src0_sel:DWORD src1_sel:WORD_1
	global_store_dwordx2 v[112:113], v[0:1], off offset:-4096
	global_load_dwordx4 v[0:3], v[80:81], off offset:1024
	s_waitcnt vmcnt(0)
	v_mov_b32_e32 v115, v2
	v_mov_b32_e32 v2, v1
	v_mov_b32_e32 v114, v0
	v_pk_mul_f32 v[2:3], v[2:3], v[6:7]
	v_pk_mul_f32 v[0:1], v[114:115], v[140:141]
	v_and_b32_sdwa v29, v3, v139 dst_sel:DWORD dst_unused:UNUSED_PAD src0_sel:WORD_1 src1_sel:DWORD
	v_and_b32_sdwa v114, v2, v139 dst_sel:DWORD dst_unused:UNUSED_PAD src0_sel:WORD_1 src1_sel:DWORD
	v_and_b32_sdwa v6, v1, v139 dst_sel:DWORD dst_unused:UNUSED_PAD src0_sel:WORD_1 src1_sel:DWORD
	v_and_b32_sdwa v7, v0, v139 dst_sel:DWORD dst_unused:UNUSED_PAD src0_sel:WORD_1 src1_sel:DWORD
	v_add3_u32 v3, v3, v29, s29
	v_add3_u32 v2, v2, v114, s29
	v_add3_u32 v0, v0, v7, s29
	v_add3_u32 v1, v1, v6, s29
	v_and_b32_e32 v3, 0xffff0000, v3
	v_and_b32_e32 v2, 0xffff0000, v2
	v_or_b32_sdwa v1, v3, v1 dst_sel:DWORD dst_unused:UNUSED_PAD src0_sel:DWORD src1_sel:WORD_1
	v_or_b32_sdwa v0, v2, v0 dst_sel:DWORD dst_unused:UNUSED_PAD src0_sel:DWORD src1_sel:WORD_1
	global_store_dwordx2 v[118:119], v[0:1], off offset:512
	global_load_dwordx4 v[0:3], v[80:81], off offset:2048
	s_waitcnt vmcnt(0)
	v_mov_b32_e32 v7, v2
	v_mov_b32_e32 v2, v1
	v_mov_b32_e32 v6, v0
	v_pk_mul_f32 v[2:3], v[2:3], v[10:11]
	v_pk_mul_f32 v[0:1], v[6:7], v[4:5]
	v_and_b32_sdwa v6, v3, v139 dst_sel:DWORD dst_unused:UNUSED_PAD src0_sel:WORD_1 src1_sel:DWORD
	v_and_b32_sdwa v7, v2, v139 dst_sel:DWORD dst_unused:UNUSED_PAD src0_sel:WORD_1 src1_sel:DWORD
	v_and_b32_sdwa v4, v1, v139 dst_sel:DWORD dst_unused:UNUSED_PAD src0_sel:WORD_1 src1_sel:DWORD
	v_and_b32_sdwa v5, v0, v139 dst_sel:DWORD dst_unused:UNUSED_PAD src0_sel:WORD_1 src1_sel:DWORD
	v_add3_u32 v3, v3, v6, s29
	v_add3_u32 v2, v2, v7, s29
	v_add3_u32 v0, v0, v5, s29
	v_add3_u32 v1, v1, v4, s29
	v_and_b32_e32 v3, 0xffff0000, v3
	v_and_b32_e32 v2, 0xffff0000, v2
	v_or_b32_sdwa v1, v3, v1 dst_sel:DWORD dst_unused:UNUSED_PAD src0_sel:DWORD src1_sel:WORD_1
	v_or_b32_sdwa v0, v2, v0 dst_sel:DWORD dst_unused:UNUSED_PAD src0_sel:DWORD src1_sel:WORD_1
	global_store_dwordx2 v[118:119], v[0:1], off offset:1024
	global_load_dwordx4 v[0:3], v[80:81], off offset:3072
	s_waitcnt vmcnt(0)
	v_mov_b32_e32 v5, v2
	v_mov_b32_e32 v2, v1
	v_mov_b32_e32 v4, v0
	v_pk_mul_f32 v[2:3], v[2:3], v[14:15]
	v_pk_mul_f32 v[0:1], v[4:5], v[8:9]
	v_and_b32_sdwa v6, v3, v139 dst_sel:DWORD dst_unused:UNUSED_PAD src0_sel:WORD_1 src1_sel:DWORD
	v_and_b32_sdwa v7, v2, v139 dst_sel:DWORD dst_unused:UNUSED_PAD src0_sel:WORD_1 src1_sel:DWORD
	v_and_b32_sdwa v4, v1, v139 dst_sel:DWORD dst_unused:UNUSED_PAD src0_sel:WORD_1 src1_sel:DWORD
	v_and_b32_sdwa v5, v0, v139 dst_sel:DWORD dst_unused:UNUSED_PAD src0_sel:WORD_1 src1_sel:DWORD
	v_add3_u32 v3, v3, v6, s29
	v_add3_u32 v2, v2, v7, s29
	v_add3_u32 v0, v0, v5, s29
	v_add3_u32 v1, v1, v4, s29
	v_and_b32_e32 v3, 0xffff0000, v3
	v_and_b32_e32 v2, 0xffff0000, v2
	v_or_b32_sdwa v1, v3, v1 dst_sel:DWORD dst_unused:UNUSED_PAD src0_sel:DWORD src1_sel:WORD_1
	v_or_b32_sdwa v0, v2, v0 dst_sel:DWORD dst_unused:UNUSED_PAD src0_sel:DWORD src1_sel:WORD_1
	global_store_dwordx2 v[118:119], v[0:1], off offset:1536
	global_load_dwordx4 v[0:3], v[82:83], off
	s_waitcnt vmcnt(0)
	v_mov_b32_e32 v5, v2
	v_mov_b32_e32 v2, v1
	v_mov_b32_e32 v4, v0
	v_pk_mul_f32 v[2:3], v[2:3], v[20:21]
	v_pk_mul_f32 v[0:1], v[4:5], v[12:13]
	v_and_b32_sdwa v6, v3, v139 dst_sel:DWORD dst_unused:UNUSED_PAD src0_sel:WORD_1 src1_sel:DWORD
	v_and_b32_sdwa v7, v2, v139 dst_sel:DWORD dst_unused:UNUSED_PAD src0_sel:WORD_1 src1_sel:DWORD
	v_and_b32_sdwa v4, v1, v139 dst_sel:DWORD dst_unused:UNUSED_PAD src0_sel:WORD_1 src1_sel:DWORD
	v_and_b32_sdwa v5, v0, v139 dst_sel:DWORD dst_unused:UNUSED_PAD src0_sel:WORD_1 src1_sel:DWORD
	v_add3_u32 v3, v3, v6, s29
	v_add3_u32 v2, v2, v7, s29
	v_add3_u32 v0, v0, v5, s29
	v_add3_u32 v1, v1, v4, s29
	v_and_b32_e32 v3, 0xffff0000, v3
	v_and_b32_e32 v2, 0xffff0000, v2
	v_or_b32_sdwa v1, v3, v1 dst_sel:DWORD dst_unused:UNUSED_PAD src0_sel:DWORD src1_sel:WORD_1
	v_or_b32_sdwa v0, v2, v0 dst_sel:DWORD dst_unused:UNUSED_PAD src0_sel:DWORD src1_sel:WORD_1
	global_store_dwordx2 v[118:119], v[0:1], off offset:2048
	global_load_dwordx4 v[0:3], v[84:85], off
	s_waitcnt vmcnt(0)
	v_mov_b32_e32 v5, v2
	v_mov_b32_e32 v2, v1
	v_mov_b32_e32 v4, v0
	v_pk_mul_f32 v[2:3], v[2:3], v[26:27]
	v_pk_mul_f32 v[0:1], v[4:5], v[124:125]
	v_and_b32_sdwa v6, v3, v139 dst_sel:DWORD dst_unused:UNUSED_PAD src0_sel:WORD_1 src1_sel:DWORD
	v_and_b32_sdwa v7, v2, v139 dst_sel:DWORD dst_unused:UNUSED_PAD src0_sel:WORD_1 src1_sel:DWORD
	v_and_b32_sdwa v4, v1, v139 dst_sel:DWORD dst_unused:UNUSED_PAD src0_sel:WORD_1 src1_sel:DWORD
	v_and_b32_sdwa v5, v0, v139 dst_sel:DWORD dst_unused:UNUSED_PAD src0_sel:WORD_1 src1_sel:DWORD
	v_add3_u32 v3, v3, v6, s29
	v_add3_u32 v2, v2, v7, s29
	v_add3_u32 v0, v0, v5, s29
	v_add3_u32 v1, v1, v4, s29
	v_and_b32_e32 v3, 0xffff0000, v3
	v_and_b32_e32 v2, 0xffff0000, v2
	v_or_b32_sdwa v1, v3, v1 dst_sel:DWORD dst_unused:UNUSED_PAD src0_sel:DWORD src1_sel:WORD_1
	v_or_b32_sdwa v0, v2, v0 dst_sel:DWORD dst_unused:UNUSED_PAD src0_sel:DWORD src1_sel:WORD_1
	global_store_dwordx2 v[118:119], v[0:1], off offset:2560
	global_load_dwordx4 v[0:3], v[86:87], off
	s_waitcnt vmcnt(0)
	v_mov_b32_e32 v5, v2
	v_mov_b32_e32 v2, v1
	v_mov_b32_e32 v4, v0
	v_pk_mul_f32 v[2:3], v[44:45], v[2:3]
	v_pk_mul_f32 v[0:1], v[128:129], v[4:5]
	v_and_b32_sdwa v6, v3, v139 dst_sel:DWORD dst_unused:UNUSED_PAD src0_sel:WORD_1 src1_sel:DWORD
	v_and_b32_sdwa v7, v2, v139 dst_sel:DWORD dst_unused:UNUSED_PAD src0_sel:WORD_1 src1_sel:DWORD
	v_and_b32_sdwa v4, v1, v139 dst_sel:DWORD dst_unused:UNUSED_PAD src0_sel:WORD_1 src1_sel:DWORD
	v_and_b32_sdwa v5, v0, v139 dst_sel:DWORD dst_unused:UNUSED_PAD src0_sel:WORD_1 src1_sel:DWORD
	v_add3_u32 v3, v3, v6, s29
	v_add3_u32 v2, v2, v7, s29
	v_add3_u32 v0, v0, v5, s29
	v_add3_u32 v1, v1, v4, s29
	v_and_b32_e32 v3, 0xffff0000, v3
	v_and_b32_e32 v2, 0xffff0000, v2
	v_or_b32_sdwa v1, v3, v1 dst_sel:DWORD dst_unused:UNUSED_PAD src0_sel:DWORD src1_sel:WORD_1
	v_or_b32_sdwa v0, v2, v0 dst_sel:DWORD dst_unused:UNUSED_PAD src0_sel:DWORD src1_sel:WORD_1
	global_store_dwordx2 v[118:119], v[0:1], off offset:3072
	global_load_dwordx4 v[0:3], v[88:89], off
	s_waitcnt vmcnt(0)
	v_mov_b32_e32 v5, v2
	v_mov_b32_e32 v2, v1
	v_mov_b32_e32 v4, v0
	v_pk_mul_f32 v[2:3], v[48:49], v[2:3]
	v_pk_mul_f32 v[0:1], v[130:131], v[4:5]
	v_and_b32_sdwa v6, v3, v139 dst_sel:DWORD dst_unused:UNUSED_PAD src0_sel:WORD_1 src1_sel:DWORD
	v_and_b32_sdwa v7, v2, v139 dst_sel:DWORD dst_unused:UNUSED_PAD src0_sel:WORD_1 src1_sel:DWORD
	v_and_b32_sdwa v4, v1, v139 dst_sel:DWORD dst_unused:UNUSED_PAD src0_sel:WORD_1 src1_sel:DWORD
	v_and_b32_sdwa v5, v0, v139 dst_sel:DWORD dst_unused:UNUSED_PAD src0_sel:WORD_1 src1_sel:DWORD
	v_add3_u32 v3, v3, v6, s29
	v_add3_u32 v2, v2, v7, s29
	v_add3_u32 v0, v0, v5, s29
	v_add3_u32 v1, v1, v4, s29
	v_and_b32_e32 v3, 0xffff0000, v3
	v_and_b32_e32 v2, 0xffff0000, v2
	v_or_b32_sdwa v1, v3, v1 dst_sel:DWORD dst_unused:UNUSED_PAD src0_sel:DWORD src1_sel:WORD_1
	v_or_b32_sdwa v0, v2, v0 dst_sel:DWORD dst_unused:UNUSED_PAD src0_sel:DWORD src1_sel:WORD_1
	global_store_dwordx2 v[118:119], v[0:1], off offset:3584
	global_load_dwordx4 v[0:3], v[90:91], off
	s_waitcnt vmcnt(0)
	v_mov_b32_e32 v5, v2
	v_mov_b32_e32 v2, v1
	v_mov_b32_e32 v4, v0
	v_pk_mul_f32 v[2:3], v[52:53], v[2:3]
	v_pk_mul_f32 v[0:1], v[142:143], v[4:5]
	v_and_b32_sdwa v6, v3, v139 dst_sel:DWORD dst_unused:UNUSED_PAD src0_sel:WORD_1 src1_sel:DWORD
	v_and_b32_sdwa v7, v2, v139 dst_sel:DWORD dst_unused:UNUSED_PAD src0_sel:WORD_1 src1_sel:DWORD
	v_and_b32_sdwa v4, v1, v139 dst_sel:DWORD dst_unused:UNUSED_PAD src0_sel:WORD_1 src1_sel:DWORD
	v_and_b32_sdwa v5, v0, v139 dst_sel:DWORD dst_unused:UNUSED_PAD src0_sel:WORD_1 src1_sel:DWORD
	v_add3_u32 v3, v3, v6, s29
	v_add3_u32 v2, v2, v7, s29
	v_add3_u32 v0, v0, v5, s29
	v_add3_u32 v1, v1, v4, s29
	v_and_b32_e32 v3, 0xffff0000, v3
	v_and_b32_e32 v2, 0xffff0000, v2
	v_or_b32_sdwa v1, v3, v1 dst_sel:DWORD dst_unused:UNUSED_PAD src0_sel:DWORD src1_sel:WORD_1
	v_or_b32_sdwa v0, v2, v0 dst_sel:DWORD dst_unused:UNUSED_PAD src0_sel:DWORD src1_sel:WORD_1
	global_store_dwordx2 v[112:113], v[0:1], off
	global_load_dwordx4 v[0:3], v[92:93], off
	v_pk_mul_f32 v[6:7], v[36:37], v[28:29] op_sel_hi:[1,0]
	v_pk_mul_f32 v[4:5], v[50:51], v[28:29] op_sel_hi:[1,0]
	s_waitcnt vmcnt(0)
	v_mov_b32_e32 v9, v2
	v_mov_b32_e32 v2, v1
	v_mov_b32_e32 v8, v0
	v_pk_mul_f32 v[2:3], v[6:7], v[2:3]
	v_pk_mul_f32 v[0:1], v[4:5], v[8:9]
	v_and_b32_sdwa v6, v3, v139 dst_sel:DWORD dst_unused:UNUSED_PAD src0_sel:WORD_1 src1_sel:DWORD
	v_and_b32_sdwa v7, v2, v139 dst_sel:DWORD dst_unused:UNUSED_PAD src0_sel:WORD_1 src1_sel:DWORD
	v_and_b32_sdwa v4, v1, v139 dst_sel:DWORD dst_unused:UNUSED_PAD src0_sel:WORD_1 src1_sel:DWORD
	v_and_b32_sdwa v5, v0, v139 dst_sel:DWORD dst_unused:UNUSED_PAD src0_sel:WORD_1 src1_sel:DWORD
	v_add3_u32 v3, v3, v6, s29
	v_add3_u32 v2, v2, v7, s29
	v_add3_u32 v0, v0, v5, s29
	v_add3_u32 v1, v1, v4, s29
	v_and_b32_e32 v3, 0xffff0000, v3
	v_and_b32_e32 v2, 0xffff0000, v2
	v_or_b32_sdwa v1, v3, v1 dst_sel:DWORD dst_unused:UNUSED_PAD src0_sel:DWORD src1_sel:WORD_1
	v_or_b32_sdwa v0, v2, v0 dst_sel:DWORD dst_unused:UNUSED_PAD src0_sel:DWORD src1_sel:WORD_1
	global_store_dwordx2 v[112:113], v[0:1], off offset:512
	global_load_dwordx4 v[0:3], v[94:95], off
	v_pk_mul_f32 v[6:7], v[42:43], v[28:29] op_sel_hi:[1,0]
	v_pk_mul_f32 v[4:5], v[126:127], v[28:29] op_sel_hi:[1,0]
	s_waitcnt vmcnt(0)
	v_mov_b32_e32 v9, v2
	v_mov_b32_e32 v2, v1
	v_mov_b32_e32 v8, v0
	v_pk_mul_f32 v[2:3], v[6:7], v[2:3]
	v_pk_mul_f32 v[0:1], v[4:5], v[8:9]
	v_and_b32_sdwa v6, v3, v139 dst_sel:DWORD dst_unused:UNUSED_PAD src0_sel:WORD_1 src1_sel:DWORD
	v_and_b32_sdwa v7, v2, v139 dst_sel:DWORD dst_unused:UNUSED_PAD src0_sel:WORD_1 src1_sel:DWORD
	v_and_b32_sdwa v4, v1, v139 dst_sel:DWORD dst_unused:UNUSED_PAD src0_sel:WORD_1 src1_sel:DWORD
	v_and_b32_sdwa v5, v0, v139 dst_sel:DWORD dst_unused:UNUSED_PAD src0_sel:WORD_1 src1_sel:DWORD
	v_add3_u32 v3, v3, v6, s29
	v_add3_u32 v2, v2, v7, s29
	v_add3_u32 v0, v0, v5, s29
	v_add3_u32 v1, v1, v4, s29
	v_and_b32_e32 v3, 0xffff0000, v3
	v_and_b32_e32 v2, 0xffff0000, v2
	v_or_b32_sdwa v1, v3, v1 dst_sel:DWORD dst_unused:UNUSED_PAD src0_sel:DWORD src1_sel:WORD_1
	v_or_b32_sdwa v0, v2, v0 dst_sel:DWORD dst_unused:UNUSED_PAD src0_sel:DWORD src1_sel:WORD_1
	global_store_dwordx2 v[112:113], v[0:1], off offset:1024
	global_load_dwordx4 v[0:3], v[96:97], off
	v_mov_b32_e32 v5, v40
	v_mov_b32_e32 v40, v39
	v_mov_b32_e32 v4, v38
	v_pk_mul_f32 v[6:7], v[40:41], v[28:29] op_sel_hi:[1,0]
	v_pk_mul_f32 v[4:5], v[4:5], v[28:29] op_sel_hi:[1,0]
	s_waitcnt vmcnt(0)
	v_mov_b32_e32 v9, v2
	v_mov_b32_e32 v2, v1
	v_mov_b32_e32 v8, v0
	v_pk_mul_f32 v[2:3], v[6:7], v[2:3]
	v_pk_mul_f32 v[0:1], v[4:5], v[8:9]
	v_and_b32_sdwa v6, v3, v139 dst_sel:DWORD dst_unused:UNUSED_PAD src0_sel:WORD_1 src1_sel:DWORD
	v_and_b32_sdwa v7, v2, v139 dst_sel:DWORD dst_unused:UNUSED_PAD src0_sel:WORD_1 src1_sel:DWORD
	v_and_b32_sdwa v4, v1, v139 dst_sel:DWORD dst_unused:UNUSED_PAD src0_sel:WORD_1 src1_sel:DWORD
	v_and_b32_sdwa v5, v0, v139 dst_sel:DWORD dst_unused:UNUSED_PAD src0_sel:WORD_1 src1_sel:DWORD
	v_add3_u32 v3, v3, v6, s29
	v_add3_u32 v2, v2, v7, s29
	v_add3_u32 v0, v0, v5, s29
	v_add3_u32 v1, v1, v4, s29
	v_and_b32_e32 v3, 0xffff0000, v3
	v_and_b32_e32 v2, 0xffff0000, v2
	v_or_b32_sdwa v1, v3, v1 dst_sel:DWORD dst_unused:UNUSED_PAD src0_sel:DWORD src1_sel:WORD_1
	v_or_b32_sdwa v0, v2, v0 dst_sel:DWORD dst_unused:UNUSED_PAD src0_sel:DWORD src1_sel:WORD_1
	global_store_dwordx2 v[112:113], v[0:1], off offset:1536
	global_load_dwordx4 v[0:3], v[98:99], off
	v_mov_b32_e32 v5, v34
	v_mov_b32_e32 v34, v33
	v_mov_b32_e32 v4, v32
	v_pk_mul_f32 v[6:7], v[34:35], v[28:29] op_sel_hi:[1,0]
	v_pk_mul_f32 v[4:5], v[4:5], v[28:29] op_sel_hi:[1,0]
	s_waitcnt vmcnt(0)
	v_mov_b32_e32 v9, v2
	v_mov_b32_e32 v2, v1
	v_mov_b32_e32 v8, v0
	v_pk_mul_f32 v[2:3], v[6:7], v[2:3]
	v_pk_mul_f32 v[0:1], v[4:5], v[8:9]
	v_and_b32_sdwa v6, v3, v139 dst_sel:DWORD dst_unused:UNUSED_PAD src0_sel:WORD_1 src1_sel:DWORD
	v_and_b32_sdwa v7, v2, v139 dst_sel:DWORD dst_unused:UNUSED_PAD src0_sel:WORD_1 src1_sel:DWORD
	v_and_b32_sdwa v4, v1, v139 dst_sel:DWORD dst_unused:UNUSED_PAD src0_sel:WORD_1 src1_sel:DWORD
	v_and_b32_sdwa v5, v0, v139 dst_sel:DWORD dst_unused:UNUSED_PAD src0_sel:WORD_1 src1_sel:DWORD
	v_add3_u32 v3, v3, v6, s29
	v_add3_u32 v2, v2, v7, s29
	v_add3_u32 v0, v0, v5, s29
	v_add3_u32 v1, v1, v4, s29
	v_and_b32_e32 v3, 0xffff0000, v3
	v_and_b32_e32 v2, 0xffff0000, v2
	v_or_b32_sdwa v1, v3, v1 dst_sel:DWORD dst_unused:UNUSED_PAD src0_sel:DWORD src1_sel:WORD_1
	v_or_b32_sdwa v0, v2, v0 dst_sel:DWORD dst_unused:UNUSED_PAD src0_sel:DWORD src1_sel:WORD_1
	global_store_dwordx2 v[112:113], v[0:1], off offset:2048
	global_load_dwordx4 v[0:3], v[100:101], off
	v_pk_mul_f32 v[6:7], v[30:31], v[28:29] op_sel_hi:[1,0]
	v_pk_mul_f32 v[4:5], v[46:47], v[28:29] op_sel_hi:[1,0]
	s_waitcnt vmcnt(0)
	v_mov_b32_e32 v9, v2
	v_mov_b32_e32 v2, v1
	v_mov_b32_e32 v8, v0
	v_pk_mul_f32 v[2:3], v[6:7], v[2:3]
	v_pk_mul_f32 v[0:1], v[4:5], v[8:9]
	v_and_b32_sdwa v6, v3, v139 dst_sel:DWORD dst_unused:UNUSED_PAD src0_sel:WORD_1 src1_sel:DWORD
	v_and_b32_sdwa v7, v2, v139 dst_sel:DWORD dst_unused:UNUSED_PAD src0_sel:WORD_1 src1_sel:DWORD
	v_and_b32_sdwa v4, v1, v139 dst_sel:DWORD dst_unused:UNUSED_PAD src0_sel:WORD_1 src1_sel:DWORD
	v_and_b32_sdwa v5, v0, v139 dst_sel:DWORD dst_unused:UNUSED_PAD src0_sel:WORD_1 src1_sel:DWORD
	v_add3_u32 v3, v3, v6, s29
	v_add3_u32 v2, v2, v7, s29
	v_add3_u32 v0, v0, v5, s29
	v_add3_u32 v1, v1, v4, s29
	v_and_b32_e32 v3, 0xffff0000, v3
	v_and_b32_e32 v2, 0xffff0000, v2
	v_or_b32_sdwa v1, v3, v1 dst_sel:DWORD dst_unused:UNUSED_PAD src0_sel:DWORD src1_sel:WORD_1
	v_or_b32_sdwa v0, v2, v0 dst_sel:DWORD dst_unused:UNUSED_PAD src0_sel:DWORD src1_sel:WORD_1
	global_store_dwordx2 v[112:113], v[0:1], off offset:2560
	global_load_dwordx4 v[0:3], v[102:103], off
	v_mov_b32_e32 v5, v24
	v_mov_b32_e32 v24, v23
	v_mov_b32_e32 v4, v22
	v_pk_mul_f32 v[6:7], v[24:25], v[28:29] op_sel_hi:[1,0]
	v_pk_mul_f32 v[4:5], v[4:5], v[28:29] op_sel_hi:[1,0]
	s_waitcnt vmcnt(0)
	v_mov_b32_e32 v9, v2
	v_mov_b32_e32 v2, v1
	v_mov_b32_e32 v8, v0
	v_pk_mul_f32 v[2:3], v[6:7], v[2:3]
	v_pk_mul_f32 v[0:1], v[4:5], v[8:9]
	v_and_b32_sdwa v6, v3, v139 dst_sel:DWORD dst_unused:UNUSED_PAD src0_sel:WORD_1 src1_sel:DWORD
	v_and_b32_sdwa v7, v2, v139 dst_sel:DWORD dst_unused:UNUSED_PAD src0_sel:WORD_1 src1_sel:DWORD
	v_and_b32_sdwa v4, v1, v139 dst_sel:DWORD dst_unused:UNUSED_PAD src0_sel:WORD_1 src1_sel:DWORD
	v_and_b32_sdwa v5, v0, v139 dst_sel:DWORD dst_unused:UNUSED_PAD src0_sel:WORD_1 src1_sel:DWORD
	v_add3_u32 v3, v3, v6, s29
	v_add3_u32 v2, v2, v7, s29
	v_add3_u32 v0, v0, v5, s29
	v_add3_u32 v1, v1, v4, s29
	v_and_b32_e32 v3, 0xffff0000, v3
	v_and_b32_e32 v2, 0xffff0000, v2
	v_or_b32_sdwa v1, v3, v1 dst_sel:DWORD dst_unused:UNUSED_PAD src0_sel:DWORD src1_sel:WORD_1
	v_or_b32_sdwa v0, v2, v0 dst_sel:DWORD dst_unused:UNUSED_PAD src0_sel:DWORD src1_sel:WORD_1
	global_store_dwordx2 v[112:113], v[0:1], off offset:3072
	global_load_dwordx4 v[0:3], v[104:105], off
	v_mov_b32_e32 v5, v18
	v_mov_b32_e32 v18, v17
	v_mov_b32_e32 v4, v16
	v_pk_mul_f32 v[6:7], v[18:19], v[28:29] op_sel_hi:[1,0]
	v_pk_mul_f32 v[4:5], v[4:5], v[28:29] op_sel_hi:[1,0]
	s_waitcnt vmcnt(0)
	v_mov_b32_e32 v9, v2
	v_mov_b32_e32 v2, v1
	v_mov_b32_e32 v8, v0
	v_pk_mul_f32 v[2:3], v[6:7], v[2:3]
	v_pk_mul_f32 v[0:1], v[4:5], v[8:9]
	v_and_b32_sdwa v6, v3, v139 dst_sel:DWORD dst_unused:UNUSED_PAD src0_sel:WORD_1 src1_sel:DWORD
	v_and_b32_sdwa v7, v2, v139 dst_sel:DWORD dst_unused:UNUSED_PAD src0_sel:WORD_1 src1_sel:DWORD
	v_and_b32_sdwa v4, v1, v139 dst_sel:DWORD dst_unused:UNUSED_PAD src0_sel:WORD_1 src1_sel:DWORD
	v_and_b32_sdwa v5, v0, v139 dst_sel:DWORD dst_unused:UNUSED_PAD src0_sel:WORD_1 src1_sel:DWORD
	v_add3_u32 v3, v3, v6, s29
	v_add3_u32 v2, v2, v7, s29
	v_add3_u32 v0, v0, v5, s29
	v_add3_u32 v1, v1, v4, s29
	v_and_b32_e32 v3, 0xffff0000, v3
	v_and_b32_e32 v2, 0xffff0000, v2
	v_or_b32_sdwa v1, v3, v1 dst_sel:DWORD dst_unused:UNUSED_PAD src0_sel:DWORD src1_sel:WORD_1
	v_or_b32_sdwa v0, v2, v0 dst_sel:DWORD dst_unused:UNUSED_PAD src0_sel:DWORD src1_sel:WORD_1
	global_store_dwordx2 v[112:113], v[0:1], off offset:3584
	s_cbranch_scc0 .LBB0_2076

.LBB0_3749:
	v_lshl_add_u64 v[4:5], s[6:7], 0, v[112:113]
	global_load_dword v10, v[4:5], off
	v_lshl_add_u64 v[8:9], s[6:7], 0, v[114:115]
	v_add_co_u32_e32 v30, vcc, s17, v8
	v_lshl_add_u64 v[14:15], s[6:7], 0, v[116:117]
	s_nop 0
	v_addc_co_u32_e32 v31, vcc, 0, v9, vcc
	v_add_co_u32_e32 v16, vcc, s26, v8
	v_lshl_add_u64 v[12:13], s[4:5], 0, v[116:117]
	s_nop 0
	v_addc_co_u32_e32 v17, vcc, 0, v9, vcc
	v_add_co_u32_e32 v18, vcc, s24, v14
	global_load_dwordx4 v[0:3], v[54:55], off
	s_nop 0
	v_addc_co_u32_e32 v19, vcc, 0, v15, vcc
	v_add_co_u32_e32 v28, vcc, s25, v14
	s_add_i32 s14, s14, s16
	s_nop 0
	v_addc_co_u32_e32 v29, vcc, 0, v15, vcc
	v_add_co_u32_e32 v34, vcc, s21, v12
	v_lshl_add_u64 v[112:113], v[112:113], 0, s[8:9]
	s_nop 0
	v_addc_co_u32_e32 v35, vcc, 0, v13, vcc
	v_add_co_u32_e32 v22, vcc, s22, v12
	v_lshl_add_u64 v[114:115], v[114:115], 0, s[10:11]
	s_nop 0
	v_addc_co_u32_e32 v23, vcc, 0, v13, vcc
	v_add_co_u32_e32 v32, vcc, s27, v14
	v_lshl_add_u64 v[116:117], v[116:117], 0, s[18:19]
	s_nop 0
	v_addc_co_u32_e32 v33, vcc, 0, v15, vcc
	v_add_co_u32_e32 v120, vcc, s28, v14
	s_cmpk_gt_i32 s14, 0x3fff
	s_nop 0
	v_addc_co_u32_e32 v121, vcc, 0, v15, vcc
	v_add_co_u32_e32 v122, vcc, s23, v12
	s_nop 1
	v_addc_co_u32_e32 v123, vcc, 0, v13, vcc
	v_add_co_u32_e32 v124, vcc, s30, v8
	s_nop 1
	v_addc_co_u32_e32 v125, vcc, 0, v9, vcc
	v_add_co_u32_e32 v118, vcc, s31, v8
	s_nop 1
	v_addc_co_u32_e32 v119, vcc, 0, v9, vcc
	global_load_dwordx2 v[8:9], v[16:17], off offset:-4096
	global_load_dwordx4 v[4:7], v[12:13], off
	s_waitcnt vmcnt(3)
	ds_bpermute_b32 v11, v129, v10
	s_waitcnt lgkmcnt(0)
	v_add_f32_e32 v10, v10, v11
	ds_bpermute_b32 v11, v138, v10
	s_waitcnt lgkmcnt(0)
	v_add_f32_e32 v10, v10, v11
	ds_bpermute_b32 v11, v139, v10
	s_waitcnt lgkmcnt(0)
	v_add_f32_e32 v10, v10, v11
	ds_bpermute_b32 v11, v140, v10
	s_waitcnt lgkmcnt(0)
	v_add_f32_e32 v10, v10, v11
	ds_bpermute_b32 v11, v141, v10
	s_waitcnt lgkmcnt(0)
	v_add_f32_e32 v10, v10, v11
	ds_bpermute_b32 v11, v142, v10
	s_waitcnt lgkmcnt(0)
	v_add_f32_e32 v10, v10, v11
	v_fmamk_f32 v10, v10, 0x39800000, v143
	v_mul_f32_e32 v11, 0x4f800000, v10
	v_cmp_gt_f32_e32 vcc, s15, v10
	s_waitcnt vmcnt(1)
	v_lshlrev_b32_e32 v14, 16, v8
	v_cndmask_b32_e32 v10, v10, v11, vcc
	v_sqrt_f32_e32 v11, v10
	v_and_b32_e32 v15, 0xffff0000, v8
	v_lshlrev_b32_e32 v8, 16, v9
	v_and_b32_e32 v9, 0xffff0000, v9
	v_add_u32_e32 v20, -1, v11
	v_add_u32_e32 v21, 1, v11
	v_fma_f32 v24, -v20, v11, v10
	v_fma_f32 v25, -v21, v11, v10
	v_cmp_ge_f32_e64 s[2:3], 0, v24
	s_nop 1
	v_cndmask_b32_e64 v11, v11, v20, s[2:3]
	v_cmp_lt_f32_e64 s[2:3], 0, v25
	s_nop 1
	v_cndmask_b32_e64 v11, v11, v21, s[2:3]
	v_mul_f32_e32 v20, 0x37800000, v11
	v_cndmask_b32_e32 v11, v11, v20, vcc
	v_cmp_class_f32_e32 vcc, v10, v144
	s_nop 1
	v_cndmask_b32_e32 v10, v11, v10, vcc
	v_div_scale_f32 v11, s[2:3], v10, v10, 1.0
	v_rcp_f32_e32 v21, v11
	v_div_scale_f32 v20, vcc, 1.0, v10, 1.0
	v_fma_f32 v24, -v11, v21, 1.0
	v_fmac_f32_e32 v21, v24, v21
	v_mul_f32_e32 v24, v20, v21
	v_fma_f32 v25, -v11, v24, v20
	v_fmac_f32_e32 v24, v25, v21
	v_fma_f32 v11, -v11, v24, v20
	v_div_fmas_f32 v11, v11, v21, v24
	v_div_fixup_f32 v128, v11, v10, 1.0
	v_pk_mul_f32 v[10:11], v[128:129], v[14:15] op_sel_hi:[0,1]
	v_pk_mul_f32 v[8:9], v[128:129], v[8:9] op_sel_hi:[0,1]
	s_waitcnt vmcnt(0)
	v_pk_fma_f32 v[0:1], v[0:1], v[10:11], v[4:5]
	v_pk_fma_f32 v[2:3], v[2:3], v[8:9], v[6:7]
	global_store_dwordx4 v[28:29], v[0:3], off offset:-4096 nt
	v_mov_b32_e32 v126, v0
	v_mov_b32_e32 v127, v2
	v_mov_b32_e32 v2, v1
	global_load_dwordx2 v[0:1], v[30:31], off offset:512
	global_load_dwordx4 v[4:7], v[12:13], off offset:1024
	global_load_dwordx4 v[8:11], v[56:57], off
	v_pk_mul_f32 v[14:15], v[2:3], v[2:3]
	s_nop 0
	v_pk_fma_f32 v[14:15], v[126:127], v[126:127], v[14:15]
	s_nop 0
	v_pk_add_f32 v[40:41], v[14:15], v[14:15] op_sel:[0,1] op_sel_hi:[1,0]
	s_waitcnt vmcnt(2)
	v_lshlrev_b32_e32 v14, 16, v0
	v_and_b32_e32 v15, 0xffff0000, v0
	v_lshlrev_b32_e32 v0, 16, v1
	v_and_b32_e32 v1, 0xffff0000, v1
	v_pk_mul_f32 v[14:15], v[128:129], v[14:15] op_sel_hi:[0,1]
	v_pk_mul_f32 v[0:1], v[128:129], v[0:1] op_sel_hi:[0,1]
	s_waitcnt vmcnt(0)
	v_pk_fma_f32 v[4:5], v[8:9], v[14:15], v[4:5]
	v_pk_fma_f32 v[6:7], v[10:11], v[0:1], v[6:7]
	global_store_dwordx4 v[18:19], v[4:7], off offset:1024 nt
	v_mov_b32_e32 v0, v4
	v_mov_b32_e32 v1, v6
	v_mov_b32_e32 v6, v5
	global_load_dwordx2 v[4:5], v[30:31], off offset:1024
	global_load_dwordx4 v[8:11], v[12:13], off offset:2048
	global_load_dwordx4 v[24:27], v[58:59], off
	v_pk_mul_f32 v[14:15], v[6:7], v[6:7]
	s_nop 0
	v_pk_fma_f32 v[14:15], v[0:1], v[0:1], v[14:15]
	s_nop 0
	v_pk_add_f32 v[42:43], v[14:15], v[14:15] op_sel:[0,1] op_sel_hi:[1,0]
	s_waitcnt vmcnt(2)
	v_lshlrev_b32_e32 v14, 16, v4
	v_and_b32_e32 v15, 0xffff0000, v4
	v_lshlrev_b32_e32 v4, 16, v5
	v_and_b32_e32 v5, 0xffff0000, v5
	v_pk_mul_f32 v[14:15], v[128:129], v[14:15] op_sel_hi:[0,1]
	v_pk_mul_f32 v[4:5], v[128:129], v[4:5] op_sel_hi:[0,1]
	s_waitcnt vmcnt(0)
	v_pk_fma_f32 v[8:9], v[24:25], v[14:15], v[8:9]
	v_pk_fma_f32 v[10:11], v[26:27], v[4:5], v[10:11]
	global_store_dwordx4 v[18:19], v[8:11], off offset:2048 nt
	global_load_dwordx2 v[44:45], v[30:31], off offset:1536
	global_load_dwordx4 v[24:27], v[12:13], off offset:3072
	global_load_dwordx4 v[36:39], v[60:61], off
	v_mul_f32_e32 v14, v9, v9
	v_mul_f32_e32 v20, v11, v11
	v_mov_b32_e32 v4, v8
	v_mov_b32_e32 v5, v10
	v_pk_fma_f32 v[46:47], v[8:9], v[8:9], v[14:15] op_sel_hi:[1,1,0]
	v_pk_fma_f32 v[48:49], v[10:11], v[10:11], v[20:21] op_sel_hi:[1,1,0]
	v_mov_b32_e32 v10, v9
	s_waitcnt vmcnt(2)
	v_lshlrev_b32_e32 v8, 16, v44
	v_and_b32_e32 v9, 0xffff0000, v44
	v_lshlrev_b32_e32 v12, 16, v45
	v_and_b32_e32 v13, 0xffff0000, v45
	v_pk_mul_f32 v[8:9], v[128:129], v[8:9] op_sel_hi:[0,1]
	v_pk_mul_f32 v[14:15], v[128:129], v[12:13] op_sel_hi:[0,1]
	s_waitcnt vmcnt(0)
	v_pk_fma_f32 v[12:13], v[36:37], v[8:9], v[24:25]
	v_pk_fma_f32 v[14:15], v[38:39], v[14:15], v[26:27]
	global_store_dwordx4 v[18:19], v[12:15], off offset:3072 nt
	v_pk_mul_f32 v[36:37], v[12:13], v[12:13]
	v_pk_mul_f32 v[38:39], v[14:15], v[14:15]
	v_mov_b32_e32 v8, v12
	v_mov_b32_e32 v9, v14
	v_mov_b32_e32 v14, v13
	global_load_dwordx2 v[12:13], v[30:31], off offset:2048
	global_load_dwordx4 v[18:21], v[22:23], off offset:-4096
	global_load_dwordx4 v[24:27], v[62:63], off
	v_mov_b32_e32 v41, v36
	v_mov_b32_e32 v43, v37
	v_mov_b32_e32 v47, v38
	v_mov_b32_e32 v49, v39
	v_pk_add_f32 v[36:37], v[40:41], v[42:43]
	v_pk_add_f32 v[38:39], v[46:47], v[48:49]
	s_nop 0
	v_pk_add_f32 v[36:37], v[36:37], v[38:39]
	s_nop 0
	v_pk_add_f32 v[46:47], v[36:37], v[36:37] op_sel:[0,1] op_sel_hi:[1,0]
	s_waitcnt vmcnt(2)
	v_lshlrev_b32_e32 v36, 16, v12
	v_and_b32_e32 v37, 0xffff0000, v12
	v_lshlrev_b32_e32 v12, 16, v13
	v_and_b32_e32 v13, 0xffff0000, v13
	v_pk_mul_f32 v[36:37], v[128:129], v[36:37] op_sel_hi:[0,1]
	v_pk_mul_f32 v[12:13], v[128:129], v[12:13] op_sel_hi:[0,1]
	s_waitcnt vmcnt(0)
	v_pk_fma_f32 v[18:19], v[24:25], v[36:37], v[18:19]
	v_pk_fma_f32 v[20:21], v[26:27], v[12:13], v[20:21]
	global_store_dwordx4 v[28:29], v[18:21], off nt
	v_mov_b32_e32 v12, v18
	v_mov_b32_e32 v13, v20
	v_mov_b32_e32 v20, v19
	global_load_dwordx2 v[18:19], v[30:31], off offset:2560
	global_load_dwordx4 v[24:27], v[34:35], off offset:1024
	global_load_dwordx4 v[36:39], v[64:65], off
	v_pk_mul_f32 v[40:41], v[20:21], v[20:21]
	s_nop 0
	v_pk_fma_f32 v[40:41], v[12:13], v[12:13], v[40:41]
	s_nop 0
	v_pk_add_f32 v[48:49], v[40:41], v[40:41] op_sel:[0,1] op_sel_hi:[1,0]
	s_waitcnt vmcnt(2)
	v_lshlrev_b32_e32 v40, 16, v18
	v_and_b32_e32 v41, 0xffff0000, v18
	v_lshlrev_b32_e32 v18, 16, v19
	v_and_b32_e32 v19, 0xffff0000, v19
	v_pk_mul_f32 v[40:41], v[128:129], v[40:41] op_sel_hi:[0,1]
	v_pk_mul_f32 v[18:19], v[128:129], v[18:19] op_sel_hi:[0,1]
	s_waitcnt vmcnt(0)
	v_pk_fma_f32 v[24:25], v[36:37], v[40:41], v[24:25]
	v_pk_fma_f32 v[26:27], v[38:39], v[18:19], v[26:27]
	global_store_dwordx4 v[28:29], v[24:27], off offset:1024 nt
	global_load_dwordx2 v[50:51], v[30:31], off offset:3072
	global_load_dwordx4 v[36:39], v[34:35], off offset:2048
	global_load_dwordx4 v[42:45], v[66:67], off
	v_mul_f32_e32 v18, v25, v25
	v_mul_f32_e32 v40, v27, v27
	v_mov_b32_e32 v130, v24
	v_mov_b32_e32 v131, v26
	v_pk_fma_f32 v[18:19], v[24:25], v[24:25], v[18:19] op_sel_hi:[1,1,0]
	v_pk_fma_f32 v[52:53], v[26:27], v[26:27], v[40:41] op_sel_hi:[1,1,0]
	v_mov_b32_e32 v26, v25
	s_waitcnt vmcnt(2)
	v_lshlrev_b32_e32 v24, 16, v50
	v_and_b32_e32 v25, 0xffff0000, v50
	v_lshlrev_b32_e32 v40, 16, v51
	v_and_b32_e32 v41, 0xffff0000, v51
	v_pk_mul_f32 v[24:25], v[128:129], v[24:25] op_sel_hi:[0,1]
	v_pk_mul_f32 v[40:41], v[128:129], v[40:41] op_sel_hi:[0,1]
	s_waitcnt vmcnt(0)
	v_pk_fma_f32 v[42:43], v[42:43], v[24:25], v[36:37]
	v_pk_fma_f32 v[44:45], v[44:45], v[40:41], v[38:39]
	global_store_dwordx4 v[28:29], v[42:45], off offset:2048 nt
	global_load_dwordx2 v[30:31], v[30:31], off offset:3584
	s_nop 0
	global_load_dwordx4 v[34:37], v[34:35], off offset:3072
	s_nop 0
	global_load_dwordx4 v[38:41], v[68:69], off
	v_pk_mul_f32 v[24:25], v[42:43], v[42:43]
	v_pk_mul_f32 v[50:51], v[44:45], v[44:45]
	v_mov_b32_e32 v47, v24
	v_mov_b32_e32 v49, v25
	v_mov_b32_e32 v19, v50
	v_mov_b32_e32 v53, v51
	v_pk_add_f32 v[24:25], v[46:47], v[48:49]
	v_pk_add_f32 v[18:19], v[18:19], v[52:53]
	v_mov_b32_e32 v134, v42
	v_pk_add_f32 v[18:19], v[24:25], v[18:19]
	v_mov_b32_e32 v135, v44
	v_mov_b32_e32 v44, v43
	v_pk_add_f32 v[18:19], v[18:19], v[18:19] op_sel:[0,1] op_sel_hi:[1,0]
	s_waitcnt vmcnt(2)
	v_lshlrev_b32_e32 v24, 16, v30
	v_and_b32_e32 v25, 0xffff0000, v30
	v_lshlrev_b32_e32 v30, 16, v31
	v_and_b32_e32 v31, 0xffff0000, v31
	v_pk_mul_f32 v[24:25], v[128:129], v[24:25] op_sel_hi:[0,1]
	v_pk_mul_f32 v[30:31], v[128:129], v[30:31] op_sel_hi:[0,1]
	s_waitcnt vmcnt(0)
	v_pk_fma_f32 v[46:47], v[38:39], v[24:25], v[34:35]
	v_pk_fma_f32 v[48:49], v[40:41], v[30:31], v[36:37]
	global_store_dwordx4 v[28:29], v[46:49], off offset:3072 nt
	global_load_dwordx2 v[24:25], v[16:17], off
	s_nop 0
	global_load_dwordx4 v[28:31], v[22:23], off
	global_load_dwordx4 v[34:37], v[70:71], off
	v_mov_b32_e32 v136, v46
	v_mov_b32_e32 v137, v48
	v_mov_b32_e32 v48, v47
	v_pk_mul_f32 v[38:39], v[48:49], v[48:49]
	s_waitcnt vmcnt(2)
	v_lshlrev_b32_e32 v40, 16, v24
	v_and_b32_e32 v41, 0xffff0000, v24
	v_lshlrev_b32_e32 v24, 16, v25
	v_and_b32_e32 v25, 0xffff0000, v25
	v_pk_mul_f32 v[40:41], v[128:129], v[40:41] op_sel_hi:[0,1]
	v_pk_mul_f32 v[24:25], v[128:129], v[24:25] op_sel_hi:[0,1]
	s_waitcnt vmcnt(0)
	v_pk_fma_f32 v[50:51], v[34:35], v[40:41], v[28:29]
	v_pk_fma_f32 v[52:53], v[36:37], v[24:25], v[30:31]
	global_store_dwordx4 v[120:121], v[50:53], off offset:-4096 nt
	global_load_dwordx2 v[42:43], v[16:17], off offset:512
	global_load_dwordx4 v[28:31], v[22:23], off offset:1024
	global_load_dwordx4 v[34:37], v[72:73], off
	v_mul_f32_e32 v40, v53, v53
	v_pk_fma_f32 v[46:47], v[52:53], v[52:53], v[40:41] op_sel_hi:[1,1,0]
	v_mul_f32_e32 v24, v51, v51
	v_mov_b32_e32 v150, v50
	v_mov_b32_e32 v151, v52
	v_pk_fma_f32 v[24:25], v[50:51], v[50:51], v[24:25] op_sel_hi:[1,1,0]
	v_mov_b32_e32 v52, v51
	v_pk_fma_f32 v[38:39], v[136:137], v[136:137], v[38:39]
	s_waitcnt vmcnt(2)
	v_lshlrev_b32_e32 v40, 16, v42
	v_and_b32_e32 v41, 0xffff0000, v42
	v_lshlrev_b32_e32 v42, 16, v43
	v_and_b32_e32 v43, 0xffff0000, v43
	v_pk_mul_f32 v[40:41], v[128:129], v[40:41] op_sel_hi:[0,1]
	v_pk_mul_f32 v[42:43], v[128:129], v[42:43] op_sel_hi:[0,1]
	s_waitcnt vmcnt(0)
	v_pk_fma_f32 v[34:35], v[34:35], v[40:41], v[28:29]
	v_pk_fma_f32 v[36:37], v[36:37], v[42:43], v[30:31]
	global_store_dwordx4 v[32:33], v[34:37], off offset:1024 nt
	v_pk_mul_f32 v[132:133], v[34:35], v[34:35]
	v_pk_mul_f32 v[146:147], v[36:37], v[36:37]
	v_mov_b32_e32 v50, v34
	v_mov_b32_e32 v51, v36
	v_mov_b32_e32 v36, v35
	global_load_dwordx2 v[34:35], v[16:17], off offset:1024
	global_load_dwordx4 v[28:31], v[22:23], off offset:2048
	global_load_dwordx4 v[40:43], v[74:75], off
	v_pk_add_f32 v[38:39], v[38:39], v[38:39] op_sel:[0,1] op_sel_hi:[1,0]
	v_mov_b32_e32 v19, v132
	v_mov_b32_e32 v39, v133
	v_mov_b32_e32 v25, v146
	v_mov_b32_e32 v47, v147
	v_pk_add_f32 v[18:19], v[18:19], v[38:39]
	v_pk_add_f32 v[24:25], v[24:25], v[46:47]
	s_nop 0
	v_pk_add_f32 v[18:19], v[18:19], v[24:25]
	s_waitcnt vmcnt(2)
	v_lshlrev_b32_e32 v24, 16, v34
	v_and_b32_e32 v25, 0xffff0000, v34
	v_lshlrev_b32_e32 v34, 16, v35
	v_and_b32_e32 v35, 0xffff0000, v35
	v_pk_mul_f32 v[24:25], v[128:129], v[24:25] op_sel_hi:[0,1]
	v_pk_mul_f32 v[34:35], v[128:129], v[34:35] op_sel_hi:[0,1]
	s_waitcnt vmcnt(0)
	v_pk_fma_f32 v[40:41], v[40:41], v[24:25], v[28:29]
	v_pk_fma_f32 v[42:43], v[42:43], v[34:35], v[30:31]
	global_store_dwordx4 v[32:33], v[40:43], off offset:2048 nt
	global_load_dwordx2 v[34:35], v[16:17], off offset:1536
	s_nop 0
	global_load_dwordx4 v[22:25], v[22:23], off offset:3072
	s_nop 0
	global_load_dwordx4 v[28:31], v[76:77], off
	v_mov_b32_e32 v133, v42
	v_mov_b32_e32 v42, v41
	v_mov_b32_e32 v132, v40
	v_pk_mul_f32 v[38:39], v[42:43], v[42:43]
	v_pk_add_f32 v[18:19], v[18:19], v[18:19] op_sel:[0,1] op_sel_hi:[1,0]
	v_pk_fma_f32 v[38:39], v[132:133], v[132:133], v[38:39]
	s_nop 0
	v_pk_add_f32 v[46:47], v[38:39], v[38:39] op_sel:[0,1] op_sel_hi:[1,0]
	s_waitcnt vmcnt(2)
	v_lshlrev_b32_e32 v38, 16, v34
	v_and_b32_e32 v39, 0xffff0000, v34
	v_lshlrev_b32_e32 v34, 16, v35
	v_and_b32_e32 v35, 0xffff0000, v35
	v_pk_mul_f32 v[38:39], v[128:129], v[38:39] op_sel_hi:[0,1]
	v_pk_mul_f32 v[34:35], v[128:129], v[34:35] op_sel_hi:[0,1]
	s_waitcnt vmcnt(0)
	v_pk_fma_f32 v[38:39], v[28:29], v[38:39], v[22:23]
	v_pk_fma_f32 v[40:41], v[30:31], v[34:35], v[24:25]
	global_store_dwordx4 v[32:33], v[38:41], off offset:3072 nt
	global_load_dwordx2 v[146:147], v[16:17], off offset:2048
	global_load_dwordx4 v[22:25], v[122:123], off
	global_load_dwordx4 v[28:31], v[78:79], off
	v_mul_f32_e32 v32, v39, v39
	v_mul_f32_e32 v34, v41, v41
	v_pk_fma_f32 v[148:149], v[38:39], v[38:39], v[32:33] op_sel_hi:[1,1,0]
	v_pk_fma_f32 v[152:153], v[40:41], v[40:41], v[34:35] op_sel_hi:[1,1,0]
	s_waitcnt vmcnt(2)
	v_lshlrev_b32_e32 v32, 16, v146
	v_and_b32_e32 v33, 0xffff0000, v146
	v_lshlrev_b32_e32 v34, 16, v147
	v_and_b32_e32 v35, 0xffff0000, v147
	v_pk_mul_f32 v[32:33], v[128:129], v[32:33] op_sel_hi:[0,1]
	v_pk_mul_f32 v[34:35], v[128:129], v[34:35] op_sel_hi:[0,1]
	s_waitcnt vmcnt(0)
	v_pk_fma_f32 v[32:33], v[28:29], v[32:33], v[22:23]
	v_pk_fma_f32 v[34:35], v[30:31], v[34:35], v[24:25]
	global_store_dwordx4 v[120:121], v[32:35], off nt
	global_load_dwordx2 v[156:157], v[16:17], off offset:2560
	global_load_dwordx4 v[22:25], v[122:123], off offset:1024
	global_load_dwordx4 v[28:31], v[80:81], off
	v_pk_mul_f32 v[146:147], v[32:33], v[32:33]
	v_pk_mul_f32 v[154:155], v[34:35], v[34:35]
	v_mov_b32_e32 v19, v146
	v_mov_b32_e32 v47, v147
	v_mov_b32_e32 v149, v154
	v_mov_b32_e32 v153, v155
	v_pk_add_f32 v[18:19], v[18:19], v[46:47]
	v_pk_add_f32 v[46:47], v[148:149], v[152:153]
	s_nop 0
	v_pk_add_f32 v[18:19], v[18:19], v[46:47]
	s_waitcnt vmcnt(2)
	v_lshlrev_b32_e32 v46, 16, v157
	v_pk_add_f32 v[152:153], v[18:19], v[18:19] op_sel:[0,1] op_sel_hi:[1,0]
	v_lshlrev_b32_e32 v18, 16, v156
	v_and_b32_e32 v19, 0xffff0000, v156
	v_and_b32_e32 v47, 0xffff0000, v157
	v_pk_mul_f32 v[18:19], v[128:129], v[18:19] op_sel_hi:[0,1]
	v_pk_mul_f32 v[46:47], v[128:129], v[46:47] op_sel_hi:[0,1]
	s_waitcnt vmcnt(0)
	v_pk_fma_f32 v[28:29], v[28:29], v[18:19], v[22:23]
	v_pk_fma_f32 v[30:31], v[30:31], v[46:47], v[24:25]
	global_store_dwordx4 v[120:121], v[28:31], off offset:1024 nt
	global_load_dwordx2 v[18:19], v[16:17], off offset:3072
	global_load_dwordx4 v[22:25], v[122:123], off offset:2048
	global_load_dwordx4 v[146:149], v[82:83], off
	v_mov_b32_e32 v47, v30
	v_mov_b32_e32 v30, v29
	v_mov_b32_e32 v46, v28
	v_pk_mul_f32 v[28:29], v[30:31], v[30:31]
	s_waitcnt vmcnt(2)
	v_lshlrev_b32_e32 v154, 16, v18
	v_and_b32_e32 v155, 0xffff0000, v18
	v_lshlrev_b32_e32 v18, 16, v19
	v_and_b32_e32 v19, 0xffff0000, v19
	v_pk_mul_f32 v[154:155], v[128:129], v[154:155] op_sel_hi:[0,1]
	v_pk_mul_f32 v[18:19], v[128:129], v[18:19] op_sel_hi:[0,1]
	s_waitcnt vmcnt(0)
	v_pk_fma_f32 v[22:23], v[146:147], v[154:155], v[22:23]
	v_pk_fma_f32 v[24:25], v[148:149], v[18:19], v[24:25]
	global_store_dwordx4 v[120:121], v[22:25], off offset:2048 nt
	global_load_dwordx2 v[158:159], v[16:17], off offset:3584
	s_nop 0
	global_load_dwordx4 v[16:19], v[122:123], off offset:3072
	global_load_dwordx4 v[146:149], v[84:85], off
	v_pk_fma_f32 v[28:29], v[46:47], v[46:47], v[28:29]
	v_mul_f32_e32 v154, v23, v23
	v_mul_f32_e32 v156, v25, v25
	v_pk_add_f32 v[28:29], v[28:29], v[28:29] op_sel:[0,1] op_sel_hi:[1,0]
	v_pk_fma_f32 v[154:155], v[22:23], v[22:23], v[154:155] op_sel_hi:[1,1,0]
	v_pk_fma_f32 v[156:157], v[24:25], v[24:25], v[156:157] op_sel_hi:[1,1,0]
	s_waitcnt vmcnt(2)
	v_lshlrev_b32_e32 v122, 16, v158
	v_and_b32_e32 v123, 0xffff0000, v158
	v_lshlrev_b32_e32 v158, 16, v159
	v_and_b32_e32 v159, 0xffff0000, v159
	v_pk_mul_f32 v[122:123], v[128:129], v[122:123] op_sel_hi:[0,1]
	v_pk_mul_f32 v[158:159], v[128:129], v[158:159] op_sel_hi:[0,1]
	s_waitcnt vmcnt(0)
	v_pk_fma_f32 v[16:17], v[146:147], v[122:123], v[16:17]
	v_pk_fma_f32 v[18:19], v[148:149], v[158:159], v[18:19]
	global_store_dwordx4 v[120:121], v[16:19], off offset:3072 nt
	v_pk_mul_f32 v[120:121], v[16:17], v[16:17]
	v_pk_mul_f32 v[122:123], v[18:19], v[18:19]
	v_mov_b32_e32 v153, v120
	v_mov_b32_e32 v29, v121
	v_mov_b32_e32 v155, v122
	v_mov_b32_e32 v157, v123
	global_load_dwordx4 v[120:123], v[86:87], off
	v_pk_add_f32 v[28:29], v[152:153], v[28:29]
	v_pk_add_f32 v[146:147], v[154:155], v[156:157]
	s_nop 0
	v_pk_add_f32 v[28:29], v[28:29], v[146:147]
	s_nop 0
	v_add_f32_e32 v28, v28, v29
	ds_bpermute_b32 v29, v129, v28
	s_waitcnt lgkmcnt(0)
	v_add_f32_e32 v28, v28, v29
	ds_bpermute_b32 v29, v138, v28
	s_waitcnt lgkmcnt(0)
	v_add_f32_e32 v28, v28, v29
	ds_bpermute_b32 v29, v139, v28
	s_waitcnt lgkmcnt(0)
	v_add_f32_e32 v28, v28, v29
	ds_bpermute_b32 v29, v140, v28
	s_waitcnt lgkmcnt(0)
	v_add_f32_e32 v28, v28, v29
	ds_bpermute_b32 v29, v141, v28
	s_waitcnt lgkmcnt(0)
	v_add_f32_e32 v28, v28, v29
	ds_bpermute_b32 v29, v142, v28
	s_waitcnt lgkmcnt(0)
	v_add_f32_e32 v28, v28, v29
	v_fmamk_f32 v28, v28, 0x39800000, v143
	v_mul_f32_e32 v29, 0x4f800000, v28
	v_cmp_gt_f32_e32 vcc, s15, v28
	s_nop 1
	v_cndmask_b32_e32 v28, v28, v29, vcc
	v_sqrt_f32_e32 v29, v28
	s_nop 0
	v_add_u32_e32 v128, -1, v29
	v_add_u32_e32 v146, 1, v29
	v_fma_f32 v147, -v128, v29, v28
	v_fma_f32 v148, -v146, v29, v28
	v_cmp_ge_f32_e64 s[2:3], 0, v147
	s_nop 1
	v_cndmask_b32_e64 v29, v29, v128, s[2:3]
	v_cmp_lt_f32_e64 s[2:3], 0, v148
	s_nop 1
	v_cndmask_b32_e64 v29, v29, v146, s[2:3]
	v_mul_f32_e32 v128, 0x37800000, v29
	v_cndmask_b32_e32 v29, v29, v128, vcc
	v_cmp_class_f32_e32 vcc, v28, v144
	s_nop 1
	v_cndmask_b32_e32 v28, v29, v28, vcc
	v_div_scale_f32 v29, s[2:3], v28, v28, 1.0
	v_rcp_f32_e32 v146, v29
	v_div_scale_f32 v128, vcc, 1.0, v28, 1.0
	v_fma_f32 v147, -v29, v146, 1.0
	v_fmac_f32_e32 v146, v147, v146
	v_mul_f32_e32 v147, v128, v146
	v_fma_f32 v148, -v29, v147, v128
	v_fmac_f32_e32 v147, v148, v146
	v_fma_f32 v29, -v29, v147, v128
	v_div_fmas_f32 v29, v29, v146, v147
	v_div_fixup_f32 v28, v29, v28, 1.0
	v_pk_mul_f32 v[2:3], v[2:3], v[28:29] op_sel_hi:[1,0]
	v_pk_mul_f32 v[146:147], v[0:1], v[28:29] op_sel_hi:[1,0]
	s_waitcnt vmcnt(0)
	v_mov_b32_e32 v1, v122
	v_mov_b32_e32 v122, v121
	v_pk_mul_f32 v[126:127], v[126:127], v[28:29] op_sel_hi:[1,0]
	v_mov_b32_e32 v0, v120
	v_pk_mul_f32 v[2:3], v[122:123], v[2:3]
	v_pk_mul_f32 v[0:1], v[0:1], v[126:127]
	v_and_b32_sdwa v121, v3, v145 dst_sel:DWORD dst_unused:UNUSED_PAD src0_sel:WORD_1 src1_sel:DWORD
	v_and_b32_sdwa v122, v2, v145 dst_sel:DWORD dst_unused:UNUSED_PAD src0_sel:WORD_1 src1_sel:DWORD
	v_pk_mul_f32 v[6:7], v[6:7], v[28:29] op_sel_hi:[1,0]
	v_pk_mul_f32 v[4:5], v[4:5], v[28:29] op_sel_hi:[1,0]
	v_pk_mul_f32 v[10:11], v[10:11], v[28:29] op_sel_hi:[1,0]
	v_pk_mul_f32 v[8:9], v[8:9], v[28:29] op_sel_hi:[1,0]
	v_pk_mul_f32 v[14:15], v[14:15], v[28:29] op_sel_hi:[1,0]
	v_pk_mul_f32 v[12:13], v[12:13], v[28:29] op_sel_hi:[1,0]
	v_pk_mul_f32 v[20:21], v[20:21], v[28:29] op_sel_hi:[1,0]
	v_pk_mul_f32 v[130:131], v[130:131], v[28:29] op_sel_hi:[1,0]
	v_pk_mul_f32 v[26:27], v[26:27], v[28:29] op_sel_hi:[1,0]
	v_pk_mul_f32 v[134:135], v[134:135], v[28:29] op_sel_hi:[1,0]
	v_pk_mul_f32 v[44:45], v[44:45], v[28:29] op_sel_hi:[1,0]
	v_pk_mul_f32 v[136:137], v[136:137], v[28:29] op_sel_hi:[1,0]
	v_pk_mul_f32 v[48:49], v[48:49], v[28:29] op_sel_hi:[1,0]
	v_pk_mul_f32 v[148:149], v[150:151], v[28:29] op_sel_hi:[1,0]
	v_pk_mul_f32 v[52:53], v[52:53], v[28:29] op_sel_hi:[1,0]
	v_and_b32_sdwa v29, v1, v145 dst_sel:DWORD dst_unused:UNUSED_PAD src0_sel:WORD_1 src1_sel:DWORD
	v_and_b32_sdwa v120, v0, v145 dst_sel:DWORD dst_unused:UNUSED_PAD src0_sel:WORD_1 src1_sel:DWORD
	v_add3_u32 v3, v3, v121, s29
	v_add3_u32 v2, v2, v122, s29
	v_add3_u32 v0, v0, v120, s29
	v_add3_u32 v1, v1, v29, s29
	v_and_b32_e32 v3, 0xffff0000, v3
	v_and_b32_e32 v2, 0xffff0000, v2
	v_or_b32_sdwa v1, v3, v1 dst_sel:DWORD dst_unused:UNUSED_PAD src0_sel:DWORD src1_sel:WORD_1
	v_or_b32_sdwa v0, v2, v0 dst_sel:DWORD dst_unused:UNUSED_PAD src0_sel:DWORD src1_sel:WORD_1
	global_store_dwordx2 v[118:119], v[0:1], off offset:-4096
	global_load_dwordx4 v[0:3], v[86:87], off offset:1024
	s_waitcnt vmcnt(0)
	v_mov_b32_e32 v121, v2
	v_mov_b32_e32 v2, v1
	v_mov_b32_e32 v120, v0
	v_pk_mul_f32 v[2:3], v[2:3], v[6:7]
	v_pk_mul_f32 v[0:1], v[120:121], v[146:147]
	v_and_b32_sdwa v29, v3, v145 dst_sel:DWORD dst_unused:UNUSED_PAD src0_sel:WORD_1 src1_sel:DWORD
	v_and_b32_sdwa v120, v2, v145 dst_sel:DWORD dst_unused:UNUSED_PAD src0_sel:WORD_1 src1_sel:DWORD
	v_and_b32_sdwa v6, v1, v145 dst_sel:DWORD dst_unused:UNUSED_PAD src0_sel:WORD_1 src1_sel:DWORD
	v_and_b32_sdwa v7, v0, v145 dst_sel:DWORD dst_unused:UNUSED_PAD src0_sel:WORD_1 src1_sel:DWORD
	v_add3_u32 v3, v3, v29, s29
	v_add3_u32 v2, v2, v120, s29
	v_add3_u32 v0, v0, v7, s29
	v_add3_u32 v1, v1, v6, s29
	v_and_b32_e32 v3, 0xffff0000, v3
	v_and_b32_e32 v2, 0xffff0000, v2
	v_or_b32_sdwa v1, v3, v1 dst_sel:DWORD dst_unused:UNUSED_PAD src0_sel:DWORD src1_sel:WORD_1
	v_or_b32_sdwa v0, v2, v0 dst_sel:DWORD dst_unused:UNUSED_PAD src0_sel:DWORD src1_sel:WORD_1
	global_store_dwordx2 v[124:125], v[0:1], off offset:512
	global_load_dwordx4 v[0:3], v[86:87], off offset:2048
	s_waitcnt vmcnt(0)
	v_mov_b32_e32 v7, v2
	v_mov_b32_e32 v2, v1
	v_mov_b32_e32 v6, v0
	v_pk_mul_f32 v[2:3], v[2:3], v[10:11]
	v_pk_mul_f32 v[0:1], v[6:7], v[4:5]
	v_and_b32_sdwa v6, v3, v145 dst_sel:DWORD dst_unused:UNUSED_PAD src0_sel:WORD_1 src1_sel:DWORD
	v_and_b32_sdwa v7, v2, v145 dst_sel:DWORD dst_unused:UNUSED_PAD src0_sel:WORD_1 src1_sel:DWORD
	v_and_b32_sdwa v4, v1, v145 dst_sel:DWORD dst_unused:UNUSED_PAD src0_sel:WORD_1 src1_sel:DWORD
	v_and_b32_sdwa v5, v0, v145 dst_sel:DWORD dst_unused:UNUSED_PAD src0_sel:WORD_1 src1_sel:DWORD
	v_add3_u32 v3, v3, v6, s29
	v_add3_u32 v2, v2, v7, s29
	v_add3_u32 v0, v0, v5, s29
	v_add3_u32 v1, v1, v4, s29
	v_and_b32_e32 v3, 0xffff0000, v3
	v_and_b32_e32 v2, 0xffff0000, v2
	v_or_b32_sdwa v1, v3, v1 dst_sel:DWORD dst_unused:UNUSED_PAD src0_sel:DWORD src1_sel:WORD_1
	v_or_b32_sdwa v0, v2, v0 dst_sel:DWORD dst_unused:UNUSED_PAD src0_sel:DWORD src1_sel:WORD_1
	global_store_dwordx2 v[124:125], v[0:1], off offset:1024
	global_load_dwordx4 v[0:3], v[86:87], off offset:3072
	s_waitcnt vmcnt(0)
	v_mov_b32_e32 v5, v2
	v_mov_b32_e32 v2, v1
	v_mov_b32_e32 v4, v0
	v_pk_mul_f32 v[2:3], v[2:3], v[14:15]
	v_pk_mul_f32 v[0:1], v[4:5], v[8:9]
	v_and_b32_sdwa v6, v3, v145 dst_sel:DWORD dst_unused:UNUSED_PAD src0_sel:WORD_1 src1_sel:DWORD
	v_and_b32_sdwa v7, v2, v145 dst_sel:DWORD dst_unused:UNUSED_PAD src0_sel:WORD_1 src1_sel:DWORD
	v_and_b32_sdwa v4, v1, v145 dst_sel:DWORD dst_unused:UNUSED_PAD src0_sel:WORD_1 src1_sel:DWORD
	v_and_b32_sdwa v5, v0, v145 dst_sel:DWORD dst_unused:UNUSED_PAD src0_sel:WORD_1 src1_sel:DWORD
	v_add3_u32 v3, v3, v6, s29
	v_add3_u32 v2, v2, v7, s29
	v_add3_u32 v0, v0, v5, s29
	v_add3_u32 v1, v1, v4, s29
	v_and_b32_e32 v3, 0xffff0000, v3
	v_and_b32_e32 v2, 0xffff0000, v2
	v_or_b32_sdwa v1, v3, v1 dst_sel:DWORD dst_unused:UNUSED_PAD src0_sel:DWORD src1_sel:WORD_1
	v_or_b32_sdwa v0, v2, v0 dst_sel:DWORD dst_unused:UNUSED_PAD src0_sel:DWORD src1_sel:WORD_1
	global_store_dwordx2 v[124:125], v[0:1], off offset:1536
	global_load_dwordx4 v[0:3], v[88:89], off
	s_waitcnt vmcnt(0)
	v_mov_b32_e32 v5, v2
	v_mov_b32_e32 v2, v1
	v_mov_b32_e32 v4, v0
	v_pk_mul_f32 v[2:3], v[2:3], v[20:21]
	v_pk_mul_f32 v[0:1], v[4:5], v[12:13]
	v_and_b32_sdwa v6, v3, v145 dst_sel:DWORD dst_unused:UNUSED_PAD src0_sel:WORD_1 src1_sel:DWORD
	v_and_b32_sdwa v7, v2, v145 dst_sel:DWORD dst_unused:UNUSED_PAD src0_sel:WORD_1 src1_sel:DWORD
	v_and_b32_sdwa v4, v1, v145 dst_sel:DWORD dst_unused:UNUSED_PAD src0_sel:WORD_1 src1_sel:DWORD
	v_and_b32_sdwa v5, v0, v145 dst_sel:DWORD dst_unused:UNUSED_PAD src0_sel:WORD_1 src1_sel:DWORD
	v_add3_u32 v3, v3, v6, s29
	v_add3_u32 v2, v2, v7, s29
	v_add3_u32 v0, v0, v5, s29
	v_add3_u32 v1, v1, v4, s29
	v_and_b32_e32 v3, 0xffff0000, v3
	v_and_b32_e32 v2, 0xffff0000, v2
	v_or_b32_sdwa v1, v3, v1 dst_sel:DWORD dst_unused:UNUSED_PAD src0_sel:DWORD src1_sel:WORD_1
	v_or_b32_sdwa v0, v2, v0 dst_sel:DWORD dst_unused:UNUSED_PAD src0_sel:DWORD src1_sel:WORD_1
	global_store_dwordx2 v[124:125], v[0:1], off offset:2048
	global_load_dwordx4 v[0:3], v[90:91], off
	s_waitcnt vmcnt(0)
	v_mov_b32_e32 v5, v2
	v_mov_b32_e32 v2, v1
	v_mov_b32_e32 v4, v0
	v_pk_mul_f32 v[2:3], v[2:3], v[26:27]
	v_pk_mul_f32 v[0:1], v[4:5], v[130:131]
	v_and_b32_sdwa v6, v3, v145 dst_sel:DWORD dst_unused:UNUSED_PAD src0_sel:WORD_1 src1_sel:DWORD
	v_and_b32_sdwa v7, v2, v145 dst_sel:DWORD dst_unused:UNUSED_PAD src0_sel:WORD_1 src1_sel:DWORD
	v_and_b32_sdwa v4, v1, v145 dst_sel:DWORD dst_unused:UNUSED_PAD src0_sel:WORD_1 src1_sel:DWORD
	v_and_b32_sdwa v5, v0, v145 dst_sel:DWORD dst_unused:UNUSED_PAD src0_sel:WORD_1 src1_sel:DWORD
	v_add3_u32 v3, v3, v6, s29
	v_add3_u32 v2, v2, v7, s29
	v_add3_u32 v0, v0, v5, s29
	v_add3_u32 v1, v1, v4, s29
	v_and_b32_e32 v3, 0xffff0000, v3
	v_and_b32_e32 v2, 0xffff0000, v2
	v_or_b32_sdwa v1, v3, v1 dst_sel:DWORD dst_unused:UNUSED_PAD src0_sel:DWORD src1_sel:WORD_1
	v_or_b32_sdwa v0, v2, v0 dst_sel:DWORD dst_unused:UNUSED_PAD src0_sel:DWORD src1_sel:WORD_1
	global_store_dwordx2 v[124:125], v[0:1], off offset:2560
	global_load_dwordx4 v[0:3], v[92:93], off
	s_waitcnt vmcnt(0)
	v_mov_b32_e32 v5, v2
	v_mov_b32_e32 v2, v1
	v_mov_b32_e32 v4, v0
	v_pk_mul_f32 v[2:3], v[44:45], v[2:3]
	v_pk_mul_f32 v[0:1], v[134:135], v[4:5]
	v_and_b32_sdwa v6, v3, v145 dst_sel:DWORD dst_unused:UNUSED_PAD src0_sel:WORD_1 src1_sel:DWORD
	v_and_b32_sdwa v7, v2, v145 dst_sel:DWORD dst_unused:UNUSED_PAD src0_sel:WORD_1 src1_sel:DWORD
	v_and_b32_sdwa v4, v1, v145 dst_sel:DWORD dst_unused:UNUSED_PAD src0_sel:WORD_1 src1_sel:DWORD
	v_and_b32_sdwa v5, v0, v145 dst_sel:DWORD dst_unused:UNUSED_PAD src0_sel:WORD_1 src1_sel:DWORD
	v_add3_u32 v3, v3, v6, s29
	v_add3_u32 v2, v2, v7, s29
	v_add3_u32 v0, v0, v5, s29
	v_add3_u32 v1, v1, v4, s29
	v_and_b32_e32 v3, 0xffff0000, v3
	v_and_b32_e32 v2, 0xffff0000, v2
	v_or_b32_sdwa v1, v3, v1 dst_sel:DWORD dst_unused:UNUSED_PAD src0_sel:DWORD src1_sel:WORD_1
	v_or_b32_sdwa v0, v2, v0 dst_sel:DWORD dst_unused:UNUSED_PAD src0_sel:DWORD src1_sel:WORD_1
	global_store_dwordx2 v[124:125], v[0:1], off offset:3072
	global_load_dwordx4 v[0:3], v[94:95], off
	s_waitcnt vmcnt(0)
	v_mov_b32_e32 v5, v2
	v_mov_b32_e32 v2, v1
	v_mov_b32_e32 v4, v0
	v_pk_mul_f32 v[2:3], v[48:49], v[2:3]
	v_pk_mul_f32 v[0:1], v[136:137], v[4:5]
	v_and_b32_sdwa v6, v3, v145 dst_sel:DWORD dst_unused:UNUSED_PAD src0_sel:WORD_1 src1_sel:DWORD
	v_and_b32_sdwa v7, v2, v145 dst_sel:DWORD dst_unused:UNUSED_PAD src0_sel:WORD_1 src1_sel:DWORD
	v_and_b32_sdwa v4, v1, v145 dst_sel:DWORD dst_unused:UNUSED_PAD src0_sel:WORD_1 src1_sel:DWORD
	v_and_b32_sdwa v5, v0, v145 dst_sel:DWORD dst_unused:UNUSED_PAD src0_sel:WORD_1 src1_sel:DWORD
	v_add3_u32 v3, v3, v6, s29
	v_add3_u32 v2, v2, v7, s29
	v_add3_u32 v0, v0, v5, s29
	v_add3_u32 v1, v1, v4, s29
	v_and_b32_e32 v3, 0xffff0000, v3
	v_and_b32_e32 v2, 0xffff0000, v2
	v_or_b32_sdwa v1, v3, v1 dst_sel:DWORD dst_unused:UNUSED_PAD src0_sel:DWORD src1_sel:WORD_1
	v_or_b32_sdwa v0, v2, v0 dst_sel:DWORD dst_unused:UNUSED_PAD src0_sel:DWORD src1_sel:WORD_1
	global_store_dwordx2 v[124:125], v[0:1], off offset:3584
	global_load_dwordx4 v[0:3], v[96:97], off
	s_waitcnt vmcnt(0)
	v_mov_b32_e32 v5, v2
	v_mov_b32_e32 v2, v1
	v_mov_b32_e32 v4, v0
	v_pk_mul_f32 v[2:3], v[52:53], v[2:3]
	v_pk_mul_f32 v[0:1], v[148:149], v[4:5]
	v_and_b32_sdwa v6, v3, v145 dst_sel:DWORD dst_unused:UNUSED_PAD src0_sel:WORD_1 src1_sel:DWORD
	v_and_b32_sdwa v7, v2, v145 dst_sel:DWORD dst_unused:UNUSED_PAD src0_sel:WORD_1 src1_sel:DWORD
	v_and_b32_sdwa v4, v1, v145 dst_sel:DWORD dst_unused:UNUSED_PAD src0_sel:WORD_1 src1_sel:DWORD
	v_and_b32_sdwa v5, v0, v145 dst_sel:DWORD dst_unused:UNUSED_PAD src0_sel:WORD_1 src1_sel:DWORD
	v_add3_u32 v3, v3, v6, s29
	v_add3_u32 v2, v2, v7, s29
	v_add3_u32 v0, v0, v5, s29
	v_add3_u32 v1, v1, v4, s29
	v_and_b32_e32 v3, 0xffff0000, v3
	v_and_b32_e32 v2, 0xffff0000, v2
	v_or_b32_sdwa v1, v3, v1 dst_sel:DWORD dst_unused:UNUSED_PAD src0_sel:DWORD src1_sel:WORD_1
	v_or_b32_sdwa v0, v2, v0 dst_sel:DWORD dst_unused:UNUSED_PAD src0_sel:DWORD src1_sel:WORD_1
	global_store_dwordx2 v[118:119], v[0:1], off
	global_load_dwordx4 v[0:3], v[98:99], off
	v_pk_mul_f32 v[6:7], v[36:37], v[28:29] op_sel_hi:[1,0]
	v_pk_mul_f32 v[4:5], v[50:51], v[28:29] op_sel_hi:[1,0]
	s_waitcnt vmcnt(0)
	v_mov_b32_e32 v9, v2
	v_mov_b32_e32 v2, v1
	v_mov_b32_e32 v8, v0
	v_pk_mul_f32 v[2:3], v[6:7], v[2:3]
	v_pk_mul_f32 v[0:1], v[4:5], v[8:9]
	v_and_b32_sdwa v6, v3, v145 dst_sel:DWORD dst_unused:UNUSED_PAD src0_sel:WORD_1 src1_sel:DWORD
	v_and_b32_sdwa v7, v2, v145 dst_sel:DWORD dst_unused:UNUSED_PAD src0_sel:WORD_1 src1_sel:DWORD
	v_and_b32_sdwa v4, v1, v145 dst_sel:DWORD dst_unused:UNUSED_PAD src0_sel:WORD_1 src1_sel:DWORD
	v_and_b32_sdwa v5, v0, v145 dst_sel:DWORD dst_unused:UNUSED_PAD src0_sel:WORD_1 src1_sel:DWORD
	v_add3_u32 v3, v3, v6, s29
	v_add3_u32 v2, v2, v7, s29
	v_add3_u32 v0, v0, v5, s29
	v_add3_u32 v1, v1, v4, s29
	v_and_b32_e32 v3, 0xffff0000, v3
	v_and_b32_e32 v2, 0xffff0000, v2
	v_or_b32_sdwa v1, v3, v1 dst_sel:DWORD dst_unused:UNUSED_PAD src0_sel:DWORD src1_sel:WORD_1
	v_or_b32_sdwa v0, v2, v0 dst_sel:DWORD dst_unused:UNUSED_PAD src0_sel:DWORD src1_sel:WORD_1
	global_store_dwordx2 v[118:119], v[0:1], off offset:512
	global_load_dwordx4 v[0:3], v[100:101], off
	v_pk_mul_f32 v[6:7], v[42:43], v[28:29] op_sel_hi:[1,0]
	v_pk_mul_f32 v[4:5], v[132:133], v[28:29] op_sel_hi:[1,0]
	s_waitcnt vmcnt(0)
	v_mov_b32_e32 v9, v2
	v_mov_b32_e32 v2, v1
	v_mov_b32_e32 v8, v0
	v_pk_mul_f32 v[2:3], v[6:7], v[2:3]
	v_pk_mul_f32 v[0:1], v[4:5], v[8:9]
	v_and_b32_sdwa v6, v3, v145 dst_sel:DWORD dst_unused:UNUSED_PAD src0_sel:WORD_1 src1_sel:DWORD
	v_and_b32_sdwa v7, v2, v145 dst_sel:DWORD dst_unused:UNUSED_PAD src0_sel:WORD_1 src1_sel:DWORD
	v_and_b32_sdwa v4, v1, v145 dst_sel:DWORD dst_unused:UNUSED_PAD src0_sel:WORD_1 src1_sel:DWORD
	v_and_b32_sdwa v5, v0, v145 dst_sel:DWORD dst_unused:UNUSED_PAD src0_sel:WORD_1 src1_sel:DWORD
	v_add3_u32 v3, v3, v6, s29
	v_add3_u32 v2, v2, v7, s29
	v_add3_u32 v0, v0, v5, s29
	v_add3_u32 v1, v1, v4, s29
	v_and_b32_e32 v3, 0xffff0000, v3
	v_and_b32_e32 v2, 0xffff0000, v2
	v_or_b32_sdwa v1, v3, v1 dst_sel:DWORD dst_unused:UNUSED_PAD src0_sel:DWORD src1_sel:WORD_1
	v_or_b32_sdwa v0, v2, v0 dst_sel:DWORD dst_unused:UNUSED_PAD src0_sel:DWORD src1_sel:WORD_1
	global_store_dwordx2 v[118:119], v[0:1], off offset:1024
	global_load_dwordx4 v[0:3], v[102:103], off
	v_mov_b32_e32 v5, v40
	v_mov_b32_e32 v40, v39
	v_mov_b32_e32 v4, v38
	v_pk_mul_f32 v[6:7], v[40:41], v[28:29] op_sel_hi:[1,0]
	v_pk_mul_f32 v[4:5], v[4:5], v[28:29] op_sel_hi:[1,0]
	s_waitcnt vmcnt(0)
	v_mov_b32_e32 v9, v2
	v_mov_b32_e32 v2, v1
	v_mov_b32_e32 v8, v0
	v_pk_mul_f32 v[2:3], v[6:7], v[2:3]
	v_pk_mul_f32 v[0:1], v[4:5], v[8:9]
	v_and_b32_sdwa v6, v3, v145 dst_sel:DWORD dst_unused:UNUSED_PAD src0_sel:WORD_1 src1_sel:DWORD
	v_and_b32_sdwa v7, v2, v145 dst_sel:DWORD dst_unused:UNUSED_PAD src0_sel:WORD_1 src1_sel:DWORD
	v_and_b32_sdwa v4, v1, v145 dst_sel:DWORD dst_unused:UNUSED_PAD src0_sel:WORD_1 src1_sel:DWORD
	v_and_b32_sdwa v5, v0, v145 dst_sel:DWORD dst_unused:UNUSED_PAD src0_sel:WORD_1 src1_sel:DWORD
	v_add3_u32 v3, v3, v6, s29
	v_add3_u32 v2, v2, v7, s29
	v_add3_u32 v0, v0, v5, s29
	v_add3_u32 v1, v1, v4, s29
	v_and_b32_e32 v3, 0xffff0000, v3
	v_and_b32_e32 v2, 0xffff0000, v2
	v_or_b32_sdwa v1, v3, v1 dst_sel:DWORD dst_unused:UNUSED_PAD src0_sel:DWORD src1_sel:WORD_1
	v_or_b32_sdwa v0, v2, v0 dst_sel:DWORD dst_unused:UNUSED_PAD src0_sel:DWORD src1_sel:WORD_1
	global_store_dwordx2 v[118:119], v[0:1], off offset:1536
	global_load_dwordx4 v[0:3], v[104:105], off
	v_mov_b32_e32 v5, v34
	v_mov_b32_e32 v34, v33
	v_mov_b32_e32 v4, v32
	v_pk_mul_f32 v[6:7], v[34:35], v[28:29] op_sel_hi:[1,0]
	v_pk_mul_f32 v[4:5], v[4:5], v[28:29] op_sel_hi:[1,0]
	s_waitcnt vmcnt(0)
	v_mov_b32_e32 v9, v2
	v_mov_b32_e32 v2, v1
	v_mov_b32_e32 v8, v0
	v_pk_mul_f32 v[2:3], v[6:7], v[2:3]
	v_pk_mul_f32 v[0:1], v[4:5], v[8:9]
	v_and_b32_sdwa v6, v3, v145 dst_sel:DWORD dst_unused:UNUSED_PAD src0_sel:WORD_1 src1_sel:DWORD
	v_and_b32_sdwa v7, v2, v145 dst_sel:DWORD dst_unused:UNUSED_PAD src0_sel:WORD_1 src1_sel:DWORD
	v_and_b32_sdwa v4, v1, v145 dst_sel:DWORD dst_unused:UNUSED_PAD src0_sel:WORD_1 src1_sel:DWORD
	v_and_b32_sdwa v5, v0, v145 dst_sel:DWORD dst_unused:UNUSED_PAD src0_sel:WORD_1 src1_sel:DWORD
	v_add3_u32 v3, v3, v6, s29
	v_add3_u32 v2, v2, v7, s29
	v_add3_u32 v0, v0, v5, s29
	v_add3_u32 v1, v1, v4, s29
	v_and_b32_e32 v3, 0xffff0000, v3
	v_and_b32_e32 v2, 0xffff0000, v2
	v_or_b32_sdwa v1, v3, v1 dst_sel:DWORD dst_unused:UNUSED_PAD src0_sel:DWORD src1_sel:WORD_1
	v_or_b32_sdwa v0, v2, v0 dst_sel:DWORD dst_unused:UNUSED_PAD src0_sel:DWORD src1_sel:WORD_1
	global_store_dwordx2 v[118:119], v[0:1], off offset:2048
	global_load_dwordx4 v[0:3], v[106:107], off
	v_pk_mul_f32 v[6:7], v[30:31], v[28:29] op_sel_hi:[1,0]
	v_pk_mul_f32 v[4:5], v[46:47], v[28:29] op_sel_hi:[1,0]
	s_waitcnt vmcnt(0)
	v_mov_b32_e32 v9, v2
	v_mov_b32_e32 v2, v1
	v_mov_b32_e32 v8, v0
	v_pk_mul_f32 v[2:3], v[6:7], v[2:3]
	v_pk_mul_f32 v[0:1], v[4:5], v[8:9]
	v_and_b32_sdwa v6, v3, v145 dst_sel:DWORD dst_unused:UNUSED_PAD src0_sel:WORD_1 src1_sel:DWORD
	v_and_b32_sdwa v7, v2, v145 dst_sel:DWORD dst_unused:UNUSED_PAD src0_sel:WORD_1 src1_sel:DWORD
	v_and_b32_sdwa v4, v1, v145 dst_sel:DWORD dst_unused:UNUSED_PAD src0_sel:WORD_1 src1_sel:DWORD
	v_and_b32_sdwa v5, v0, v145 dst_sel:DWORD dst_unused:UNUSED_PAD src0_sel:WORD_1 src1_sel:DWORD
	v_add3_u32 v3, v3, v6, s29
	v_add3_u32 v2, v2, v7, s29
	v_add3_u32 v0, v0, v5, s29
	v_add3_u32 v1, v1, v4, s29
	v_and_b32_e32 v3, 0xffff0000, v3
	v_and_b32_e32 v2, 0xffff0000, v2
	v_or_b32_sdwa v1, v3, v1 dst_sel:DWORD dst_unused:UNUSED_PAD src0_sel:DWORD src1_sel:WORD_1
	v_or_b32_sdwa v0, v2, v0 dst_sel:DWORD dst_unused:UNUSED_PAD src0_sel:DWORD src1_sel:WORD_1
	global_store_dwordx2 v[118:119], v[0:1], off offset:2560
	global_load_dwordx4 v[0:3], v[108:109], off
	v_mov_b32_e32 v5, v24
	v_mov_b32_e32 v24, v23
	v_mov_b32_e32 v4, v22
	v_pk_mul_f32 v[6:7], v[24:25], v[28:29] op_sel_hi:[1,0]
	v_pk_mul_f32 v[4:5], v[4:5], v[28:29] op_sel_hi:[1,0]
	s_waitcnt vmcnt(0)
	v_mov_b32_e32 v9, v2
	v_mov_b32_e32 v2, v1
	v_mov_b32_e32 v8, v0
	v_pk_mul_f32 v[2:3], v[6:7], v[2:3]
	v_pk_mul_f32 v[0:1], v[4:5], v[8:9]
	v_and_b32_sdwa v6, v3, v145 dst_sel:DWORD dst_unused:UNUSED_PAD src0_sel:WORD_1 src1_sel:DWORD
	v_and_b32_sdwa v7, v2, v145 dst_sel:DWORD dst_unused:UNUSED_PAD src0_sel:WORD_1 src1_sel:DWORD
	v_and_b32_sdwa v4, v1, v145 dst_sel:DWORD dst_unused:UNUSED_PAD src0_sel:WORD_1 src1_sel:DWORD
	v_and_b32_sdwa v5, v0, v145 dst_sel:DWORD dst_unused:UNUSED_PAD src0_sel:WORD_1 src1_sel:DWORD
	v_add3_u32 v3, v3, v6, s29
	v_add3_u32 v2, v2, v7, s29
	v_add3_u32 v0, v0, v5, s29
	v_add3_u32 v1, v1, v4, s29
	v_and_b32_e32 v3, 0xffff0000, v3
	v_and_b32_e32 v2, 0xffff0000, v2
	v_or_b32_sdwa v1, v3, v1 dst_sel:DWORD dst_unused:UNUSED_PAD src0_sel:DWORD src1_sel:WORD_1
	v_or_b32_sdwa v0, v2, v0 dst_sel:DWORD dst_unused:UNUSED_PAD src0_sel:DWORD src1_sel:WORD_1
	global_store_dwordx2 v[118:119], v[0:1], off offset:3072
	global_load_dwordx4 v[0:3], v[110:111], off
	v_mov_b32_e32 v5, v18
	v_mov_b32_e32 v18, v17
	v_mov_b32_e32 v4, v16
	v_pk_mul_f32 v[6:7], v[18:19], v[28:29] op_sel_hi:[1,0]
	v_pk_mul_f32 v[4:5], v[4:5], v[28:29] op_sel_hi:[1,0]
	s_waitcnt vmcnt(0)
	v_mov_b32_e32 v9, v2
	v_mov_b32_e32 v2, v1
	v_mov_b32_e32 v8, v0
	v_pk_mul_f32 v[2:3], v[6:7], v[2:3]
	v_pk_mul_f32 v[0:1], v[4:5], v[8:9]
	v_and_b32_sdwa v6, v3, v145 dst_sel:DWORD dst_unused:UNUSED_PAD src0_sel:WORD_1 src1_sel:DWORD
	v_and_b32_sdwa v7, v2, v145 dst_sel:DWORD dst_unused:UNUSED_PAD src0_sel:WORD_1 src1_sel:DWORD
	v_and_b32_sdwa v4, v1, v145 dst_sel:DWORD dst_unused:UNUSED_PAD src0_sel:WORD_1 src1_sel:DWORD
	v_and_b32_sdwa v5, v0, v145 dst_sel:DWORD dst_unused:UNUSED_PAD src0_sel:WORD_1 src1_sel:DWORD
	v_add3_u32 v3, v3, v6, s29
	v_add3_u32 v2, v2, v7, s29
	v_add3_u32 v0, v0, v5, s29
	v_add3_u32 v1, v1, v4, s29
	v_and_b32_e32 v3, 0xffff0000, v3
	v_and_b32_e32 v2, 0xffff0000, v2
	v_or_b32_sdwa v1, v3, v1 dst_sel:DWORD dst_unused:UNUSED_PAD src0_sel:DWORD src1_sel:WORD_1
	v_or_b32_sdwa v0, v2, v0 dst_sel:DWORD dst_unused:UNUSED_PAD src0_sel:DWORD src1_sel:WORD_1
	global_store_dwordx2 v[118:119], v[0:1], off offset:3584
	s_cbranch_scc0 .LBB0_3749

.LBB0_4009:
	v_lshl_add_u64 v[38:39], s[14:15], 0, v[36:37]
	v_add_co_u32_e32 v64, vcc, s13, v38
	v_lshl_add_u64 v[44:45], s[14:15], 0, v[34:35]
	s_nop 0
	v_addc_co_u32_e32 v65, vcc, 0, v39, vcc
	v_add_co_u32_e32 v38, vcc, s26, v38
	v_lshl_add_u64 v[62:63], s[14:15], 0, v[32:33]
	s_nop 0
	v_addc_co_u32_e32 v39, vcc, 0, v39, vcc
	v_add_co_u32_e32 v66, vcc, s24, v44
	global_load_dwordx4 v[54:57], v[0:1], off
	s_nop 0
	v_addc_co_u32_e32 v67, vcc, 0, v45, vcc
	v_add_co_u32_e32 v68, vcc, s25, v44
	v_lshl_add_u64 v[42:43], s[6:7], 0, v[34:35]
	s_nop 0
	v_addc_co_u32_e32 v69, vcc, 0, v45, vcc
	global_load_dword v40, v[62:63], off
	global_load_dwordx2 v[70:71], v[38:39], off offset:-4096
	global_load_dwordx4 v[58:61], v[68:69], off offset:-4096
	s_add_i32 s10, s10, s12
	v_lshl_add_u64 v[32:33], v[32:33], 0, s[4:5]
	v_lshl_add_u64 v[34:35], v[34:35], 0, s[16:17]
	v_lshl_add_u64 v[36:37], v[36:37], 0, s[18:19]
	s_cmpk_gt_i32 s10, 0x3fff
	s_waitcnt vmcnt(2)
	ds_bpermute_b32 v53, v41, v40
	s_waitcnt vmcnt(1)
	v_lshlrev_b32_e32 v62, 16, v70
	v_and_b32_e32 v63, 0xffff0000, v70
	v_lshlrev_b32_e32 v70, 16, v71
	v_and_b32_e32 v71, 0xffff0000, v71
	s_waitcnt lgkmcnt(0)
	v_add_f32_e32 v40, v40, v53
	ds_bpermute_b32 v53, v46, v40
	s_waitcnt lgkmcnt(0)
	v_add_f32_e32 v40, v40, v53
	ds_bpermute_b32 v53, v47, v40
	s_waitcnt lgkmcnt(0)
	v_add_f32_e32 v40, v40, v53
	ds_bpermute_b32 v53, v48, v40
	s_waitcnt lgkmcnt(0)
	v_add_f32_e32 v40, v40, v53
	ds_bpermute_b32 v53, v49, v40
	s_waitcnt lgkmcnt(0)
	v_add_f32_e32 v40, v40, v53
	ds_bpermute_b32 v53, v50, v40
	s_waitcnt lgkmcnt(0)
	v_add_f32_e32 v40, v40, v53
	v_fmamk_f32 v40, v40, 0x39800000, v51
	v_mul_f32_e32 v53, 0x4f800000, v40
	v_cmp_gt_f32_e32 vcc, s11, v40
	s_nop 1
	v_cndmask_b32_e32 v40, v40, v53, vcc
	v_sqrt_f32_e32 v53, v40
	s_nop 0
	v_add_u32_e32 v72, -1, v53
	v_add_u32_e32 v73, 1, v53
	v_fma_f32 v74, -v72, v53, v40
	v_fma_f32 v75, -v73, v53, v40
	v_cmp_ge_f32_e64 s[2:3], 0, v74
	s_nop 1
	v_cndmask_b32_e64 v53, v53, v72, s[2:3]
	v_cmp_lt_f32_e64 s[2:3], 0, v75
	s_nop 1
	v_cndmask_b32_e64 v53, v53, v73, s[2:3]
	v_mul_f32_e32 v72, 0x37800000, v53
	v_cndmask_b32_e32 v53, v53, v72, vcc
	v_cmp_class_f32_e32 vcc, v40, v52
	s_nop 1
	v_cndmask_b32_e32 v40, v53, v40, vcc
	v_div_scale_f32 v53, s[2:3], v40, v40, 1.0
	v_rcp_f32_e32 v73, v53
	v_div_scale_f32 v72, vcc, 1.0, v40, 1.0
	v_fma_f32 v74, -v53, v73, 1.0
	v_fmac_f32_e32 v73, v74, v73
	v_mul_f32_e32 v74, v72, v73
	v_fma_f32 v75, -v53, v74, v72
	v_fmac_f32_e32 v74, v75, v73
	v_fma_f32 v53, -v53, v74, v72
	v_div_fmas_f32 v53, v53, v73, v74
	v_div_fixup_f32 v40, v53, v40, 1.0
	v_pk_mul_f32 v[62:63], v[40:41], v[62:63] op_sel_hi:[0,1]
	v_pk_mul_f32 v[70:71], v[40:41], v[70:71] op_sel_hi:[0,1]
	s_waitcnt vmcnt(0)
	v_pk_fma_f32 v[54:55], v[54:55], v[62:63], v[58:59]
	v_pk_fma_f32 v[56:57], v[56:57], v[70:71], v[60:61]
	global_store_dwordx4 v[42:43], v[54:57], off nt
	global_load_dwordx2 v[62:63], v[64:65], off offset:512
	s_nop 0
	global_load_dwordx4 v[54:57], v[66:67], off offset:1024
	global_load_dwordx4 v[58:61], v[2:3], off
	s_waitcnt vmcnt(2)
	v_lshlrev_b32_e32 v70, 16, v62
	v_and_b32_e32 v71, 0xffff0000, v62
	v_lshlrev_b32_e32 v62, 16, v63
	v_and_b32_e32 v63, 0xffff0000, v63
	v_pk_mul_f32 v[70:71], v[40:41], v[70:71] op_sel_hi:[0,1]
	v_pk_mul_f32 v[62:63], v[40:41], v[62:63] op_sel_hi:[0,1]
	s_waitcnt vmcnt(0)
	v_pk_fma_f32 v[54:55], v[58:59], v[70:71], v[54:55]
	v_pk_fma_f32 v[56:57], v[60:61], v[62:63], v[56:57]
	global_store_dwordx4 v[42:43], v[54:57], off offset:1024 nt
	global_load_dwordx2 v[62:63], v[64:65], off offset:1024
	s_nop 0
	global_load_dwordx4 v[54:57], v[66:67], off offset:2048
	global_load_dwordx4 v[58:61], v[4:5], off
	s_waitcnt vmcnt(2)
	v_lshlrev_b32_e32 v70, 16, v62
	v_and_b32_e32 v71, 0xffff0000, v62
	v_lshlrev_b32_e32 v62, 16, v63
	v_and_b32_e32 v63, 0xffff0000, v63
	v_pk_mul_f32 v[70:71], v[40:41], v[70:71] op_sel_hi:[0,1]
	v_pk_mul_f32 v[62:63], v[40:41], v[62:63] op_sel_hi:[0,1]
	s_waitcnt vmcnt(0)
	v_pk_fma_f32 v[54:55], v[58:59], v[70:71], v[54:55]
	v_pk_fma_f32 v[56:57], v[60:61], v[62:63], v[56:57]
	global_store_dwordx4 v[42:43], v[54:57], off offset:2048 nt
	global_load_dwordx2 v[62:63], v[64:65], off offset:1536
	s_nop 0
	global_load_dwordx4 v[54:57], v[66:67], off offset:3072
	global_load_dwordx4 v[58:61], v[6:7], off
	s_waitcnt vmcnt(2)
	v_lshlrev_b32_e32 v66, 16, v62
	v_and_b32_e32 v67, 0xffff0000, v62
	v_lshlrev_b32_e32 v62, 16, v63
	v_and_b32_e32 v63, 0xffff0000, v63
	v_pk_mul_f32 v[66:67], v[40:41], v[66:67] op_sel_hi:[0,1]
	v_pk_mul_f32 v[62:63], v[40:41], v[62:63] op_sel_hi:[0,1]
	s_waitcnt vmcnt(0)
	v_pk_fma_f32 v[54:55], v[58:59], v[66:67], v[54:55]
	v_pk_fma_f32 v[56:57], v[60:61], v[62:63], v[56:57]
	global_store_dwordx4 v[42:43], v[54:57], off offset:3072 nt
	global_load_dwordx2 v[62:63], v[64:65], off offset:2048
	s_nop 0
	global_load_dwordx4 v[54:57], v[68:69], off
	global_load_dwordx4 v[58:61], v[8:9], off
	v_add_co_u32_e32 v66, vcc, s22, v42
	s_waitcnt vmcnt(2)
	v_lshlrev_b32_e32 v70, 16, v62
	v_and_b32_e32 v71, 0xffff0000, v62
	v_lshlrev_b32_e32 v62, 16, v63
	v_and_b32_e32 v63, 0xffff0000, v63
	v_pk_mul_f32 v[70:71], v[40:41], v[70:71] op_sel_hi:[0,1]
	v_pk_mul_f32 v[62:63], v[40:41], v[62:63] op_sel_hi:[0,1]
	v_addc_co_u32_e32 v67, vcc, 0, v43, vcc
	s_waitcnt vmcnt(0)
	v_pk_fma_f32 v[54:55], v[58:59], v[70:71], v[54:55]
	v_pk_fma_f32 v[56:57], v[60:61], v[62:63], v[56:57]
	global_store_dwordx4 v[66:67], v[54:57], off offset:-4096 nt
	global_load_dwordx2 v[62:63], v[64:65], off offset:2560
	s_nop 0
	global_load_dwordx4 v[54:57], v[68:69], off offset:1024
	global_load_dwordx4 v[58:61], v[10:11], off
	v_add_co_u32_e32 v70, vcc, s21, v42
	s_waitcnt vmcnt(2)
	v_lshlrev_b32_e32 v72, 16, v62
	v_and_b32_e32 v73, 0xffff0000, v62
	v_lshlrev_b32_e32 v62, 16, v63
	v_and_b32_e32 v63, 0xffff0000, v63
	v_pk_mul_f32 v[72:73], v[40:41], v[72:73] op_sel_hi:[0,1]
	v_pk_mul_f32 v[62:63], v[40:41], v[62:63] op_sel_hi:[0,1]
	v_addc_co_u32_e32 v71, vcc, 0, v43, vcc
	s_waitcnt vmcnt(0)
	v_pk_fma_f32 v[54:55], v[58:59], v[72:73], v[54:55]
	v_pk_fma_f32 v[56:57], v[60:61], v[62:63], v[56:57]
	global_store_dwordx4 v[70:71], v[54:57], off offset:1024 nt
	global_load_dwordx2 v[62:63], v[64:65], off offset:3072
	s_nop 0
	global_load_dwordx4 v[54:57], v[68:69], off offset:2048
	global_load_dwordx4 v[58:61], v[12:13], off
	s_waitcnt vmcnt(2)
	v_lshlrev_b32_e32 v72, 16, v62
	v_and_b32_e32 v73, 0xffff0000, v62
	v_lshlrev_b32_e32 v62, 16, v63
	v_and_b32_e32 v63, 0xffff0000, v63
	v_pk_mul_f32 v[72:73], v[40:41], v[72:73] op_sel_hi:[0,1]
	v_pk_mul_f32 v[62:63], v[40:41], v[62:63] op_sel_hi:[0,1]
	s_waitcnt vmcnt(0)
	v_pk_fma_f32 v[54:55], v[58:59], v[72:73], v[54:55]
	v_pk_fma_f32 v[56:57], v[60:61], v[62:63], v[56:57]
	global_store_dwordx4 v[70:71], v[54:57], off offset:2048 nt
	global_load_dwordx2 v[62:63], v[64:65], off offset:3584
	s_nop 0
	global_load_dwordx4 v[54:57], v[68:69], off offset:3072
	global_load_dwordx4 v[58:61], v[14:15], off
	v_add_co_u32_e32 v64, vcc, s28, v44
	s_waitcnt vmcnt(2)
	v_lshlrev_b32_e32 v68, 16, v62
	v_and_b32_e32 v69, 0xffff0000, v62
	v_lshlrev_b32_e32 v62, 16, v63
	v_and_b32_e32 v63, 0xffff0000, v63
	v_pk_mul_f32 v[68:69], v[40:41], v[68:69] op_sel_hi:[0,1]
	v_pk_mul_f32 v[62:63], v[40:41], v[62:63] op_sel_hi:[0,1]
	s_waitcnt vmcnt(0)
	v_pk_fma_f32 v[54:55], v[58:59], v[68:69], v[54:55]
	v_pk_fma_f32 v[56:57], v[60:61], v[62:63], v[56:57]
	global_store_dwordx4 v[70:71], v[54:57], off offset:3072 nt
	v_addc_co_u32_e32 v65, vcc, 0, v45, vcc
	global_load_dwordx2 v[62:63], v[38:39], off
	global_load_dwordx4 v[54:57], v[64:65], off offset:-4096
	global_load_dwordx4 v[58:61], v[16:17], off
	v_add_co_u32_e32 v44, vcc, s27, v44
	s_waitcnt vmcnt(2)
	v_lshlrev_b32_e32 v68, 16, v62
	v_and_b32_e32 v69, 0xffff0000, v62
	v_lshlrev_b32_e32 v62, 16, v63
	v_and_b32_e32 v63, 0xffff0000, v63
	v_pk_mul_f32 v[68:69], v[40:41], v[68:69] op_sel_hi:[0,1]
	v_pk_mul_f32 v[62:63], v[40:41], v[62:63] op_sel_hi:[0,1]
	s_waitcnt vmcnt(0)
	v_pk_fma_f32 v[54:55], v[58:59], v[68:69], v[54:55]
	v_pk_fma_f32 v[56:57], v[60:61], v[62:63], v[56:57]
	global_store_dwordx4 v[66:67], v[54:57], off nt
	v_addc_co_u32_e32 v45, vcc, 0, v45, vcc
	global_load_dwordx2 v[62:63], v[38:39], off offset:512
	global_load_dwordx4 v[54:57], v[44:45], off offset:1024
	global_load_dwordx4 v[58:61], v[18:19], off
	s_waitcnt vmcnt(2)
	v_lshlrev_b32_e32 v68, 16, v62
	v_and_b32_e32 v69, 0xffff0000, v62
	v_lshlrev_b32_e32 v62, 16, v63
	v_and_b32_e32 v63, 0xffff0000, v63
	v_pk_mul_f32 v[68:69], v[40:41], v[68:69] op_sel_hi:[0,1]
	v_pk_mul_f32 v[62:63], v[40:41], v[62:63] op_sel_hi:[0,1]
	s_waitcnt vmcnt(0)
	v_pk_fma_f32 v[54:55], v[58:59], v[68:69], v[54:55]
	v_pk_fma_f32 v[56:57], v[60:61], v[62:63], v[56:57]
	global_store_dwordx4 v[66:67], v[54:57], off offset:1024 nt
	global_load_dwordx2 v[62:63], v[38:39], off offset:1024
	s_nop 0
	global_load_dwordx4 v[54:57], v[44:45], off offset:2048
	global_load_dwordx4 v[58:61], v[20:21], off
	s_waitcnt vmcnt(2)
	v_lshlrev_b32_e32 v68, 16, v62
	v_and_b32_e32 v69, 0xffff0000, v62
	v_lshlrev_b32_e32 v62, 16, v63
	v_and_b32_e32 v63, 0xffff0000, v63
	v_pk_mul_f32 v[68:69], v[40:41], v[68:69] op_sel_hi:[0,1]
	v_pk_mul_f32 v[62:63], v[40:41], v[62:63] op_sel_hi:[0,1]
	s_waitcnt vmcnt(0)
	v_pk_fma_f32 v[54:55], v[58:59], v[68:69], v[54:55]
	v_pk_fma_f32 v[56:57], v[60:61], v[62:63], v[56:57]
	global_store_dwordx4 v[66:67], v[54:57], off offset:2048 nt
	global_load_dwordx2 v[62:63], v[38:39], off offset:1536
	s_nop 0
	global_load_dwordx4 v[54:57], v[44:45], off offset:3072
	global_load_dwordx4 v[58:61], v[22:23], off
	s_waitcnt vmcnt(2)
	v_lshlrev_b32_e32 v44, 16, v62
	v_and_b32_e32 v45, 0xffff0000, v62
	v_lshlrev_b32_e32 v62, 16, v63
	v_and_b32_e32 v63, 0xffff0000, v63
	v_pk_mul_f32 v[44:45], v[40:41], v[44:45] op_sel_hi:[0,1]
	v_pk_mul_f32 v[62:63], v[40:41], v[62:63] op_sel_hi:[0,1]
	s_waitcnt vmcnt(0)
	v_pk_fma_f32 v[54:55], v[58:59], v[44:45], v[54:55]
	v_pk_fma_f32 v[56:57], v[60:61], v[62:63], v[56:57]
	global_store_dwordx4 v[66:67], v[54:57], off offset:3072 nt
	global_load_dwordx2 v[44:45], v[38:39], off offset:2048
	s_nop 0
	global_load_dwordx4 v[54:57], v[64:65], off
	global_load_dwordx4 v[58:61], v[24:25], off
	v_add_co_u32_e32 v62, vcc, s23, v42
	s_waitcnt vmcnt(2)
	v_lshlrev_b32_e32 v42, 16, v44
	v_addc_co_u32_e32 v63, vcc, 0, v43, vcc
	v_and_b32_e32 v43, 0xffff0000, v44
	v_lshlrev_b32_e32 v44, 16, v45
	v_and_b32_e32 v45, 0xffff0000, v45
	v_pk_mul_f32 v[42:43], v[40:41], v[42:43] op_sel_hi:[0,1]
	v_pk_mul_f32 v[44:45], v[40:41], v[44:45] op_sel_hi:[0,1]
	s_waitcnt vmcnt(0)
	v_pk_fma_f32 v[42:43], v[58:59], v[42:43], v[54:55]
	v_pk_fma_f32 v[44:45], v[60:61], v[44:45], v[56:57]
	global_store_dwordx4 v[62:63], v[42:45], off nt
	global_load_dwordx2 v[58:59], v[38:39], off offset:2560
	s_nop 0
	global_load_dwordx4 v[42:45], v[64:65], off offset:1024
	global_load_dwordx4 v[54:57], v[26:27], off
	s_waitcnt vmcnt(2)
	v_lshlrev_b32_e32 v60, 16, v58
	v_and_b32_e32 v61, 0xffff0000, v58
	v_lshlrev_b32_e32 v58, 16, v59
	v_and_b32_e32 v59, 0xffff0000, v59
	v_pk_mul_f32 v[60:61], v[40:41], v[60:61] op_sel_hi:[0,1]
	v_pk_mul_f32 v[58:59], v[40:41], v[58:59] op_sel_hi:[0,1]
	s_waitcnt vmcnt(0)
	v_pk_fma_f32 v[42:43], v[54:55], v[60:61], v[42:43]
	v_pk_fma_f32 v[44:45], v[56:57], v[58:59], v[44:45]
	global_store_dwordx4 v[62:63], v[42:45], off offset:1024 nt
	global_load_dwordx2 v[58:59], v[38:39], off offset:3072
	s_nop 0
	global_load_dwordx4 v[42:45], v[64:65], off offset:2048
	global_load_dwordx4 v[54:57], v[28:29], off
	s_waitcnt vmcnt(2)
	v_lshlrev_b32_e32 v60, 16, v58
	v_and_b32_e32 v61, 0xffff0000, v58
	v_lshlrev_b32_e32 v58, 16, v59
	v_and_b32_e32 v59, 0xffff0000, v59
	v_pk_mul_f32 v[60:61], v[40:41], v[60:61] op_sel_hi:[0,1]
	v_pk_mul_f32 v[58:59], v[40:41], v[58:59] op_sel_hi:[0,1]
	s_waitcnt vmcnt(0)
	v_pk_fma_f32 v[42:43], v[54:55], v[60:61], v[42:43]
	v_pk_fma_f32 v[44:45], v[56:57], v[58:59], v[44:45]
	global_store_dwordx4 v[62:63], v[42:45], off offset:2048 nt
	global_load_dwordx2 v[58:59], v[38:39], off offset:3584
	s_nop 0
	global_load_dwordx4 v[42:45], v[64:65], off offset:3072
	global_load_dwordx4 v[54:57], v[30:31], off
	s_waitcnt vmcnt(2)
	v_lshlrev_b32_e32 v38, 16, v58
	v_and_b32_e32 v39, 0xffff0000, v58
	v_lshlrev_b32_e32 v58, 16, v59
	v_and_b32_e32 v59, 0xffff0000, v59
	v_pk_mul_f32 v[38:39], v[40:41], v[38:39] op_sel_hi:[0,1]
	v_pk_mul_f32 v[58:59], v[40:41], v[58:59] op_sel_hi:[0,1]
	s_waitcnt vmcnt(0)
	v_pk_fma_f32 v[42:43], v[54:55], v[38:39], v[42:43]
	v_pk_fma_f32 v[44:45], v[56:57], v[58:59], v[44:45]
	global_store_dwordx4 v[62:63], v[42:45], off offset:3072 nt
	s_cbranch_scc0 .LBB0_4009
